# v69 + lever 9 (safe form): the K-loops' loop-control SALU block moved from behind the last barrier of the body to in front of it (issued in the MFMA shadow)
# baseline (speedup 1.0000x reference)
; #define PG8_STAGE(bufoff, gbase, voff) do { _Pragma("unroll") for (int _i = 0; _i < 2; ++_i) \
;         __builtin_amdgcn_global_load_lds((const unsigned*)((const char*)(gbase) + (voff)[_i]), (PG8_LAS unsigned*)(lds + (bufoff) + ldsw + _i * 8192), 16, 0, 0); } while (0)
; #define PG8_LDA(dst, b, h) do { _Pragma("unroll") for (int m = 0; m < 4; ++m) _Pragma("unroll") for (int k = 0; k < 2; ++k) dst[m][k] = *(const PG8_LAS bf16x8*)(lds + PG8_SA(b, h) + aoff + m * 2048 + k * 1024); } while (0)
; #define PG8_LDB(dst, b, h) do { _Pragma("unroll") for (int n = 0; n < 2; ++n) _Pragma("unroll") for (int k = 0; k < 2; ++k) dst[n][k] = *(const PG8_LAS bf16x8*)(lds + PG8_SB(b, h) + boff + n * 2048 + k * 1024); } while (0)
; #define PG8_MMA(ai, bj, At, Bt) do { __builtin_amdgcn_s_setprio(1); _Pragma("unroll") for (int m = 0; m < 4; ++m) _Pragma("unroll") for (int n = 0; n < 2; ++n) _Pragma("unroll") for (int k = 0; k < 2; ++k) \
;         acc[ai][bj][m][n] = __builtin_amdgcn_mfma_f32_16x16x32_bf16(Bt[n][k], At[m][k], acc[ai][bj][m][n], 0, 0, 0); __builtin_amdgcn_s_setprio(0); } while (0)
; #define PG8_WAIT_V(n) asm volatile("s_waitcnt vmcnt(" #n ")" ::: "memory")
; #define PG8_WAIT_L(n) asm volatile("s_waitcnt lgkmcnt(" #n ")" ::: "memory")
; template <class Epi, class Sched, bool ALIGN_EPI = false, bool SP2 = false>
; __device__ __forceinline__ void gemm_phase(PG8_LAS unsigned char* lds, const Gemm g, const Sched& S, const Epi& E, const int wv) {
;     ...
;             const bool last = (t == nt - 2);
;             const char* a1 = cA + (size_t)(t + 1) * kstep;
;             const char* a2 = last ? nA : cA + (size_t)(t + 2) * kstep; const char* b2 = last ? nB : cB + (size_t)(t + 2) * kstep;
;             const char* a3 = a2 + kstep; const char* b3 = b2 + kstep;
;             if (last && has_next) S.a_ready(nxt);
;             if constexpr (SP2) {
;             PG8_LDB(B0, 0, 0); PG8_LDB(B1, 0, 1); PG8_SCHED; PG8_LDA(At, 0, 0); PG8_STAGE(PG8_SA(1, 1), a1 + hstepA, voffA);
;             PG8_WAIT_V(8); PG8_WAIT_L(0); PG8_BAR; PG8_MMA(0, 0, At, B0); PG8_MMA(0, 1, At, B1); PG8_BAR; PG8_SCHED;
;             PG8_LDA(At, 0, 1); PG8_STAGE(PG8_SB(0, 0), b2, voffB); PG8_STAGE(PG8_SB(0, 1), b2 + hstepB, voffB); PG8_STAGE(PG8_SA(0, 0), a2, voffA);
;             PG8_WAIT_V(8); PG8_WAIT_L(0); PG8_BAR; PG8_MMA(1, 0, At, B0); PG8_MMA(1, 1, At, B1); PG8_BAR; PG8_SCHED;
.LBB0_176:
	s_add_i32 s67, s14, 2
	s_add_u32 s68, s12, 0xfff80080
	s_addc_u32 s15, s13, -1
	s_cmp_eq_u32 s61, s14
	s_cselect_b32 s15, s11, s15
	s_cselect_b32 s14, s35, s68
	s_cselect_b32 s69, s45, s43
	s_cselect_b32 s68, s44, s42
	ds_read_b128 v[66:69], v171
	ds_read_b128 v[74:77], v171 offset:1024
	ds_read_b128 v[82:85], v171 offset:2048
	ds_read_b128 v[86:89], v171 offset:3072
	ds_read_b128 v[154:157], v173
	ds_read_b128 v[158:161], v173 offset:1024
	ds_read_b128 v[174:177], v173 offset:2048
	ds_read_b128 v[178:181], v173 offset:3072
	s_add_i32 m0, s54, 0xc000
	ds_read_b128 v[202:205], v200
	ds_read_b128 v[206:209], v200 offset:1024
	ds_read_b128 v[210:213], v200 offset:2048
	ds_read_b128 v[214:217], v200 offset:3072
	ds_read_b128 v[228:231], v200 offset:4096
	ds_read_b128 v[232:235], v200 offset:5120
	ds_read_b128 v[236:239], v200 offset:6144
	ds_read_b128 v[240:243], v200 offset:7168
	global_load_lds_dwordx4 v170, s[12:13]
	s_add_i32 m0, s54, 0xe000
	s_nop 0
	global_load_lds_dwordx4 v172, s[12:13]
	s_waitcnt vmcnt(8) lgkmcnt(0)
	s_barrier
	v_mfma_f32_16x16x32_bf16 v[150:153], v[66:69], v[202:205], v[150:153]
	v_mfma_f32_16x16x32_bf16 v[146:149], v[82:85], v[202:205], v[146:149]
	v_mfma_f32_16x16x32_bf16 v[134:137], v[66:69], v[210:213], v[134:137]
	v_mfma_f32_16x16x32_bf16 v[130:133], v[82:85], v[210:213], v[130:133]
	v_mfma_f32_16x16x32_bf16 v[118:121], v[66:69], v[228:231], v[118:121]
	v_mfma_f32_16x16x32_bf16 v[114:117], v[82:85], v[228:231], v[114:117]
	v_mfma_f32_16x16x32_bf16 v[102:105], v[66:69], v[236:239], v[102:105]
	v_mfma_f32_16x16x32_bf16 v[98:101], v[82:85], v[236:239], v[98:101]
	v_mfma_f32_16x16x32_bf16 v[150:153], v[74:77], v[206:209], v[150:153]
	v_mfma_f32_16x16x32_bf16 v[146:149], v[86:89], v[206:209], v[146:149]
	v_mfma_f32_16x16x32_bf16 v[134:137], v[74:77], v[214:217], v[134:137]
	v_mfma_f32_16x16x32_bf16 v[130:133], v[86:89], v[214:217], v[130:133]
	v_mfma_f32_16x16x32_bf16 v[118:121], v[74:77], v[232:235], v[118:121]
	v_mfma_f32_16x16x32_bf16 v[114:117], v[86:89], v[232:235], v[114:117]
	v_mfma_f32_16x16x32_bf16 v[102:105], v[74:77], v[240:243], v[102:105]
	v_mfma_f32_16x16x32_bf16 v[98:101], v[86:89], v[240:243], v[98:101]
	v_mfma_f32_16x16x32_bf16 v[142:145], v[154:157], v[202:205], v[142:145]
	v_mfma_f32_16x16x32_bf16 v[138:141], v[174:177], v[202:205], v[138:141]
	v_mfma_f32_16x16x32_bf16 v[126:129], v[154:157], v[210:213], v[126:129]
	v_mfma_f32_16x16x32_bf16 v[122:125], v[174:177], v[210:213], v[122:125]
	v_mfma_f32_16x16x32_bf16 v[110:113], v[154:157], v[228:231], v[110:113]
	v_mfma_f32_16x16x32_bf16 v[106:109], v[174:177], v[228:231], v[106:109]
	v_mfma_f32_16x16x32_bf16 v[94:97], v[154:157], v[236:239], v[94:97]
	v_mfma_f32_16x16x32_bf16 v[90:93], v[174:177], v[236:239], v[90:93]
	v_mfma_f32_16x16x32_bf16 v[142:145], v[158:161], v[206:209], v[142:145]
	v_mfma_f32_16x16x32_bf16 v[138:141], v[178:181], v[206:209], v[138:141]
	v_mfma_f32_16x16x32_bf16 v[126:129], v[158:161], v[214:217], v[126:129]
	v_mfma_f32_16x16x32_bf16 v[122:125], v[178:181], v[214:217], v[122:125]
	v_mfma_f32_16x16x32_bf16 v[110:113], v[158:161], v[232:235], v[110:113]
	v_mfma_f32_16x16x32_bf16 v[106:109], v[178:181], v[232:235], v[106:109]
	v_mfma_f32_16x16x32_bf16 v[94:97], v[158:161], v[240:243], v[94:97]
	v_mfma_f32_16x16x32_bf16 v[90:93], v[178:181], v[240:243], v[90:93]
	s_barrier
	s_add_i32 s70, s53, 0x10000
	v_lshl_add_u64 v[218:219], s[68:69], 0, v[0:1]
	s_mov_b32 m0, s70
	ds_read_b128 v[202:205], v200 offset:16384
	ds_read_b128 v[206:209], v200 offset:17408
	ds_read_b128 v[210:213], v200 offset:18432
	ds_read_b128 v[214:217], v200 offset:19456
	ds_read_b128 v[228:231], v200 offset:20480
	ds_read_b128 v[232:235], v200 offset:21504
	ds_read_b128 v[236:239], v200 offset:22528
	ds_read_b128 v[240:243], v200 offset:23552
	global_load_lds_dwordx4 v[218:219], off
	s_add_i32 m0, s70, 0x2000
	v_lshl_add_u64 v[244:245], s[68:69], 0, v[166:167]
	s_add_u32 s68, s68, s24
	s_addc_u32 s69, s69, s25
	s_add_i32 s70, s53, 0x14000
	global_load_lds_dwordx4 v[244:245], off
	s_mov_b32 m0, s70
	global_load_lds_dwordx4 v0, s[68:69]
	s_add_i32 m0, s70, 0x2000
	global_load_lds_dwordx4 v166, s[68:69]
	s_mov_b32 m0, s54
	global_load_lds_dwordx4 v162, s[14:15]
	s_mov_b32 m0, s55
	s_nop 0
	global_load_lds_dwordx4 v164, s[14:15]
	s_waitcnt vmcnt(8) lgkmcnt(0)
	s_barrier
	v_mfma_f32_16x16x32_bf16 v[78:81], v[66:69], v[202:205], v[78:81]
	v_mfma_f32_16x16x32_bf16 v[70:73], v[82:85], v[202:205], v[70:73]
	v_mfma_f32_16x16x32_bf16 v[46:49], v[66:69], v[210:213], v[46:49]
	v_mfma_f32_16x16x32_bf16 v[42:45], v[82:85], v[210:213], v[42:45]
	v_mfma_f32_16x16x32_bf16 v[30:33], v[66:69], v[228:231], v[30:33]
	v_mfma_f32_16x16x32_bf16 v[26:29], v[82:85], v[228:231], v[26:29]
	v_mfma_f32_16x16x32_bf16 v[14:17], v[66:69], v[236:239], v[14:17]
	v_mfma_f32_16x16x32_bf16 v[10:13], v[82:85], v[236:239], v[10:13]
	v_mfma_f32_16x16x32_bf16 v[78:81], v[74:77], v[206:209], v[78:81]
	v_mfma_f32_16x16x32_bf16 v[70:73], v[86:89], v[206:209], v[70:73]
	v_mfma_f32_16x16x32_bf16 v[46:49], v[74:77], v[214:217], v[46:49]
	v_mfma_f32_16x16x32_bf16 v[42:45], v[86:89], v[214:217], v[42:45]
	v_mfma_f32_16x16x32_bf16 v[30:33], v[74:77], v[232:235], v[30:33]
	v_mfma_f32_16x16x32_bf16 v[26:29], v[86:89], v[232:235], v[26:29]
	v_mfma_f32_16x16x32_bf16 v[14:17], v[74:77], v[240:243], v[14:17]
	v_mfma_f32_16x16x32_bf16 v[10:13], v[86:89], v[240:243], v[10:13]
	v_mfma_f32_16x16x32_bf16 v[60:63], v[154:157], v[202:205], v[62:65]
	v_mfma_f32_16x16x32_bf16 v[54:57], v[174:177], v[202:205], v[54:57]
	v_mfma_f32_16x16x32_bf16 v[38:41], v[154:157], v[210:213], v[38:41]
	v_mfma_f32_16x16x32_bf16 v[34:37], v[174:177], v[210:213], v[34:37]
	v_mfma_f32_16x16x32_bf16 v[22:25], v[154:157], v[228:231], v[22:25]
	v_mfma_f32_16x16x32_bf16 v[18:21], v[174:177], v[228:231], v[18:21]
	v_mfma_f32_16x16x32_bf16 v[6:9], v[154:157], v[236:239], v[6:9]
	v_mfma_f32_16x16x32_bf16 v[2:5], v[174:177], v[236:239], v[2:5]
	v_mfma_f32_16x16x32_bf16 v[60:63], v[158:161], v[206:209], v[60:63]
	v_mfma_f32_16x16x32_bf16 v[54:57], v[178:181], v[206:209], v[54:57]
	v_mfma_f32_16x16x32_bf16 v[38:41], v[158:161], v[214:217], v[38:41]
	v_mfma_f32_16x16x32_bf16 v[34:37], v[178:181], v[214:217], v[34:37]
	v_mfma_f32_16x16x32_bf16 v[22:25], v[158:161], v[232:235], v[22:25]
	v_mfma_f32_16x16x32_bf16 v[18:21], v[178:181], v[232:235], v[18:21]
	v_mfma_f32_16x16x32_bf16 v[6:9], v[158:161], v[240:243], v[6:9]
	v_mfma_f32_16x16x32_bf16 v[2:5], v[178:181], v[240:243], v[2:5]
	s_barrier
; #define PG8_STAGE(bufoff, gbase, voff) do { _Pragma("unroll") for (int _i = 0; _i < 2; ++_i) \
;         __builtin_amdgcn_global_load_lds((const unsigned*)((const char*)(gbase) + (voff)[_i]), (PG8_LAS unsigned*)(lds + (bufoff) + ldsw + _i * 8192), 16, 0, 0); } while (0)
; #define PG8_LDA(dst, b, h) do { _Pragma("unroll") for (int m = 0; m < 4; ++m) _Pragma("unroll") for (int k = 0; k < 2; ++k) dst[m][k] = *(const PG8_LAS bf16x8*)(lds + PG8_SA(b, h) + aoff + m * 2048 + k * 1024); } while (0)
; #define PG8_LDB(dst, b, h) do { _Pragma("unroll") for (int n = 0; n < 2; ++n) _Pragma("unroll") for (int k = 0; k < 2; ++k) dst[n][k] = *(const PG8_LAS bf16x8*)(lds + PG8_SB(b, h) + boff + n * 2048 + k * 1024); } while (0)
; #define PG8_MMA(ai, bj, At, Bt) do { __builtin_amdgcn_s_setprio(1); _Pragma("unroll") for (int m = 0; m < 4; ++m) _Pragma("unroll") for (int n = 0; n < 2; ++n) _Pragma("unroll") for (int k = 0; k < 2; ++k) \
;         acc[ai][bj][m][n] = __builtin_amdgcn_mfma_f32_16x16x32_bf16(Bt[n][k], At[m][k], acc[ai][bj][m][n], 0, 0, 0); __builtin_amdgcn_s_setprio(0); } while (0)
; #define PG8_WAIT_V(n) asm volatile("s_waitcnt vmcnt(" #n ")" ::: "memory")
; #define PG8_WAIT_L(n) asm volatile("s_waitcnt lgkmcnt(" #n ")" ::: "memory")
; #define PG8_BAR __builtin_amdgcn_s_barrier()
; #define PG8_SCHED __builtin_amdgcn_sched_barrier(0)
; template <class Epi, class Sched, bool ALIGN_EPI = false, bool SP2 = false>
; __device__ __forceinline__ void gemm_phase(PG8_LAS unsigned char* lds, const Gemm g, const Sched& S, const Epi& E, const int wv) {
;     ...
;         for (int t = 0; t < nt; t += 2) {
;     ...
;             PG8_LDB(B0, 1, 0); PG8_LDB(B1, 1, 1); PG8_SCHED; PG8_LDA(At, 1, 0); PG8_STAGE(PG8_SA(0, 1), a2 + hstepA, voffA);
;             PG8_WAIT_V(8); PG8_WAIT_L(0); PG8_BAR; PG8_MMA(0, 0, At, B0); PG8_MMA(0, 1, At, B1); PG8_BAR; PG8_SCHED;
;             PG8_LDA(At, 1, 1); PG8_STAGE(PG8_SB(1, 0), b3, voffB); PG8_STAGE(PG8_SB(1, 1), b3 + hstepB, voffB); PG8_STAGE(PG8_SA(1, 0), a3, voffA);
;             PG8_WAIT_V(8); PG8_WAIT_L(0); PG8_BAR; PG8_MMA(1, 0, At, B0); PG8_MMA(1, 1, At, B1); PG8_BAR; PG8_SCHED;
	ds_read_b128 v[64:67], v201
	ds_read_b128 v[74:77], v201 offset:1024
	ds_read_b128 v[82:85], v201 offset:2048
	ds_read_b128 v[86:89], v201 offset:3072
	ds_read_b128 v[154:157], v227
	ds_read_b128 v[158:161], v227 offset:1024
	ds_read_b128 v[174:177], v227 offset:2048
	ds_read_b128 v[178:181], v227 offset:3072
	s_mov_b32 m0, s56
	ds_read_b128 v[202:205], v200 offset:32768
	ds_read_b128 v[206:209], v200 offset:33792
	ds_read_b128 v[210:213], v200 offset:34816
	ds_read_b128 v[214:217], v200 offset:35840
	ds_read_b128 v[228:231], v200 offset:36864
	ds_read_b128 v[232:235], v200 offset:37888
	ds_read_b128 v[236:239], v200 offset:38912
	ds_read_b128 v[240:243], v200 offset:39936
	global_load_lds_dwordx4 v59, s[14:15]
	s_mov_b32 m0, s57
	s_nop 0
	global_load_lds_dwordx4 v246, s[14:15]
	s_waitcnt vmcnt(8) lgkmcnt(0)
	s_barrier
	v_mfma_f32_16x16x32_bf16 v[150:153], v[64:67], v[202:205], v[150:153]
	v_mfma_f32_16x16x32_bf16 v[146:149], v[82:85], v[202:205], v[146:149]
	v_mfma_f32_16x16x32_bf16 v[134:137], v[64:67], v[210:213], v[134:137]
	v_mfma_f32_16x16x32_bf16 v[130:133], v[82:85], v[210:213], v[130:133]
	v_mfma_f32_16x16x32_bf16 v[118:121], v[64:67], v[228:231], v[118:121]
	v_mfma_f32_16x16x32_bf16 v[114:117], v[82:85], v[228:231], v[114:117]
	v_mfma_f32_16x16x32_bf16 v[102:105], v[64:67], v[236:239], v[102:105]
	v_mfma_f32_16x16x32_bf16 v[98:101], v[82:85], v[236:239], v[98:101]
	v_mfma_f32_16x16x32_bf16 v[150:153], v[74:77], v[206:209], v[150:153]
	v_mfma_f32_16x16x32_bf16 v[146:149], v[86:89], v[206:209], v[146:149]
	v_mfma_f32_16x16x32_bf16 v[134:137], v[74:77], v[214:217], v[134:137]
	v_mfma_f32_16x16x32_bf16 v[130:133], v[86:89], v[214:217], v[130:133]
	v_mfma_f32_16x16x32_bf16 v[118:121], v[74:77], v[232:235], v[118:121]
	v_mfma_f32_16x16x32_bf16 v[114:117], v[86:89], v[232:235], v[114:117]
	v_mfma_f32_16x16x32_bf16 v[102:105], v[74:77], v[240:243], v[102:105]
	v_mfma_f32_16x16x32_bf16 v[98:101], v[86:89], v[240:243], v[98:101]
	v_mfma_f32_16x16x32_bf16 v[142:145], v[154:157], v[202:205], v[142:145]
	v_mfma_f32_16x16x32_bf16 v[138:141], v[174:177], v[202:205], v[138:141]
	v_mfma_f32_16x16x32_bf16 v[126:129], v[154:157], v[210:213], v[126:129]
	v_mfma_f32_16x16x32_bf16 v[122:125], v[174:177], v[210:213], v[122:125]
	v_mfma_f32_16x16x32_bf16 v[110:113], v[154:157], v[228:231], v[110:113]
	v_mfma_f32_16x16x32_bf16 v[106:109], v[174:177], v[228:231], v[106:109]
	v_mfma_f32_16x16x32_bf16 v[94:97], v[154:157], v[236:239], v[94:97]
	v_mfma_f32_16x16x32_bf16 v[90:93], v[174:177], v[236:239], v[90:93]
	v_mfma_f32_16x16x32_bf16 v[142:145], v[158:161], v[206:209], v[142:145]
	v_mfma_f32_16x16x32_bf16 v[138:141], v[178:181], v[206:209], v[138:141]
	v_mfma_f32_16x16x32_bf16 v[126:129], v[158:161], v[214:217], v[126:129]
	v_mfma_f32_16x16x32_bf16 v[122:125], v[178:181], v[214:217], v[122:125]
	v_mfma_f32_16x16x32_bf16 v[110:113], v[158:161], v[232:235], v[110:113]
	v_mfma_f32_16x16x32_bf16 v[106:109], v[178:181], v[232:235], v[106:109]
	v_mfma_f32_16x16x32_bf16 v[94:97], v[158:161], v[240:243], v[94:97]
	v_mfma_f32_16x16x32_bf16 v[90:93], v[178:181], v[240:243], v[90:93]
	s_barrier
	s_add_i32 m0, s53, 0x17f80
	ds_read_b128 v[202:205], v200 offset:49152
	ds_read_b128 v[206:209], v200 offset:50176
	ds_read_b128 v[210:213], v200 offset:51200
	ds_read_b128 v[214:217], v200 offset:52224
	ds_read_b128 v[228:231], v200 offset:53248
	ds_read_b128 v[232:235], v200 offset:54272
	ds_read_b128 v[236:239], v200 offset:55296
	ds_read_b128 v[240:243], v200 offset:56320
	global_load_lds_dwordx4 v[218:219], off offset:128
	s_add_i32 m0, s53, 0x19f80
	global_load_lds_dwordx4 v[244:245], off offset:128
	s_add_i32 m0, s53, 0x1bf80
	s_nop 0
	global_load_lds_dwordx4 v0, s[68:69] offset:128
	s_add_i32 m0, s53, 0x1df80
	s_nop 0
	global_load_lds_dwordx4 v166, s[68:69] offset:128
	s_add_i32 m0, s58, 0xffffff80
	s_nop 0
	global_load_lds_dwordx4 v162, s[14:15] offset:128
	s_add_i32 m0, s59, 0xffffff80
	s_nop 0
	global_load_lds_dwordx4 v164, s[14:15] offset:128
	s_waitcnt vmcnt(8) lgkmcnt(0)
	s_barrier
	v_mfma_f32_16x16x32_bf16 v[78:81], v[64:67], v[202:205], v[78:81]
	v_mfma_f32_16x16x32_bf16 v[68:71], v[82:85], v[202:205], v[70:73]
	v_mfma_f32_16x16x32_bf16 v[46:49], v[64:67], v[210:213], v[46:49]
	v_mfma_f32_16x16x32_bf16 v[42:45], v[82:85], v[210:213], v[42:45]
	v_mfma_f32_16x16x32_bf16 v[30:33], v[64:67], v[228:231], v[30:33]
	v_mfma_f32_16x16x32_bf16 v[26:29], v[82:85], v[228:231], v[26:29]
	v_mfma_f32_16x16x32_bf16 v[14:17], v[64:67], v[236:239], v[14:17]
	v_mfma_f32_16x16x32_bf16 v[10:13], v[82:85], v[236:239], v[10:13]
	v_mfma_f32_16x16x32_bf16 v[78:81], v[74:77], v[206:209], v[78:81]
	v_mfma_f32_16x16x32_bf16 v[70:73], v[86:89], v[206:209], v[68:71]
	v_mfma_f32_16x16x32_bf16 v[46:49], v[74:77], v[214:217], v[46:49]
	v_mfma_f32_16x16x32_bf16 v[42:45], v[86:89], v[214:217], v[42:45]
	v_mfma_f32_16x16x32_bf16 v[30:33], v[74:77], v[232:235], v[30:33]
	v_mfma_f32_16x16x32_bf16 v[26:29], v[86:89], v[232:235], v[26:29]
	v_mfma_f32_16x16x32_bf16 v[14:17], v[74:77], v[240:243], v[14:17]
	v_mfma_f32_16x16x32_bf16 v[10:13], v[86:89], v[240:243], v[10:13]
	v_mfma_f32_16x16x32_bf16 v[60:63], v[154:157], v[202:205], v[60:63]
	v_mfma_f32_16x16x32_bf16 v[54:57], v[174:177], v[202:205], v[54:57]
	v_mfma_f32_16x16x32_bf16 v[38:41], v[154:157], v[210:213], v[38:41]
	v_mfma_f32_16x16x32_bf16 v[34:37], v[174:177], v[210:213], v[34:37]
	v_mfma_f32_16x16x32_bf16 v[22:25], v[154:157], v[228:231], v[22:25]
	v_mfma_f32_16x16x32_bf16 v[18:21], v[174:177], v[228:231], v[18:21]
	v_mfma_f32_16x16x32_bf16 v[6:9], v[154:157], v[236:239], v[6:9]
	v_mfma_f32_16x16x32_bf16 v[2:5], v[174:177], v[236:239], v[2:5]
	v_mfma_f32_16x16x32_bf16 v[62:65], v[158:161], v[206:209], v[60:63]
	v_mfma_f32_16x16x32_bf16 v[54:57], v[178:181], v[206:209], v[54:57]
	v_mfma_f32_16x16x32_bf16 v[38:41], v[158:161], v[214:217], v[38:41]
	v_mfma_f32_16x16x32_bf16 v[34:37], v[178:181], v[214:217], v[34:37]
	v_mfma_f32_16x16x32_bf16 v[22:25], v[158:161], v[232:235], v[22:25]
	v_mfma_f32_16x16x32_bf16 v[18:21], v[178:181], v[232:235], v[18:21]
	v_mfma_f32_16x16x32_bf16 v[6:9], v[158:161], v[240:243], v[6:9]
	v_mfma_f32_16x16x32_bf16 v[2:5], v[178:181], v[240:243], v[2:5]
	s_add_u32 s12, s12, 0x100
	s_addc_u32 s13, s13, 0
	s_add_u32 s42, s42, 0x100
	s_addc_u32 s43, s43, 0
	s_cmp_ge_i32 s67, s60
	s_mov_b32 s14, s67
	s_barrier
	s_cbranch_scc0 .LBB0_176
	s_movk_i32 s68, 0x4000
	s_movk_i32 s69, 0x6000
	s_mov_b32 s70, 0x18000
	s_mov_b32 s71, 0x3f317217

; #define PG8_STAGE(bufoff, gbase, voff) do { _Pragma("unroll") for (int _i = 0; _i < 2; ++_i) \
;         __builtin_amdgcn_global_load_lds((const unsigned*)((const char*)(gbase) + (voff)[_i]), (PG8_LAS unsigned*)(lds + (bufoff) + ldsw + _i * 8192), 16, 0, 0); } while (0)
; #define PG8_LDA(dst, b, h) do { _Pragma("unroll") for (int m = 0; m < 4; ++m) _Pragma("unroll") for (int k = 0; k < 2; ++k) dst[m][k] = *(const PG8_LAS bf16x8*)(lds + PG8_SA(b, h) + aoff + m * 2048 + k * 1024); } while (0)
; #define PG8_LDB(dst, b, h) do { _Pragma("unroll") for (int n = 0; n < 2; ++n) _Pragma("unroll") for (int k = 0; k < 2; ++k) dst[n][k] = *(const PG8_LAS bf16x8*)(lds + PG8_SB(b, h) + boff + n * 2048 + k * 1024); } while (0)
; #define PG8_MMA(ai, bj, At, Bt) do { __builtin_amdgcn_s_setprio(1); _Pragma("unroll") for (int m = 0; m < 4; ++m) _Pragma("unroll") for (int n = 0; n < 2; ++n) _Pragma("unroll") for (int k = 0; k < 2; ++k) \
;         acc[ai][bj][m][n] = __builtin_amdgcn_mfma_f32_16x16x32_bf16(Bt[n][k], At[m][k], acc[ai][bj][m][n], 0, 0, 0); __builtin_amdgcn_s_setprio(0); } while (0)
; #define PG8_WAIT_V(n) asm volatile("s_waitcnt vmcnt(" #n ")" ::: "memory")
; #define PG8_WAIT_L(n) asm volatile("s_waitcnt lgkmcnt(" #n ")" ::: "memory")
; template <class Epi, class Sched, bool ALIGN_EPI = false, bool SP2 = false>
; __device__ __forceinline__ void gemm_phase(PG8_LAS unsigned char* lds, const Gemm g, const Sched& S, const Epi& E, const int wv) {
;     ...
;             const bool last = (t == nt - 2);
;             const char* a1 = cA + (size_t)(t + 1) * kstep;
;             const char* a2 = last ? nA : cA + (size_t)(t + 2) * kstep; const char* b2 = last ? nB : cB + (size_t)(t + 2) * kstep;
;             const char* a3 = a2 + kstep; const char* b3 = b2 + kstep;
;             if (last && has_next) S.a_ready(nxt);
;             if constexpr (SP2) {
;             PG8_LDB(B0, 0, 0); PG8_LDB(B1, 0, 1); PG8_SCHED; PG8_LDA(At, 0, 0); PG8_STAGE(PG8_SA(1, 1), a1 + hstepA, voffA);
;             PG8_WAIT_V(8); PG8_WAIT_L(0); PG8_BAR; PG8_MMA(0, 0, At, B0); PG8_MMA(0, 1, At, B1); PG8_BAR; PG8_SCHED;
;             PG8_LDA(At, 0, 1); PG8_STAGE(PG8_SB(0, 0), b2, voffB); PG8_STAGE(PG8_SB(0, 1), b2 + hstepB, voffB); PG8_STAGE(PG8_SA(0, 0), a2, voffA);
;             PG8_WAIT_V(8); PG8_WAIT_L(0); PG8_BAR; PG8_MMA(1, 0, At, B0); PG8_MMA(1, 1, At, B1); PG8_BAR; PG8_SCHED;
.LBB0_336:
	s_add_i32 s40, s14, 2
	s_add_u32 s41, s12, 0xfff80080
	s_addc_u32 s15, s13, -1
	s_cmp_eq_u32 s62, s14
	s_cselect_b32 s15, s93, s15
	s_cselect_b32 s14, s92, s41
	s_cselect_b32 s45, s25, s17
	s_cselect_b32 s44, s24, s11
	ds_read_b128 v[26:29], v171
	ds_read_b128 v[30:33], v171 offset:1024
	ds_read_b128 v[42:45], v171 offset:2048
	ds_read_b128 v[46:49], v171 offset:3072
	ds_read_b128 v[146:149], v227
	ds_read_b128 v[150:153], v227 offset:1024
	ds_read_b128 v[154:157], v227 offset:2048
	ds_read_b128 v[158:161], v227 offset:3072
	s_add_i32 m0, s55, 0xc000
	ds_read_b128 v[172:175], v199
	ds_read_b128 v[176:179], v199 offset:1024
	ds_read_b128 v[180:183], v199 offset:2048
	ds_read_b128 v[200:203], v199 offset:3072
	ds_read_b128 v[204:207], v199 offset:4096
	ds_read_b128 v[208:211], v199 offset:5120
	ds_read_b128 v[212:215], v199 offset:6144
	ds_read_b128 v[216:219], v199 offset:7168
	global_load_lds_dwordx4 v168, s[12:13]
	s_add_i32 m0, s55, 0xe000
	s_nop 0
	global_load_lds_dwordx4 v170, s[12:13]
	s_waitcnt vmcnt(8) lgkmcnt(0)
	s_barrier
	v_mfma_f32_16x16x32_bf16 v[138:141], v[26:29], v[172:175], v[138:141]
	v_mfma_f32_16x16x32_bf16 v[142:145], v[42:45], v[172:175], v[142:145]
	v_mfma_f32_16x16x32_bf16 v[126:129], v[26:29], v[180:183], v[126:129]
	v_mfma_f32_16x16x32_bf16 v[122:125], v[42:45], v[180:183], v[122:125]
	v_mfma_f32_16x16x32_bf16 v[110:113], v[26:29], v[204:207], v[110:113]
	v_mfma_f32_16x16x32_bf16 v[106:109], v[42:45], v[204:207], v[106:109]
	v_mfma_f32_16x16x32_bf16 v[94:97], v[26:29], v[212:215], v[94:97]
	v_mfma_f32_16x16x32_bf16 v[90:93], v[42:45], v[212:215], v[90:93]
	v_mfma_f32_16x16x32_bf16 v[138:141], v[30:33], v[176:179], v[138:141]
	v_mfma_f32_16x16x32_bf16 v[142:145], v[46:49], v[176:179], v[142:145]
	v_mfma_f32_16x16x32_bf16 v[126:129], v[30:33], v[200:203], v[126:129]
	v_mfma_f32_16x16x32_bf16 v[122:125], v[46:49], v[200:203], v[122:125]
	v_mfma_f32_16x16x32_bf16 v[110:113], v[30:33], v[208:211], v[110:113]
	v_mfma_f32_16x16x32_bf16 v[106:109], v[46:49], v[208:211], v[106:109]
	v_mfma_f32_16x16x32_bf16 v[94:97], v[30:33], v[216:219], v[94:97]
	v_mfma_f32_16x16x32_bf16 v[90:93], v[46:49], v[216:219], v[90:93]
	v_mfma_f32_16x16x32_bf16 v[134:137], v[146:149], v[172:175], v[134:137]
	v_mfma_f32_16x16x32_bf16 v[130:133], v[154:157], v[172:175], v[130:133]
	v_mfma_f32_16x16x32_bf16 v[118:121], v[146:149], v[180:183], v[118:121]
	v_mfma_f32_16x16x32_bf16 v[114:117], v[154:157], v[180:183], v[114:117]
	v_mfma_f32_16x16x32_bf16 v[102:105], v[146:149], v[204:207], v[102:105]
	v_mfma_f32_16x16x32_bf16 v[98:101], v[154:157], v[204:207], v[98:101]
	v_mfma_f32_16x16x32_bf16 v[86:89], v[146:149], v[212:215], v[86:89]
	v_mfma_f32_16x16x32_bf16 v[82:85], v[154:157], v[212:215], v[82:85]
	v_mfma_f32_16x16x32_bf16 v[134:137], v[150:153], v[176:179], v[134:137]
	v_mfma_f32_16x16x32_bf16 v[130:133], v[158:161], v[176:179], v[130:133]
	v_mfma_f32_16x16x32_bf16 v[118:121], v[150:153], v[200:203], v[118:121]
	v_mfma_f32_16x16x32_bf16 v[114:117], v[158:161], v[200:203], v[114:117]
	v_mfma_f32_16x16x32_bf16 v[102:105], v[150:153], v[208:211], v[102:105]
	v_mfma_f32_16x16x32_bf16 v[98:101], v[158:161], v[208:211], v[98:101]
	v_mfma_f32_16x16x32_bf16 v[86:89], v[150:153], v[216:219], v[86:89]
	v_mfma_f32_16x16x32_bf16 v[82:85], v[158:161], v[216:219], v[82:85]
	s_barrier
	s_add_i32 s65, s54, 0x10000
	v_lshl_add_u64 v[184:185], s[44:45], 0, v[0:1]
	s_mov_b32 m0, s65
	ds_read_b128 v[172:175], v199 offset:16384
	ds_read_b128 v[176:179], v199 offset:17408
	ds_read_b128 v[180:183], v199 offset:18432
	ds_read_b128 v[200:203], v199 offset:19456
	ds_read_b128 v[204:207], v199 offset:20480
	ds_read_b128 v[208:211], v199 offset:21504
	ds_read_b128 v[212:215], v199 offset:22528
	ds_read_b128 v[216:219], v199 offset:23552
	global_load_lds_dwordx4 v[184:185], off
	s_add_i32 m0, s65, 0x2000
	v_lshl_add_u64 v[194:195], s[44:45], 0, v[162:163]
	s_add_u32 s44, s44, s28
	s_addc_u32 s45, s45, s29
	s_add_i32 s41, s54, 0x14000
	global_load_lds_dwordx4 v[194:195], off
	s_mov_b32 m0, s41
	global_load_lds_dwordx4 v0, s[44:45]
	s_add_i32 m0, s41, 0x2000
	global_load_lds_dwordx4 v162, s[44:45]
	s_mov_b32 m0, s55
	global_load_lds_dwordx4 v166, s[14:15]
	s_mov_b32 m0, s56
	s_nop 0
	global_load_lds_dwordx4 v164, s[14:15]
	s_waitcnt vmcnt(8) lgkmcnt(0)
	s_barrier
	v_mfma_f32_16x16x32_bf16 v[78:81], v[26:29], v[172:175], v[78:81]
	v_mfma_f32_16x16x32_bf16 v[74:77], v[42:45], v[172:175], v[74:77]
	v_mfma_f32_16x16x32_bf16 v[62:65], v[26:29], v[180:183], v[62:65]
	v_mfma_f32_16x16x32_bf16 v[58:61], v[42:45], v[180:183], v[58:61]
	v_mfma_f32_16x16x32_bf16 v[38:41], v[26:29], v[204:207], v[38:41]
	v_mfma_f32_16x16x32_bf16 v[34:37], v[42:45], v[204:207], v[34:37]
	v_mfma_f32_16x16x32_bf16 v[14:17], v[26:29], v[212:215], v[14:17]
	v_mfma_f32_16x16x32_bf16 v[10:13], v[42:45], v[212:215], v[10:13]
	v_mfma_f32_16x16x32_bf16 v[78:81], v[30:33], v[176:179], v[78:81]
	v_mfma_f32_16x16x32_bf16 v[74:77], v[46:49], v[176:179], v[74:77]
	v_mfma_f32_16x16x32_bf16 v[62:65], v[30:33], v[200:203], v[62:65]
	v_mfma_f32_16x16x32_bf16 v[58:61], v[46:49], v[200:203], v[58:61]
	v_mfma_f32_16x16x32_bf16 v[38:41], v[30:33], v[208:211], v[38:41]
	v_mfma_f32_16x16x32_bf16 v[34:37], v[46:49], v[208:211], v[34:37]
	v_mfma_f32_16x16x32_bf16 v[14:17], v[30:33], v[216:219], v[14:17]
	v_mfma_f32_16x16x32_bf16 v[10:13], v[46:49], v[216:219], v[10:13]
	v_mfma_f32_16x16x32_bf16 v[22:25], v[146:149], v[204:207], v[22:25]
	v_mfma_f32_16x16x32_bf16 v[18:21], v[154:157], v[204:207], v[18:21]
	v_mfma_f32_16x16x32_bf16 v[6:9], v[146:149], v[212:215], v[6:9]
	v_mfma_f32_16x16x32_bf16 v[2:5], v[154:157], v[212:215], v[2:5]
	v_mfma_f32_16x16x32_bf16 v[26:29], v[146:149], v[172:175], v[70:73]
	v_mfma_f32_16x16x32_bf16 v[30:33], v[154:157], v[172:175], v[66:69]
	v_mfma_f32_16x16x32_bf16 v[42:45], v[146:149], v[180:183], v[54:57]
	v_mfma_f32_16x16x32_bf16 v[46:49], v[154:157], v[180:183], v[50:53]
	v_mfma_f32_16x16x32_bf16 v[22:25], v[150:153], v[208:211], v[22:25]
	v_mfma_f32_16x16x32_bf16 v[18:21], v[158:161], v[208:211], v[18:21]
	v_mfma_f32_16x16x32_bf16 v[6:9], v[150:153], v[216:219], v[6:9]
	v_mfma_f32_16x16x32_bf16 v[2:5], v[158:161], v[216:219], v[2:5]
	v_mfma_f32_16x16x32_bf16 v[26:29], v[150:153], v[176:179], v[26:29]
	v_mfma_f32_16x16x32_bf16 v[30:33], v[158:161], v[176:179], v[30:33]
	v_mfma_f32_16x16x32_bf16 v[42:45], v[150:153], v[200:203], v[42:45]
	v_mfma_f32_16x16x32_bf16 v[46:49], v[158:161], v[200:203], v[46:49]
	s_barrier
; #define PG8_STAGE(bufoff, gbase, voff) do { _Pragma("unroll") for (int _i = 0; _i < 2; ++_i) \
;         __builtin_amdgcn_global_load_lds((const unsigned*)((const char*)(gbase) + (voff)[_i]), (PG8_LAS unsigned*)(lds + (bufoff) + ldsw + _i * 8192), 16, 0, 0); } while (0)
; #define PG8_LDA(dst, b, h) do { _Pragma("unroll") for (int m = 0; m < 4; ++m) _Pragma("unroll") for (int k = 0; k < 2; ++k) dst[m][k] = *(const PG8_LAS bf16x8*)(lds + PG8_SA(b, h) + aoff + m * 2048 + k * 1024); } while (0)
; #define PG8_LDB(dst, b, h) do { _Pragma("unroll") for (int n = 0; n < 2; ++n) _Pragma("unroll") for (int k = 0; k < 2; ++k) dst[n][k] = *(const PG8_LAS bf16x8*)(lds + PG8_SB(b, h) + boff + n * 2048 + k * 1024); } while (0)
; #define PG8_MMA(ai, bj, At, Bt) do { __builtin_amdgcn_s_setprio(1); _Pragma("unroll") for (int m = 0; m < 4; ++m) _Pragma("unroll") for (int n = 0; n < 2; ++n) _Pragma("unroll") for (int k = 0; k < 2; ++k) \
;         acc[ai][bj][m][n] = __builtin_amdgcn_mfma_f32_16x16x32_bf16(Bt[n][k], At[m][k], acc[ai][bj][m][n], 0, 0, 0); __builtin_amdgcn_s_setprio(0); } while (0)
; #define PG8_WAIT_V(n) asm volatile("s_waitcnt vmcnt(" #n ")" ::: "memory")
; #define PG8_WAIT_L(n) asm volatile("s_waitcnt lgkmcnt(" #n ")" ::: "memory")
; #define PG8_BAR __builtin_amdgcn_s_barrier()
; #define PG8_SCHED __builtin_amdgcn_sched_barrier(0)
; template <class Epi, class Sched, bool ALIGN_EPI = false, bool SP2 = false>
; __device__ __forceinline__ void gemm_phase(PG8_LAS unsigned char* lds, const Gemm g, const Sched& S, const Epi& E, const int wv) {
;     ...
;         for (int t = 0; t < nt; t += 2) {
;     ...
;             PG8_LDB(B0, 1, 0); PG8_LDB(B1, 1, 1); PG8_SCHED; PG8_LDA(At, 1, 0); PG8_STAGE(PG8_SA(0, 1), a2 + hstepA, voffA);
;             PG8_WAIT_V(8); PG8_WAIT_L(0); PG8_BAR; PG8_MMA(0, 0, At, B0); PG8_MMA(0, 1, At, B1); PG8_BAR; PG8_SCHED;
;             PG8_LDA(At, 1, 1); PG8_STAGE(PG8_SB(1, 0), b3, voffB); PG8_STAGE(PG8_SB(1, 1), b3 + hstepB, voffB); PG8_STAGE(PG8_SA(1, 0), a3, voffA);
;             PG8_WAIT_V(8); PG8_WAIT_L(0); PG8_BAR; PG8_MMA(1, 0, At, B0); PG8_MMA(1, 1, At, B1); PG8_BAR; PG8_SCHED;
	ds_read_b128 v[50:53], v244
	ds_read_b128 v[54:57], v244 offset:1024
	ds_read_b128 v[66:69], v244 offset:2048
	ds_read_b128 v[70:73], v244 offset:3072
	ds_read_b128 v[146:149], v245
	ds_read_b128 v[150:153], v245 offset:1024
	ds_read_b128 v[154:157], v245 offset:2048
	ds_read_b128 v[158:161], v245 offset:3072
	s_mov_b32 m0, s57
	ds_read_b128 v[172:175], v199 offset:32768
	ds_read_b128 v[176:179], v199 offset:33792
	ds_read_b128 v[180:183], v199 offset:34816
	ds_read_b128 v[200:203], v199 offset:35840
	ds_read_b128 v[204:207], v199 offset:36864
	ds_read_b128 v[208:211], v199 offset:37888
	ds_read_b128 v[212:215], v199 offset:38912
	ds_read_b128 v[216:219], v199 offset:39936
	global_load_lds_dwordx4 v246, s[14:15]
	s_mov_b32 m0, s58
	s_nop 0
	global_load_lds_dwordx4 v247, s[14:15]
	s_waitcnt vmcnt(8) lgkmcnt(0)
	s_barrier
	v_mfma_f32_16x16x32_bf16 v[138:141], v[50:53], v[172:175], v[138:141]
	v_mfma_f32_16x16x32_bf16 v[142:145], v[66:69], v[172:175], v[142:145]
	v_mfma_f32_16x16x32_bf16 v[126:129], v[50:53], v[180:183], v[126:129]
	v_mfma_f32_16x16x32_bf16 v[122:125], v[66:69], v[180:183], v[122:125]
	v_mfma_f32_16x16x32_bf16 v[110:113], v[50:53], v[204:207], v[110:113]
	v_mfma_f32_16x16x32_bf16 v[106:109], v[66:69], v[204:207], v[106:109]
	v_mfma_f32_16x16x32_bf16 v[94:97], v[50:53], v[212:215], v[94:97]
	v_mfma_f32_16x16x32_bf16 v[90:93], v[66:69], v[212:215], v[90:93]
	v_mfma_f32_16x16x32_bf16 v[138:141], v[54:57], v[176:179], v[138:141]
	v_mfma_f32_16x16x32_bf16 v[142:145], v[70:73], v[176:179], v[142:145]
	v_mfma_f32_16x16x32_bf16 v[126:129], v[54:57], v[200:203], v[126:129]
	v_mfma_f32_16x16x32_bf16 v[122:125], v[70:73], v[200:203], v[122:125]
	v_mfma_f32_16x16x32_bf16 v[110:113], v[54:57], v[208:211], v[110:113]
	v_mfma_f32_16x16x32_bf16 v[106:109], v[70:73], v[208:211], v[106:109]
	v_mfma_f32_16x16x32_bf16 v[94:97], v[54:57], v[216:219], v[94:97]
	v_mfma_f32_16x16x32_bf16 v[90:93], v[70:73], v[216:219], v[90:93]
	v_mfma_f32_16x16x32_bf16 v[134:137], v[146:149], v[172:175], v[134:137]
	v_mfma_f32_16x16x32_bf16 v[130:133], v[154:157], v[172:175], v[130:133]
	v_mfma_f32_16x16x32_bf16 v[118:121], v[146:149], v[180:183], v[118:121]
	v_mfma_f32_16x16x32_bf16 v[114:117], v[154:157], v[180:183], v[114:117]
	v_mfma_f32_16x16x32_bf16 v[102:105], v[146:149], v[204:207], v[102:105]
	v_mfma_f32_16x16x32_bf16 v[98:101], v[154:157], v[204:207], v[98:101]
	v_mfma_f32_16x16x32_bf16 v[86:89], v[146:149], v[212:215], v[86:89]
	v_mfma_f32_16x16x32_bf16 v[82:85], v[154:157], v[212:215], v[82:85]
	v_mfma_f32_16x16x32_bf16 v[134:137], v[150:153], v[176:179], v[134:137]
	v_mfma_f32_16x16x32_bf16 v[130:133], v[158:161], v[176:179], v[130:133]
	v_mfma_f32_16x16x32_bf16 v[118:121], v[150:153], v[200:203], v[118:121]
	v_mfma_f32_16x16x32_bf16 v[114:117], v[158:161], v[200:203], v[114:117]
	v_mfma_f32_16x16x32_bf16 v[102:105], v[150:153], v[208:211], v[102:105]
	v_mfma_f32_16x16x32_bf16 v[98:101], v[158:161], v[208:211], v[98:101]
	v_mfma_f32_16x16x32_bf16 v[86:89], v[150:153], v[216:219], v[86:89]
	v_mfma_f32_16x16x32_bf16 v[82:85], v[158:161], v[216:219], v[82:85]
	s_barrier
	s_add_i32 m0, s54, 0x17f80
	ds_read_b128 v[172:175], v199 offset:49152
	ds_read_b128 v[176:179], v199 offset:50176
	ds_read_b128 v[180:183], v199 offset:51200
	ds_read_b128 v[200:203], v199 offset:52224
	ds_read_b128 v[204:207], v199 offset:53248
	ds_read_b128 v[208:211], v199 offset:54272
	ds_read_b128 v[212:215], v199 offset:55296
	ds_read_b128 v[216:219], v199 offset:56320
	global_load_lds_dwordx4 v[184:185], off offset:128
	s_add_i32 m0, s54, 0x19f80
	global_load_lds_dwordx4 v[194:195], off offset:128
	s_add_i32 m0, s54, 0x1bf80
	s_nop 0
	global_load_lds_dwordx4 v0, s[44:45] offset:128
	s_add_i32 m0, s54, 0x1df80
	s_nop 0
	global_load_lds_dwordx4 v162, s[44:45] offset:128
	s_add_i32 m0, s60, 0xffffff80
	s_nop 0
	global_load_lds_dwordx4 v166, s[14:15] offset:128
	s_add_i32 m0, s61, 0xffffff80
	s_nop 0
	global_load_lds_dwordx4 v164, s[14:15] offset:128
	s_waitcnt vmcnt(8) lgkmcnt(0)
	s_barrier
	v_mfma_f32_16x16x32_bf16 v[78:81], v[50:53], v[172:175], v[78:81]
	v_mfma_f32_16x16x32_bf16 v[74:77], v[66:69], v[172:175], v[74:77]
	v_mfma_f32_16x16x32_bf16 v[62:65], v[50:53], v[180:183], v[62:65]
	v_mfma_f32_16x16x32_bf16 v[58:61], v[66:69], v[180:183], v[58:61]
	v_mfma_f32_16x16x32_bf16 v[38:41], v[50:53], v[204:207], v[38:41]
	v_mfma_f32_16x16x32_bf16 v[34:37], v[66:69], v[204:207], v[34:37]
	v_mfma_f32_16x16x32_bf16 v[14:17], v[50:53], v[212:215], v[14:17]
	v_mfma_f32_16x16x32_bf16 v[10:13], v[66:69], v[212:215], v[10:13]
	v_mfma_f32_16x16x32_bf16 v[78:81], v[54:57], v[176:179], v[78:81]
	v_mfma_f32_16x16x32_bf16 v[74:77], v[70:73], v[176:179], v[74:77]
	v_mfma_f32_16x16x32_bf16 v[62:65], v[54:57], v[200:203], v[62:65]
	v_mfma_f32_16x16x32_bf16 v[58:61], v[70:73], v[200:203], v[58:61]
	v_mfma_f32_16x16x32_bf16 v[38:41], v[54:57], v[208:211], v[38:41]
	v_mfma_f32_16x16x32_bf16 v[34:37], v[70:73], v[208:211], v[34:37]
	v_mfma_f32_16x16x32_bf16 v[14:17], v[54:57], v[216:219], v[14:17]
	v_mfma_f32_16x16x32_bf16 v[10:13], v[70:73], v[216:219], v[10:13]
	v_mfma_f32_16x16x32_bf16 v[26:29], v[146:149], v[172:175], v[26:29]
	v_mfma_f32_16x16x32_bf16 v[70:73], v[150:153], v[176:179], v[26:29]
	v_mfma_f32_16x16x32_bf16 v[26:29], v[154:157], v[172:175], v[30:33]
	v_mfma_f32_16x16x32_bf16 v[66:69], v[158:161], v[176:179], v[26:29]
	v_mfma_f32_16x16x32_bf16 v[26:29], v[146:149], v[180:183], v[42:45]
	v_mfma_f32_16x16x32_bf16 v[54:57], v[150:153], v[200:203], v[26:29]
	v_mfma_f32_16x16x32_bf16 v[26:29], v[154:157], v[180:183], v[46:49]
	v_mfma_f32_16x16x32_bf16 v[22:25], v[146:149], v[204:207], v[22:25]
	v_mfma_f32_16x16x32_bf16 v[18:21], v[154:157], v[204:207], v[18:21]
	v_mfma_f32_16x16x32_bf16 v[6:9], v[146:149], v[212:215], v[6:9]
	v_mfma_f32_16x16x32_bf16 v[2:5], v[154:157], v[212:215], v[2:5]
	v_mfma_f32_16x16x32_bf16 v[50:53], v[158:161], v[200:203], v[26:29]
	v_mfma_f32_16x16x32_bf16 v[22:25], v[150:153], v[208:211], v[22:25]
	v_mfma_f32_16x16x32_bf16 v[18:21], v[158:161], v[208:211], v[18:21]
	v_mfma_f32_16x16x32_bf16 v[6:9], v[150:153], v[216:219], v[6:9]
	v_mfma_f32_16x16x32_bf16 v[2:5], v[158:161], v[216:219], v[2:5]
	s_add_u32 s12, s12, 0x100
	s_addc_u32 s13, s13, 0
	s_add_u32 s11, s11, 0x100
	s_addc_u32 s17, s17, 0
	s_cmp_ge_i32 s40, s59
	s_mov_b32 s14, s40
	s_barrier
	s_cbranch_scc0 .LBB0_336

; #define PG8_STAGE(bufoff, gbase, voff) do { _Pragma("unroll") for (int _i = 0; _i < 2; ++_i) \
;         __builtin_amdgcn_global_load_lds((const unsigned*)((const char*)(gbase) + (voff)[_i]), (PG8_LAS unsigned*)(lds + (bufoff) + ldsw + _i * 8192), 16, 0, 0); } while (0)
; #define PG8_LDA(dst, b, h) do { _Pragma("unroll") for (int m = 0; m < 4; ++m) _Pragma("unroll") for (int k = 0; k < 2; ++k) dst[m][k] = *(const PG8_LAS bf16x8*)(lds + PG8_SA(b, h) + aoff + m * 2048 + k * 1024); } while (0)
; #define PG8_LDB(dst, b, h) do { _Pragma("unroll") for (int n = 0; n < 2; ++n) _Pragma("unroll") for (int k = 0; k < 2; ++k) dst[n][k] = *(const PG8_LAS bf16x8*)(lds + PG8_SB(b, h) + boff + n * 2048 + k * 1024); } while (0)
; #define PG8_MMA(ai, bj, At, Bt) do { __builtin_amdgcn_s_setprio(1); _Pragma("unroll") for (int m = 0; m < 4; ++m) _Pragma("unroll") for (int n = 0; n < 2; ++n) _Pragma("unroll") for (int k = 0; k < 2; ++k) \
;         acc[ai][bj][m][n] = __builtin_amdgcn_mfma_f32_16x16x32_bf16(Bt[n][k], At[m][k], acc[ai][bj][m][n], 0, 0, 0); __builtin_amdgcn_s_setprio(0); } while (0)
; #define PG8_WAIT_V(n) asm volatile("s_waitcnt vmcnt(" #n ")" ::: "memory")
; #define PG8_WAIT_L(n) asm volatile("s_waitcnt lgkmcnt(" #n ")" ::: "memory")
; template <class Epi, class Sched, bool ALIGN_EPI = false, bool SP2 = false>
; __device__ __forceinline__ void gemm_phase(PG8_LAS unsigned char* lds, const Gemm g, const Sched& S, const Epi& E, const int wv) {
;     ...
;             const bool last = (t == nt - 2);
;             const char* a1 = cA + (size_t)(t + 1) * kstep;
;             const char* a2 = last ? nA : cA + (size_t)(t + 2) * kstep; const char* b2 = last ? nB : cB + (size_t)(t + 2) * kstep;
;             const char* a3 = a2 + kstep; const char* b3 = b2 + kstep;
;             if (last && has_next) S.a_ready(nxt);
;             if constexpr (SP2) {
;             PG8_LDB(B0, 0, 0); PG8_LDB(B1, 0, 1); PG8_SCHED; PG8_LDA(At, 0, 0); PG8_STAGE(PG8_SA(1, 1), a1 + hstepA, voffA);
;             PG8_WAIT_V(8); PG8_WAIT_L(0); PG8_BAR; PG8_MMA(0, 0, At, B0); PG8_MMA(0, 1, At, B1); PG8_BAR; PG8_SCHED;
;             PG8_LDA(At, 0, 1); PG8_STAGE(PG8_SB(0, 0), b2, voffB); PG8_STAGE(PG8_SB(0, 1), b2 + hstepB, voffB); PG8_STAGE(PG8_SA(0, 0), a2, voffA);
;             PG8_WAIT_V(8); PG8_WAIT_L(0); PG8_BAR; PG8_MMA(1, 0, At, B0); PG8_MMA(1, 1, At, B1); PG8_BAR; PG8_SCHED;
.LBB0_699:
	s_add_i32 s72, s54, 2
	s_add_u32 s73, s44, 0xfff80080
	s_addc_u32 s55, s45, -1
	s_cmp_eq_u32 s66, s54
	s_cselect_b32 s55, s31, s55
	s_cselect_b32 s54, s71, s73
	s_cselect_b32 s75, s13, s57
	s_cselect_b32 s74, s12, s56
	ds_read_b128 v[126:129], v190
	ds_read_b128 v[138:141], v190 offset:1024
	ds_read_b128 v[142:145], v190 offset:2048
	ds_read_b128 v[146:149], v190 offset:3072
	ds_read_b128 v[150:153], v191
	ds_read_b128 v[154:157], v191 offset:1024
	ds_read_b128 v[158:161], v191 offset:2048
	ds_read_b128 v[162:165], v191 offset:3072
	s_add_i32 m0, s59, 0xc000
	ds_read_b128 v[166:169], v235
	ds_read_b128 v[170:173], v235 offset:1024
	ds_read_b128 v[174:177], v235 offset:2048
	ds_read_b128 v[178:181], v235 offset:3072
	ds_read_b128 v[182:185], v235 offset:4096
	ds_read_b128 v[204:207], v235 offset:5120
	ds_read_b128 v[208:211], v235 offset:6144
	ds_read_b128 v[212:215], v235 offset:7168
	global_load_lds_dwordx4 v200, s[44:45]
	s_add_i32 m0, s59, 0xe000
	s_nop 0
	global_load_lds_dwordx4 v202, s[44:45]
	s_waitcnt vmcnt(8) lgkmcnt(0)
	s_barrier
	v_mfma_f32_16x16x32_bf16 v[134:137], v[126:129], v[166:169], v[134:137]
	v_mfma_f32_16x16x32_bf16 v[130:133], v[142:145], v[166:169], v[130:133]
	v_mfma_f32_16x16x32_bf16 v[110:113], v[126:129], v[174:177], v[110:113]
	v_mfma_f32_16x16x32_bf16 v[106:109], v[142:145], v[174:177], v[106:109]
	v_mfma_f32_16x16x32_bf16 v[94:97], v[126:129], v[182:185], v[94:97]
	v_mfma_f32_16x16x32_bf16 v[90:93], v[142:145], v[182:185], v[90:93]
	v_mfma_f32_16x16x32_bf16 v[78:81], v[126:129], v[208:211], v[78:81]
	v_mfma_f32_16x16x32_bf16 v[74:77], v[142:145], v[208:211], v[74:77]
	v_mfma_f32_16x16x32_bf16 v[134:137], v[138:141], v[170:173], v[134:137]
	v_mfma_f32_16x16x32_bf16 v[130:133], v[146:149], v[170:173], v[130:133]
	v_mfma_f32_16x16x32_bf16 v[110:113], v[138:141], v[178:181], v[110:113]
	v_mfma_f32_16x16x32_bf16 v[106:109], v[146:149], v[178:181], v[106:109]
	v_mfma_f32_16x16x32_bf16 v[94:97], v[138:141], v[204:207], v[94:97]
	v_mfma_f32_16x16x32_bf16 v[90:93], v[146:149], v[204:207], v[90:93]
	v_mfma_f32_16x16x32_bf16 v[78:81], v[138:141], v[212:215], v[78:81]
	v_mfma_f32_16x16x32_bf16 v[74:77], v[146:149], v[212:215], v[74:77]
	v_mfma_f32_16x16x32_bf16 v[122:125], v[150:153], v[166:169], v[122:125]
	v_mfma_f32_16x16x32_bf16 v[116:119], v[158:161], v[166:169], v[118:121]
	v_mfma_f32_16x16x32_bf16 v[102:105], v[150:153], v[174:177], v[102:105]
	v_mfma_f32_16x16x32_bf16 v[98:101], v[158:161], v[174:177], v[98:101]
	v_mfma_f32_16x16x32_bf16 v[86:89], v[150:153], v[182:185], v[86:89]
	v_mfma_f32_16x16x32_bf16 v[82:85], v[158:161], v[182:185], v[82:85]
	v_mfma_f32_16x16x32_bf16 v[70:73], v[150:153], v[208:211], v[70:73]
	v_mfma_f32_16x16x32_bf16 v[66:69], v[158:161], v[208:211], v[66:69]
	v_mfma_f32_16x16x32_bf16 v[122:125], v[154:157], v[170:173], v[122:125]
	v_mfma_f32_16x16x32_bf16 v[116:119], v[162:165], v[170:173], v[116:119]
	v_mfma_f32_16x16x32_bf16 v[102:105], v[154:157], v[178:181], v[102:105]
	v_mfma_f32_16x16x32_bf16 v[98:101], v[162:165], v[178:181], v[98:101]
	v_mfma_f32_16x16x32_bf16 v[86:89], v[154:157], v[204:207], v[86:89]
	v_mfma_f32_16x16x32_bf16 v[82:85], v[162:165], v[204:207], v[82:85]
	v_mfma_f32_16x16x32_bf16 v[70:73], v[154:157], v[212:215], v[70:73]
	v_mfma_f32_16x16x32_bf16 v[66:69], v[162:165], v[212:215], v[66:69]
	s_barrier
	s_add_i32 s76, s53, 0x10000
	v_lshl_add_u64 v[216:217], s[74:75], 0, v[0:1]
	s_mov_b32 m0, s76
	ds_read_b128 v[166:169], v235 offset:16384
	ds_read_b128 v[170:173], v235 offset:17408
	ds_read_b128 v[174:177], v235 offset:18432
	ds_read_b128 v[178:181], v235 offset:19456
	ds_read_b128 v[182:185], v235 offset:20480
	ds_read_b128 v[204:207], v235 offset:21504
	ds_read_b128 v[208:211], v235 offset:22528
	ds_read_b128 v[212:215], v235 offset:23552
	global_load_lds_dwordx4 v[216:217], off
	s_add_i32 m0, s76, 0x2000
	v_lshl_add_u64 v[218:219], s[74:75], 0, v[198:199]
	s_add_u32 s74, s74, s34
	s_addc_u32 s75, s75, s35
	s_add_i32 s73, s53, 0x14000
	global_load_lds_dwordx4 v[218:219], off
	s_mov_b32 m0, s73
	global_load_lds_dwordx4 v0, s[74:75]
	s_add_i32 m0, s73, 0x2000
	global_load_lds_dwordx4 v198, s[74:75]
	s_mov_b32 m0, s59
	global_load_lds_dwordx4 v194, s[54:55]
	s_mov_b32 m0, s60
	s_nop 0
	global_load_lds_dwordx4 v196, s[54:55]
	s_waitcnt vmcnt(8) lgkmcnt(0)
	s_barrier
	v_mfma_f32_16x16x32_bf16 v[62:65], v[126:129], v[166:169], v[62:65]
	v_mfma_f32_16x16x32_bf16 v[58:61], v[142:145], v[166:169], v[58:61]
	v_mfma_f32_16x16x32_bf16 v[46:49], v[126:129], v[174:177], v[46:49]
	v_mfma_f32_16x16x32_bf16 v[42:45], v[142:145], v[174:177], v[42:45]
	v_mfma_f32_16x16x32_bf16 v[30:33], v[126:129], v[182:185], v[30:33]
	v_mfma_f32_16x16x32_bf16 v[26:29], v[142:145], v[182:185], v[26:29]
	v_mfma_f32_16x16x32_bf16 v[14:17], v[126:129], v[208:211], v[14:17]
	v_mfma_f32_16x16x32_bf16 v[10:13], v[142:145], v[208:211], v[10:13]
	v_mfma_f32_16x16x32_bf16 v[62:65], v[138:141], v[170:173], v[62:65]
	v_mfma_f32_16x16x32_bf16 v[58:61], v[146:149], v[170:173], v[58:61]
	v_mfma_f32_16x16x32_bf16 v[46:49], v[138:141], v[178:181], v[46:49]
	v_mfma_f32_16x16x32_bf16 v[42:45], v[146:149], v[178:181], v[42:45]
	v_mfma_f32_16x16x32_bf16 v[30:33], v[138:141], v[204:207], v[30:33]
	v_mfma_f32_16x16x32_bf16 v[26:29], v[146:149], v[204:207], v[26:29]
	v_mfma_f32_16x16x32_bf16 v[14:17], v[138:141], v[212:215], v[14:17]
	v_mfma_f32_16x16x32_bf16 v[10:13], v[146:149], v[212:215], v[10:13]
	v_mfma_f32_16x16x32_bf16 v[54:57], v[150:153], v[166:169], v[54:57]
	v_mfma_f32_16x16x32_bf16 v[50:53], v[158:161], v[166:169], v[50:53]
	v_mfma_f32_16x16x32_bf16 v[38:41], v[150:153], v[174:177], v[38:41]
	v_mfma_f32_16x16x32_bf16 v[34:37], v[158:161], v[174:177], v[34:37]
	v_mfma_f32_16x16x32_bf16 v[22:25], v[150:153], v[182:185], v[22:25]
	v_mfma_f32_16x16x32_bf16 v[18:21], v[158:161], v[182:185], v[18:21]
	v_mfma_f32_16x16x32_bf16 v[6:9], v[150:153], v[208:211], v[6:9]
	v_mfma_f32_16x16x32_bf16 v[2:5], v[158:161], v[208:211], v[2:5]
	v_mfma_f32_16x16x32_bf16 v[54:57], v[154:157], v[170:173], v[54:57]
	v_mfma_f32_16x16x32_bf16 v[50:53], v[162:165], v[170:173], v[50:53]
	v_mfma_f32_16x16x32_bf16 v[38:41], v[154:157], v[178:181], v[38:41]
	v_mfma_f32_16x16x32_bf16 v[34:37], v[162:165], v[178:181], v[34:37]
	v_mfma_f32_16x16x32_bf16 v[22:25], v[154:157], v[204:207], v[22:25]
	v_mfma_f32_16x16x32_bf16 v[18:21], v[162:165], v[204:207], v[18:21]
	v_mfma_f32_16x16x32_bf16 v[6:9], v[154:157], v[212:215], v[6:9]
	v_mfma_f32_16x16x32_bf16 v[2:5], v[162:165], v[212:215], v[2:5]
	s_barrier
; #define PG8_STAGE(bufoff, gbase, voff) do { _Pragma("unroll") for (int _i = 0; _i < 2; ++_i) \
;         __builtin_amdgcn_global_load_lds((const unsigned*)((const char*)(gbase) + (voff)[_i]), (PG8_LAS unsigned*)(lds + (bufoff) + ldsw + _i * 8192), 16, 0, 0); } while (0)
; #define PG8_LDA(dst, b, h) do { _Pragma("unroll") for (int m = 0; m < 4; ++m) _Pragma("unroll") for (int k = 0; k < 2; ++k) dst[m][k] = *(const PG8_LAS bf16x8*)(lds + PG8_SA(b, h) + aoff + m * 2048 + k * 1024); } while (0)
; #define PG8_LDB(dst, b, h) do { _Pragma("unroll") for (int n = 0; n < 2; ++n) _Pragma("unroll") for (int k = 0; k < 2; ++k) dst[n][k] = *(const PG8_LAS bf16x8*)(lds + PG8_SB(b, h) + boff + n * 2048 + k * 1024); } while (0)
; #define PG8_MMA(ai, bj, At, Bt) do { __builtin_amdgcn_s_setprio(1); _Pragma("unroll") for (int m = 0; m < 4; ++m) _Pragma("unroll") for (int n = 0; n < 2; ++n) _Pragma("unroll") for (int k = 0; k < 2; ++k) \
;         acc[ai][bj][m][n] = __builtin_amdgcn_mfma_f32_16x16x32_bf16(Bt[n][k], At[m][k], acc[ai][bj][m][n], 0, 0, 0); __builtin_amdgcn_s_setprio(0); } while (0)
; #define PG8_WAIT_V(n) asm volatile("s_waitcnt vmcnt(" #n ")" ::: "memory")
; #define PG8_WAIT_L(n) asm volatile("s_waitcnt lgkmcnt(" #n ")" ::: "memory")
; #define PG8_BAR __builtin_amdgcn_s_barrier()
; #define PG8_SCHED __builtin_amdgcn_sched_barrier(0)
; template <class Epi, class Sched, bool ALIGN_EPI = false, bool SP2 = false>
; __device__ __forceinline__ void gemm_phase(PG8_LAS unsigned char* lds, const Gemm g, const Sched& S, const Epi& E, const int wv) {
;     ...
;         for (int t = 0; t < nt; t += 2) {
;     ...
;             PG8_LDB(B0, 1, 0); PG8_LDB(B1, 1, 1); PG8_SCHED; PG8_LDA(At, 1, 0); PG8_STAGE(PG8_SA(0, 1), a2 + hstepA, voffA);
;             PG8_WAIT_V(8); PG8_WAIT_L(0); PG8_BAR; PG8_MMA(0, 0, At, B0); PG8_MMA(0, 1, At, B1); PG8_BAR; PG8_SCHED;
;             PG8_LDA(At, 1, 1); PG8_STAGE(PG8_SB(1, 0), b3, voffB); PG8_STAGE(PG8_SB(1, 1), b3 + hstepB, voffB); PG8_STAGE(PG8_SA(1, 0), a3, voffA);
;             PG8_WAIT_V(8); PG8_WAIT_L(0); PG8_BAR; PG8_MMA(1, 0, At, B0); PG8_MMA(1, 1, At, B1); PG8_BAR; PG8_SCHED;
	ds_read_b128 v[126:129], v192
	ds_read_b128 v[138:141], v192 offset:1024
	ds_read_b128 v[142:145], v192 offset:2048
	ds_read_b128 v[146:149], v192 offset:3072
	ds_read_b128 v[150:153], v193
	ds_read_b128 v[154:157], v193 offset:1024
	ds_read_b128 v[158:161], v193 offset:2048
	ds_read_b128 v[162:165], v193 offset:3072
	s_mov_b32 m0, s61
	ds_read_b128 v[166:169], v235 offset:32768
	ds_read_b128 v[170:173], v235 offset:33792
	ds_read_b128 v[174:177], v235 offset:34816
	ds_read_b128 v[178:181], v235 offset:35840
	ds_read_b128 v[182:185], v235 offset:36864
	ds_read_b128 v[204:207], v235 offset:37888
	ds_read_b128 v[208:211], v235 offset:38912
	ds_read_b128 v[212:215], v235 offset:39936
	global_load_lds_dwordx4 v115, s[54:55]
	s_mov_b32 m0, s62
	s_nop 0
	global_load_lds_dwordx4 v201, s[54:55]
	s_waitcnt vmcnt(8) lgkmcnt(0)
	s_barrier
	v_mfma_f32_16x16x32_bf16 v[134:137], v[126:129], v[166:169], v[134:137]
	v_mfma_f32_16x16x32_bf16 v[130:133], v[142:145], v[166:169], v[130:133]
	v_mfma_f32_16x16x32_bf16 v[110:113], v[126:129], v[174:177], v[110:113]
	v_mfma_f32_16x16x32_bf16 v[106:109], v[142:145], v[174:177], v[106:109]
	v_mfma_f32_16x16x32_bf16 v[94:97], v[126:129], v[182:185], v[94:97]
	v_mfma_f32_16x16x32_bf16 v[90:93], v[142:145], v[182:185], v[90:93]
	v_mfma_f32_16x16x32_bf16 v[78:81], v[126:129], v[208:211], v[78:81]
	v_mfma_f32_16x16x32_bf16 v[74:77], v[142:145], v[208:211], v[74:77]
	v_mfma_f32_16x16x32_bf16 v[134:137], v[138:141], v[170:173], v[134:137]
	v_mfma_f32_16x16x32_bf16 v[130:133], v[146:149], v[170:173], v[130:133]
	v_mfma_f32_16x16x32_bf16 v[110:113], v[138:141], v[178:181], v[110:113]
	v_mfma_f32_16x16x32_bf16 v[106:109], v[146:149], v[178:181], v[106:109]
	v_mfma_f32_16x16x32_bf16 v[94:97], v[138:141], v[204:207], v[94:97]
	v_mfma_f32_16x16x32_bf16 v[90:93], v[146:149], v[204:207], v[90:93]
	v_mfma_f32_16x16x32_bf16 v[78:81], v[138:141], v[212:215], v[78:81]
	v_mfma_f32_16x16x32_bf16 v[74:77], v[146:149], v[212:215], v[74:77]
	v_mfma_f32_16x16x32_bf16 v[120:123], v[150:153], v[166:169], v[122:125]
	v_mfma_f32_16x16x32_bf16 v[116:119], v[158:161], v[166:169], v[116:119]
	v_mfma_f32_16x16x32_bf16 v[102:105], v[150:153], v[174:177], v[102:105]
	v_mfma_f32_16x16x32_bf16 v[98:101], v[158:161], v[174:177], v[98:101]
	v_mfma_f32_16x16x32_bf16 v[86:89], v[150:153], v[182:185], v[86:89]
	v_mfma_f32_16x16x32_bf16 v[82:85], v[158:161], v[182:185], v[82:85]
	v_mfma_f32_16x16x32_bf16 v[70:73], v[150:153], v[208:211], v[70:73]
	v_mfma_f32_16x16x32_bf16 v[66:69], v[158:161], v[208:211], v[66:69]
	v_mfma_f32_16x16x32_bf16 v[122:125], v[154:157], v[170:173], v[120:123]
	v_mfma_f32_16x16x32_bf16 v[118:121], v[162:165], v[170:173], v[116:119]
	v_mfma_f32_16x16x32_bf16 v[102:105], v[154:157], v[178:181], v[102:105]
	v_mfma_f32_16x16x32_bf16 v[98:101], v[162:165], v[178:181], v[98:101]
	v_mfma_f32_16x16x32_bf16 v[86:89], v[154:157], v[204:207], v[86:89]
	v_mfma_f32_16x16x32_bf16 v[82:85], v[162:165], v[204:207], v[82:85]
	v_mfma_f32_16x16x32_bf16 v[70:73], v[154:157], v[212:215], v[70:73]
	v_mfma_f32_16x16x32_bf16 v[66:69], v[162:165], v[212:215], v[66:69]
	s_barrier
	s_add_i32 m0, s53, 0x17f80
	ds_read_b128 v[166:169], v235 offset:49152
	ds_read_b128 v[170:173], v235 offset:50176
	ds_read_b128 v[174:177], v235 offset:51200
	ds_read_b128 v[178:181], v235 offset:52224
	ds_read_b128 v[182:185], v235 offset:53248
	ds_read_b128 v[204:207], v235 offset:54272
	ds_read_b128 v[208:211], v235 offset:55296
	ds_read_b128 v[212:215], v235 offset:56320
	global_load_lds_dwordx4 v[216:217], off offset:128
	s_add_i32 m0, s53, 0x19f80
	global_load_lds_dwordx4 v[218:219], off offset:128
	s_add_i32 m0, s53, 0x1bf80
	s_nop 0
	global_load_lds_dwordx4 v0, s[74:75] offset:128
	s_add_i32 m0, s53, 0x1df80
	s_nop 0
	global_load_lds_dwordx4 v198, s[74:75] offset:128
	s_add_i32 m0, s64, 0xffffff80
	s_nop 0
	global_load_lds_dwordx4 v194, s[54:55] offset:128
	s_add_i32 m0, s65, 0xffffff80
	s_nop 0
	global_load_lds_dwordx4 v196, s[54:55] offset:128
	s_waitcnt vmcnt(8) lgkmcnt(0)
	s_barrier
	v_mfma_f32_16x16x32_bf16 v[62:65], v[126:129], v[166:169], v[62:65]
	v_mfma_f32_16x16x32_bf16 v[58:61], v[142:145], v[166:169], v[58:61]
	v_mfma_f32_16x16x32_bf16 v[46:49], v[126:129], v[174:177], v[46:49]
	v_mfma_f32_16x16x32_bf16 v[42:45], v[142:145], v[174:177], v[42:45]
	v_mfma_f32_16x16x32_bf16 v[30:33], v[126:129], v[182:185], v[30:33]
	v_mfma_f32_16x16x32_bf16 v[26:29], v[142:145], v[182:185], v[26:29]
	v_mfma_f32_16x16x32_bf16 v[14:17], v[126:129], v[208:211], v[14:17]
	v_mfma_f32_16x16x32_bf16 v[10:13], v[142:145], v[208:211], v[10:13]
	v_mfma_f32_16x16x32_bf16 v[62:65], v[138:141], v[170:173], v[62:65]
	v_mfma_f32_16x16x32_bf16 v[58:61], v[146:149], v[170:173], v[58:61]
	v_mfma_f32_16x16x32_bf16 v[46:49], v[138:141], v[178:181], v[46:49]
	v_mfma_f32_16x16x32_bf16 v[42:45], v[146:149], v[178:181], v[42:45]
	v_mfma_f32_16x16x32_bf16 v[30:33], v[138:141], v[204:207], v[30:33]
	v_mfma_f32_16x16x32_bf16 v[26:29], v[146:149], v[204:207], v[26:29]
	v_mfma_f32_16x16x32_bf16 v[14:17], v[138:141], v[212:215], v[14:17]
	v_mfma_f32_16x16x32_bf16 v[10:13], v[146:149], v[212:215], v[10:13]
	v_mfma_f32_16x16x32_bf16 v[54:57], v[150:153], v[166:169], v[54:57]
	v_mfma_f32_16x16x32_bf16 v[50:53], v[158:161], v[166:169], v[50:53]
	v_mfma_f32_16x16x32_bf16 v[38:41], v[150:153], v[174:177], v[38:41]
	v_mfma_f32_16x16x32_bf16 v[34:37], v[158:161], v[174:177], v[34:37]
	v_mfma_f32_16x16x32_bf16 v[22:25], v[150:153], v[182:185], v[22:25]
	v_mfma_f32_16x16x32_bf16 v[18:21], v[158:161], v[182:185], v[18:21]
	v_mfma_f32_16x16x32_bf16 v[6:9], v[150:153], v[208:211], v[6:9]
	v_mfma_f32_16x16x32_bf16 v[2:5], v[158:161], v[208:211], v[2:5]
	v_mfma_f32_16x16x32_bf16 v[54:57], v[154:157], v[170:173], v[54:57]
	v_mfma_f32_16x16x32_bf16 v[50:53], v[162:165], v[170:173], v[50:53]
	v_mfma_f32_16x16x32_bf16 v[38:41], v[154:157], v[178:181], v[38:41]
	v_mfma_f32_16x16x32_bf16 v[34:37], v[162:165], v[178:181], v[34:37]
	v_mfma_f32_16x16x32_bf16 v[22:25], v[154:157], v[204:207], v[22:25]
	v_mfma_f32_16x16x32_bf16 v[18:21], v[162:165], v[204:207], v[18:21]
	v_mfma_f32_16x16x32_bf16 v[6:9], v[154:157], v[212:215], v[6:9]
	v_mfma_f32_16x16x32_bf16 v[2:5], v[162:165], v[212:215], v[2:5]
	s_add_u32 s44, s44, 0x100
	s_addc_u32 s45, s45, 0
	s_add_u32 s56, s56, 0x100
	s_addc_u32 s57, s57, 0
	s_cmp_ge_i32 s72, s63
	s_mov_b32 s54, s72
	s_barrier
	s_cbranch_scc0 .LBB0_699
	s_movk_i32 s75, 0x2000
	s_mov_b32 s72, 0x10000
	s_mov_b32 s73, 0x12000
	s_mov_b32 s74, 0x14000
	s_mov_b32 s71, 0x3f317217
	s_and_b64 vcc, exec, s[48:49]
	s_cbranch_vccz .LBB0_673

; #define PG8_STAGE(bufoff, gbase, voff) do { _Pragma("unroll") for (int _i = 0; _i < 2; ++_i) \
;         __builtin_amdgcn_global_load_lds((const unsigned*)((const char*)(gbase) + (voff)[_i]), (PG8_LAS unsigned*)(lds + (bufoff) + ldsw + _i * 8192), 16, 0, 0); } while (0)
; #define PG8_LDA(dst, b, h) do { _Pragma("unroll") for (int m = 0; m < 4; ++m) _Pragma("unroll") for (int k = 0; k < 2; ++k) dst[m][k] = *(const PG8_LAS bf16x8*)(lds + PG8_SA(b, h) + aoff + m * 2048 + k * 1024); } while (0)
; #define PG8_LDB(dst, b, h) do { _Pragma("unroll") for (int n = 0; n < 2; ++n) _Pragma("unroll") for (int k = 0; k < 2; ++k) dst[n][k] = *(const PG8_LAS bf16x8*)(lds + PG8_SB(b, h) + boff + n * 2048 + k * 1024); } while (0)
; #define PG8_MMA(ai, bj, At, Bt) do { __builtin_amdgcn_s_setprio(1); _Pragma("unroll") for (int m = 0; m < 4; ++m) _Pragma("unroll") for (int n = 0; n < 2; ++n) _Pragma("unroll") for (int k = 0; k < 2; ++k) \
;         acc[ai][bj][m][n] = __builtin_amdgcn_mfma_f32_16x16x32_bf16(Bt[n][k], At[m][k], acc[ai][bj][m][n], 0, 0, 0); __builtin_amdgcn_s_setprio(0); } while (0)
; #define PG8_WAIT_V(n) asm volatile("s_waitcnt vmcnt(" #n ")" ::: "memory")
; #define PG8_WAIT_L(n) asm volatile("s_waitcnt lgkmcnt(" #n ")" ::: "memory")
; template <class Epi, class Sched, bool ALIGN_EPI = false, bool SP2 = false>
; __device__ __forceinline__ void gemm_phase(PG8_LAS unsigned char* lds, const Gemm g, const Sched& S, const Epi& E, const int wv) {
;     ...
;             const bool last = (t == nt - 2);
;             const char* a1 = cA + (size_t)(t + 1) * kstep;
;             const char* a2 = last ? nA : cA + (size_t)(t + 2) * kstep; const char* b2 = last ? nB : cB + (size_t)(t + 2) * kstep;
;             const char* a3 = a2 + kstep; const char* b3 = b2 + kstep;
;             if (last && has_next) S.a_ready(nxt);
;             if constexpr (SP2) {
;             PG8_LDB(B0, 0, 0); PG8_LDB(B1, 0, 1); PG8_SCHED; PG8_LDA(At, 0, 0); PG8_STAGE(PG8_SA(1, 1), a1 + hstepA, voffA);
;             PG8_WAIT_V(8); PG8_WAIT_L(0); PG8_BAR; PG8_MMA(0, 0, At, B0); PG8_MMA(0, 1, At, B1); PG8_BAR; PG8_SCHED;
;             PG8_LDA(At, 0, 1); PG8_STAGE(PG8_SB(0, 0), b2, voffB); PG8_STAGE(PG8_SB(0, 1), b2 + hstepB, voffB); PG8_STAGE(PG8_SA(0, 0), a2, voffA);
;             PG8_WAIT_V(8); PG8_WAIT_L(0); PG8_BAR; PG8_MMA(1, 0, At, B0); PG8_MMA(1, 1, At, B1); PG8_BAR; PG8_SCHED;
.LBB0_809:
	s_add_i32 s52, s46, 2
	s_add_u32 s14, s48, 0x100
	s_addc_u32 s15, s49, 0
	s_cmp_eq_u32 s71, s46
	s_cselect_b32 s47, s11, s15
	s_cselect_b32 s46, s13, s14
	s_cselect_b32 s77, s87, s51
	s_cselect_b32 s76, s86, s35
	ds_read_b128 v[138:141], v192
	ds_read_b128 v[142:145], v192 offset:1024
	ds_read_b128 v[146:149], v192 offset:2048
	ds_read_b128 v[150:153], v192 offset:3072
	ds_read_b128 v[154:157], v193
	ds_read_b128 v[158:161], v193 offset:1024
	ds_read_b128 v[162:165], v193 offset:2048
	ds_read_b128 v[166:169], v193 offset:3072
	s_add_i32 m0, s63, 0xc000
	ds_read_b128 v[194:197], v211
	ds_read_b128 v[198:201], v211 offset:1024
	ds_read_b128 v[202:205], v211 offset:2048
	ds_read_b128 v[214:217], v211 offset:3072
	ds_read_b128 v[228:231], v211 offset:4096
	ds_read_b128 v[232:235], v211 offset:5120
	ds_read_b128 v[236:239], v211 offset:6144
	ds_read_b128 v[240:243], v211 offset:7168
	global_load_lds_dwordx4 v182, s[48:49]
	v_lshl_add_u64 v[190:191], s[48:49], 0, v[184:185]
	s_add_i32 m0, s63, 0xe000
	s_nop 0
	global_load_lds_dwordx4 v[190:191], off
	s_waitcnt vmcnt(8) lgkmcnt(0)
	s_barrier
	v_mfma_f32_16x16x32_bf16 v[118:121], v[138:141], v[194:197], v[118:121]
	v_mfma_f32_16x16x32_bf16 v[46:49], v[146:149], v[194:197], v[46:49]
	v_mfma_f32_16x16x32_bf16 v[110:113], v[138:141], v[202:205], v[110:113]
	v_mfma_f32_16x16x32_bf16 v[38:41], v[146:149], v[202:205], v[38:41]
	v_mfma_f32_16x16x32_bf16 v[134:137], v[138:141], v[228:231], v[134:137]
	v_mfma_f32_16x16x32_bf16 v[62:65], v[146:149], v[228:231], v[62:65]
	v_mfma_f32_16x16x32_bf16 v[130:133], v[138:141], v[236:239], v[130:133]
	v_mfma_f32_16x16x32_bf16 v[58:61], v[146:149], v[236:239], v[58:61]
	v_mfma_f32_16x16x32_bf16 v[118:121], v[142:145], v[198:201], v[118:121]
	v_mfma_f32_16x16x32_bf16 v[46:49], v[150:153], v[198:201], v[46:49]
	v_mfma_f32_16x16x32_bf16 v[110:113], v[142:145], v[214:217], v[110:113]
	v_mfma_f32_16x16x32_bf16 v[38:41], v[150:153], v[214:217], v[38:41]
	v_mfma_f32_16x16x32_bf16 v[134:137], v[142:145], v[232:235], v[134:137]
	v_mfma_f32_16x16x32_bf16 v[62:65], v[150:153], v[232:235], v[62:65]
	v_mfma_f32_16x16x32_bf16 v[130:133], v[142:145], v[240:243], v[130:133]
	v_mfma_f32_16x16x32_bf16 v[58:61], v[150:153], v[240:243], v[58:61]
	v_mfma_f32_16x16x32_bf16 v[114:117], v[154:157], v[194:197], v[114:117]
	v_mfma_f32_16x16x32_bf16 v[42:45], v[162:165], v[194:197], v[42:45]
	v_mfma_f32_16x16x32_bf16 v[106:109], v[154:157], v[202:205], v[106:109]
	v_mfma_f32_16x16x32_bf16 v[34:37], v[162:165], v[202:205], v[34:37]
	v_mfma_f32_16x16x32_bf16 v[126:129], v[154:157], v[228:231], v[126:129]
	v_mfma_f32_16x16x32_bf16 v[54:57], v[162:165], v[228:231], v[54:57]
	v_mfma_f32_16x16x32_bf16 v[122:125], v[154:157], v[236:239], v[122:125]
	v_mfma_f32_16x16x32_bf16 v[50:53], v[162:165], v[236:239], v[50:53]
	v_mfma_f32_16x16x32_bf16 v[114:117], v[158:161], v[198:201], v[114:117]
	v_mfma_f32_16x16x32_bf16 v[42:45], v[166:169], v[198:201], v[42:45]
	v_mfma_f32_16x16x32_bf16 v[106:109], v[158:161], v[214:217], v[106:109]
	v_mfma_f32_16x16x32_bf16 v[34:37], v[166:169], v[214:217], v[34:37]
	v_mfma_f32_16x16x32_bf16 v[126:129], v[158:161], v[232:235], v[126:129]
	v_mfma_f32_16x16x32_bf16 v[54:57], v[166:169], v[232:235], v[54:57]
	v_mfma_f32_16x16x32_bf16 v[122:125], v[158:161], v[240:243], v[122:125]
	v_mfma_f32_16x16x32_bf16 v[50:53], v[166:169], v[240:243], v[50:53]
	s_barrier
	s_add_i32 s48, s62, 0x10000
	s_mov_b32 m0, s48
	ds_read_b128 v[194:197], v211 offset:16384
	ds_read_b128 v[198:201], v211 offset:17408
	ds_read_b128 v[202:205], v211 offset:18432
	ds_read_b128 v[214:217], v211 offset:19456
	ds_read_b128 v[228:231], v211 offset:20480
	ds_read_b128 v[232:235], v211 offset:21504
	ds_read_b128 v[236:239], v211 offset:22528
	ds_read_b128 v[240:243], v211 offset:23552
	global_load_lds_dwordx4 v0, s[76:77]
	s_add_i32 m0, s48, 0x2000
	s_add_u32 s48, s76, s16
	s_addc_u32 s49, s77, s17
	s_add_i32 s53, s62, 0x14000
	global_load_lds_dwordx4 v174, s[76:77]
	s_mov_b32 m0, s53
	global_load_lds_dwordx4 v0, s[48:49]
	s_add_i32 m0, s53, 0x2000
	global_load_lds_dwordx4 v174, s[48:49]
	s_mov_b32 m0, s63
	global_load_lds_dwordx4 v170, s[46:47]
	s_mov_b32 m0, s64
	s_nop 0
	global_load_lds_dwordx4 v172, s[46:47]
	s_waitcnt vmcnt(8) lgkmcnt(0)
	s_barrier
	v_mfma_f32_16x16x32_bf16 v[86:89], v[138:141], v[194:197], v[86:89]
	v_mfma_f32_16x16x32_bf16 v[14:17], v[146:149], v[194:197], v[14:17]
	v_mfma_f32_16x16x32_bf16 v[70:73], v[138:141], v[202:205], v[70:73]
	v_mfma_f32_16x16x32_bf16 v[6:9], v[146:149], v[202:205], v[6:9]
	v_mfma_f32_16x16x32_bf16 v[102:105], v[138:141], v[228:231], v[102:105]
	v_mfma_f32_16x16x32_bf16 v[30:33], v[146:149], v[228:231], v[30:33]
	v_mfma_f32_16x16x32_bf16 v[98:101], v[138:141], v[236:239], v[98:101]
	v_mfma_f32_16x16x32_bf16 v[26:29], v[146:149], v[236:239], v[26:29]
	v_mfma_f32_16x16x32_bf16 v[86:89], v[142:145], v[198:201], v[86:89]
	v_mfma_f32_16x16x32_bf16 v[14:17], v[150:153], v[198:201], v[14:17]
	v_mfma_f32_16x16x32_bf16 v[70:73], v[142:145], v[214:217], v[70:73]
	v_mfma_f32_16x16x32_bf16 v[6:9], v[150:153], v[214:217], v[6:9]
	v_mfma_f32_16x16x32_bf16 v[102:105], v[142:145], v[232:235], v[102:105]
	v_mfma_f32_16x16x32_bf16 v[30:33], v[150:153], v[232:235], v[30:33]
	v_mfma_f32_16x16x32_bf16 v[98:101], v[142:145], v[240:243], v[98:101]
	v_mfma_f32_16x16x32_bf16 v[26:29], v[150:153], v[240:243], v[26:29]
	v_mfma_f32_16x16x32_bf16 v[82:85], v[154:157], v[194:197], v[82:85]
	v_mfma_f32_16x16x32_bf16 v[10:13], v[162:165], v[194:197], v[10:13]
	v_mfma_f32_16x16x32_bf16 v[66:69], v[154:157], v[202:205], v[66:69]
	v_mfma_f32_16x16x32_bf16 v[2:5], v[162:165], v[202:205], v[2:5]
	v_mfma_f32_16x16x32_bf16 v[94:97], v[154:157], v[228:231], v[94:97]
	v_mfma_f32_16x16x32_bf16 v[22:25], v[162:165], v[228:231], v[22:25]
	v_mfma_f32_16x16x32_bf16 v[90:93], v[154:157], v[236:239], v[90:93]
	v_mfma_f32_16x16x32_bf16 v[18:21], v[162:165], v[236:239], v[18:21]
	v_mfma_f32_16x16x32_bf16 v[82:85], v[158:161], v[198:201], v[82:85]
	v_mfma_f32_16x16x32_bf16 v[10:13], v[166:169], v[198:201], v[10:13]
	v_mfma_f32_16x16x32_bf16 v[66:69], v[158:161], v[214:217], v[66:69]
	v_mfma_f32_16x16x32_bf16 v[2:5], v[166:169], v[214:217], v[2:5]
	v_mfma_f32_16x16x32_bf16 v[94:97], v[158:161], v[232:235], v[94:97]
	v_mfma_f32_16x16x32_bf16 v[22:25], v[166:169], v[232:235], v[22:25]
	v_mfma_f32_16x16x32_bf16 v[90:93], v[158:161], v[240:243], v[90:93]
	v_mfma_f32_16x16x32_bf16 v[18:21], v[166:169], v[240:243], v[18:21]
	s_barrier
; #define PG8_STAGE(bufoff, gbase, voff) do { _Pragma("unroll") for (int _i = 0; _i < 2; ++_i) \
;         __builtin_amdgcn_global_load_lds((const unsigned*)((const char*)(gbase) + (voff)[_i]), (PG8_LAS unsigned*)(lds + (bufoff) + ldsw + _i * 8192), 16, 0, 0); } while (0)
; #define PG8_LDA(dst, b, h) do { _Pragma("unroll") for (int m = 0; m < 4; ++m) _Pragma("unroll") for (int k = 0; k < 2; ++k) dst[m][k] = *(const PG8_LAS bf16x8*)(lds + PG8_SA(b, h) + aoff + m * 2048 + k * 1024); } while (0)
; #define PG8_LDB(dst, b, h) do { _Pragma("unroll") for (int n = 0; n < 2; ++n) _Pragma("unroll") for (int k = 0; k < 2; ++k) dst[n][k] = *(const PG8_LAS bf16x8*)(lds + PG8_SB(b, h) + boff + n * 2048 + k * 1024); } while (0)
; #define PG8_MMA(ai, bj, At, Bt) do { __builtin_amdgcn_s_setprio(1); _Pragma("unroll") for (int m = 0; m < 4; ++m) _Pragma("unroll") for (int n = 0; n < 2; ++n) _Pragma("unroll") for (int k = 0; k < 2; ++k) \
;         acc[ai][bj][m][n] = __builtin_amdgcn_mfma_f32_16x16x32_bf16(Bt[n][k], At[m][k], acc[ai][bj][m][n], 0, 0, 0); __builtin_amdgcn_s_setprio(0); } while (0)
; #define PG8_WAIT_V(n) asm volatile("s_waitcnt vmcnt(" #n ")" ::: "memory")
; #define PG8_WAIT_L(n) asm volatile("s_waitcnt lgkmcnt(" #n ")" ::: "memory")
; #define PG8_BAR __builtin_amdgcn_s_barrier()
; template <class Epi, class Sched, bool ALIGN_EPI = false, bool SP2 = false>
; __device__ __forceinline__ void gemm_phase(PG8_LAS unsigned char* lds, const Gemm g, const Sched& S, const Epi& E, const int wv) {
;     ...
;         for (int t = 0; t < nt; t += 2) {
;             const bool last = (t == nt - 2);
;             const char* a1 = cA + (size_t)(t + 1) * kstep;
;             const char* a2 = last ? nA : cA + (size_t)(t + 2) * kstep; const char* b2 = last ? nB : cB + (size_t)(t + 2) * kstep;
;             const char* a3 = a2 + kstep; const char* b3 = b2 + kstep;
;     ...
;             PG8_LDB(B0, 1, 0); PG8_LDB(B1, 1, 1); PG8_SCHED; PG8_LDA(At, 1, 0); PG8_STAGE(PG8_SA(0, 1), a2 + hstepA, voffA);
;             PG8_WAIT_V(8); PG8_WAIT_L(0); PG8_BAR; PG8_MMA(0, 0, At, B0); PG8_MMA(0, 1, At, B1); PG8_BAR; PG8_SCHED;
;             PG8_LDA(At, 1, 1); PG8_STAGE(PG8_SB(1, 0), b3, voffB); PG8_STAGE(PG8_SB(1, 1), b3 + hstepB, voffB); PG8_STAGE(PG8_SA(1, 0), a3, voffA);
;             PG8_WAIT_V(8); PG8_WAIT_L(0); PG8_BAR; PG8_MMA(1, 0, At, B0); PG8_MMA(1, 1, At, B1); PG8_BAR; PG8_SCHED;
	ds_read_b128 v[138:141], v213
	ds_read_b128 v[142:145], v213 offset:1024
	ds_read_b128 v[146:149], v213 offset:2048
	ds_read_b128 v[150:153], v213 offset:3072
	ds_read_b128 v[154:157], v227
	ds_read_b128 v[158:161], v227 offset:1024
	ds_read_b128 v[162:165], v227 offset:2048
	ds_read_b128 v[166:169], v227 offset:3072
	s_mov_b32 m0, s65
	ds_read_b128 v[194:197], v211 offset:32768
	ds_read_b128 v[198:201], v211 offset:33792
	ds_read_b128 v[202:205], v211 offset:34816
	ds_read_b128 v[214:217], v211 offset:35840
	ds_read_b128 v[228:231], v211 offset:36864
	ds_read_b128 v[232:235], v211 offset:37888
	ds_read_b128 v[236:239], v211 offset:38912
	ds_read_b128 v[240:243], v211 offset:39936
	global_load_lds_dwordx4 v218, s[46:47]
	s_mov_b32 m0, s66
	s_nop 0
	global_load_lds_dwordx4 v219, s[46:47]
	s_waitcnt vmcnt(8) lgkmcnt(0)
	s_barrier
	v_mfma_f32_16x16x32_bf16 v[118:121], v[138:141], v[194:197], v[118:121]
	v_mfma_f32_16x16x32_bf16 v[46:49], v[146:149], v[194:197], v[46:49]
	v_mfma_f32_16x16x32_bf16 v[110:113], v[138:141], v[202:205], v[110:113]
	v_mfma_f32_16x16x32_bf16 v[38:41], v[146:149], v[202:205], v[38:41]
	v_mfma_f32_16x16x32_bf16 v[134:137], v[138:141], v[228:231], v[134:137]
	v_mfma_f32_16x16x32_bf16 v[62:65], v[146:149], v[228:231], v[62:65]
	v_mfma_f32_16x16x32_bf16 v[130:133], v[138:141], v[236:239], v[130:133]
	v_mfma_f32_16x16x32_bf16 v[58:61], v[146:149], v[236:239], v[58:61]
	v_mfma_f32_16x16x32_bf16 v[118:121], v[142:145], v[198:201], v[118:121]
	v_mfma_f32_16x16x32_bf16 v[46:49], v[150:153], v[198:201], v[46:49]
	v_mfma_f32_16x16x32_bf16 v[110:113], v[142:145], v[214:217], v[110:113]
	v_mfma_f32_16x16x32_bf16 v[38:41], v[150:153], v[214:217], v[38:41]
	v_mfma_f32_16x16x32_bf16 v[134:137], v[142:145], v[232:235], v[134:137]
	v_mfma_f32_16x16x32_bf16 v[62:65], v[150:153], v[232:235], v[62:65]
	v_mfma_f32_16x16x32_bf16 v[130:133], v[142:145], v[240:243], v[130:133]
	v_mfma_f32_16x16x32_bf16 v[58:61], v[150:153], v[240:243], v[58:61]
	v_mfma_f32_16x16x32_bf16 v[114:117], v[154:157], v[194:197], v[114:117]
	v_mfma_f32_16x16x32_bf16 v[42:45], v[162:165], v[194:197], v[42:45]
	v_mfma_f32_16x16x32_bf16 v[106:109], v[154:157], v[202:205], v[106:109]
	v_mfma_f32_16x16x32_bf16 v[34:37], v[162:165], v[202:205], v[34:37]
	v_mfma_f32_16x16x32_bf16 v[126:129], v[154:157], v[228:231], v[126:129]
	v_mfma_f32_16x16x32_bf16 v[54:57], v[162:165], v[228:231], v[54:57]
	v_mfma_f32_16x16x32_bf16 v[122:125], v[154:157], v[236:239], v[122:125]
	v_mfma_f32_16x16x32_bf16 v[50:53], v[162:165], v[236:239], v[50:53]
	v_mfma_f32_16x16x32_bf16 v[114:117], v[158:161], v[198:201], v[114:117]
	v_mfma_f32_16x16x32_bf16 v[42:45], v[166:169], v[198:201], v[42:45]
	v_mfma_f32_16x16x32_bf16 v[106:109], v[158:161], v[214:217], v[106:109]
	v_mfma_f32_16x16x32_bf16 v[34:37], v[166:169], v[214:217], v[34:37]
	v_mfma_f32_16x16x32_bf16 v[126:129], v[158:161], v[232:235], v[126:129]
	v_mfma_f32_16x16x32_bf16 v[54:57], v[166:169], v[232:235], v[54:57]
	v_mfma_f32_16x16x32_bf16 v[122:125], v[158:161], v[240:243], v[122:125]
	v_mfma_f32_16x16x32_bf16 v[50:53], v[166:169], v[240:243], v[50:53]
	s_barrier
	s_add_i32 m0, s62, 0x17f80
	ds_read_b128 v[194:197], v211 offset:49152
	ds_read_b128 v[198:201], v211 offset:50176
	ds_read_b128 v[202:205], v211 offset:51200
	ds_read_b128 v[214:217], v211 offset:52224
	ds_read_b128 v[228:231], v211 offset:53248
	ds_read_b128 v[232:235], v211 offset:54272
	ds_read_b128 v[236:239], v211 offset:55296
	ds_read_b128 v[240:243], v211 offset:56320
	global_load_lds_dwordx4 v0, s[76:77] offset:128
	s_add_i32 m0, s62, 0x19f80
	global_load_lds_dwordx4 v174, s[76:77] offset:128
	s_add_i32 m0, s62, 0x1bf80
	s_nop 0
	global_load_lds_dwordx4 v0, s[48:49] offset:128
	s_add_i32 m0, s62, 0x1df80
	s_nop 0
	global_load_lds_dwordx4 v174, s[48:49] offset:128
	s_add_i32 m0, s69, 0xffffff80
	s_nop 0
	global_load_lds_dwordx4 v170, s[46:47] offset:128
	s_add_i32 m0, s70, 0xffffff80
	s_nop 0
	global_load_lds_dwordx4 v172, s[46:47] offset:128
	s_waitcnt vmcnt(8) lgkmcnt(0)
	s_barrier
	v_mfma_f32_16x16x32_bf16 v[86:89], v[138:141], v[194:197], v[86:89]
	v_mfma_f32_16x16x32_bf16 v[14:17], v[146:149], v[194:197], v[14:17]
	v_mfma_f32_16x16x32_bf16 v[70:73], v[138:141], v[202:205], v[70:73]
	v_mfma_f32_16x16x32_bf16 v[6:9], v[146:149], v[202:205], v[6:9]
	v_mfma_f32_16x16x32_bf16 v[102:105], v[138:141], v[228:231], v[102:105]
	v_mfma_f32_16x16x32_bf16 v[30:33], v[146:149], v[228:231], v[30:33]
	v_mfma_f32_16x16x32_bf16 v[98:101], v[138:141], v[236:239], v[98:101]
	v_mfma_f32_16x16x32_bf16 v[26:29], v[146:149], v[236:239], v[26:29]
	v_mfma_f32_16x16x32_bf16 v[86:89], v[142:145], v[198:201], v[86:89]
	v_mfma_f32_16x16x32_bf16 v[14:17], v[150:153], v[198:201], v[14:17]
	v_mfma_f32_16x16x32_bf16 v[70:73], v[142:145], v[214:217], v[70:73]
	v_mfma_f32_16x16x32_bf16 v[6:9], v[150:153], v[214:217], v[6:9]
	v_mfma_f32_16x16x32_bf16 v[102:105], v[142:145], v[232:235], v[102:105]
	v_mfma_f32_16x16x32_bf16 v[30:33], v[150:153], v[232:235], v[30:33]
	v_mfma_f32_16x16x32_bf16 v[98:101], v[142:145], v[240:243], v[98:101]
	v_mfma_f32_16x16x32_bf16 v[26:29], v[150:153], v[240:243], v[26:29]
	v_mfma_f32_16x16x32_bf16 v[82:85], v[154:157], v[194:197], v[82:85]
	v_mfma_f32_16x16x32_bf16 v[10:13], v[162:165], v[194:197], v[10:13]
	v_mfma_f32_16x16x32_bf16 v[66:69], v[154:157], v[202:205], v[66:69]
	v_mfma_f32_16x16x32_bf16 v[2:5], v[162:165], v[202:205], v[2:5]
	v_mfma_f32_16x16x32_bf16 v[94:97], v[154:157], v[228:231], v[94:97]
	v_mfma_f32_16x16x32_bf16 v[22:25], v[162:165], v[228:231], v[22:25]
	v_mfma_f32_16x16x32_bf16 v[90:93], v[154:157], v[236:239], v[90:93]
	v_mfma_f32_16x16x32_bf16 v[18:21], v[162:165], v[236:239], v[18:21]
	v_mfma_f32_16x16x32_bf16 v[82:85], v[158:161], v[198:201], v[82:85]
	v_mfma_f32_16x16x32_bf16 v[10:13], v[166:169], v[198:201], v[10:13]
	v_mfma_f32_16x16x32_bf16 v[66:69], v[158:161], v[214:217], v[66:69]
	v_mfma_f32_16x16x32_bf16 v[2:5], v[166:169], v[214:217], v[2:5]
	v_mfma_f32_16x16x32_bf16 v[94:97], v[158:161], v[232:235], v[94:97]
	v_mfma_f32_16x16x32_bf16 v[22:25], v[166:169], v[232:235], v[22:25]
	v_mfma_f32_16x16x32_bf16 v[90:93], v[158:161], v[240:243], v[90:93]
	v_mfma_f32_16x16x32_bf16 v[18:21], v[166:169], v[240:243], v[18:21]
	s_add_u32 s35, s35, 0x100
	s_addc_u32 s51, s51, 0
	s_cmp_ge_i32 s52, s67
	s_mov_b64 s[48:49], s[14:15]
	s_mov_b32 s46, s52
	s_barrier
	s_cbranch_scc0 .LBB0_809
	s_movk_i32 s75, 0x2000
	s_movk_i32 s76, 0x3000
	s_and_b64 vcc, exec, s[30:31]
	s_cbranch_vccz .LBB0_784

; #define PG8_STAGE(bufoff, gbase, voff) do { _Pragma("unroll") for (int _i = 0; _i < 2; ++_i) \
;         __builtin_amdgcn_global_load_lds((const unsigned*)((const char*)(gbase) + (voff)[_i]), (PG8_LAS unsigned*)(lds + (bufoff) + ldsw + _i * 8192), 16, 0, 0); } while (0)
; #define PG8_LDA(dst, b, h) do { _Pragma("unroll") for (int m = 0; m < 4; ++m) _Pragma("unroll") for (int k = 0; k < 2; ++k) dst[m][k] = *(const PG8_LAS bf16x8*)(lds + PG8_SA(b, h) + aoff + m * 2048 + k * 1024); } while (0)
; #define PG8_LDB(dst, b, h) do { _Pragma("unroll") for (int n = 0; n < 2; ++n) _Pragma("unroll") for (int k = 0; k < 2; ++k) dst[n][k] = *(const PG8_LAS bf16x8*)(lds + PG8_SB(b, h) + boff + n * 2048 + k * 1024); } while (0)
; #define PG8_MMA(ai, bj, At, Bt) do { __builtin_amdgcn_s_setprio(1); _Pragma("unroll") for (int m = 0; m < 4; ++m) _Pragma("unroll") for (int n = 0; n < 2; ++n) _Pragma("unroll") for (int k = 0; k < 2; ++k) \
;         acc[ai][bj][m][n] = __builtin_amdgcn_mfma_f32_16x16x32_bf16(Bt[n][k], At[m][k], acc[ai][bj][m][n], 0, 0, 0); __builtin_amdgcn_s_setprio(0); } while (0)
; #define PG8_WAIT_V(n) asm volatile("s_waitcnt vmcnt(" #n ")" ::: "memory")
; #define PG8_WAIT_L(n) asm volatile("s_waitcnt lgkmcnt(" #n ")" ::: "memory")
; template <class Epi, class Sched, bool ALIGN_EPI = false, bool SP2 = false>
; __device__ __forceinline__ void gemm_phase(PG8_LAS unsigned char* lds, const Gemm g, const Sched& S, const Epi& E, const int wv) {
;     ...
;             const bool last = (t == nt - 2);
;             const char* a1 = cA + (size_t)(t + 1) * kstep;
;             const char* a2 = last ? nA : cA + (size_t)(t + 2) * kstep; const char* b2 = last ? nB : cB + (size_t)(t + 2) * kstep;
;             const char* a3 = a2 + kstep; const char* b3 = b2 + kstep;
;             if (last && has_next) S.a_ready(nxt);
;             if constexpr (SP2) {
;             PG8_LDB(B0, 0, 0); PG8_LDB(B1, 0, 1); PG8_SCHED; PG8_LDA(At, 0, 0); PG8_STAGE(PG8_SA(1, 1), a1 + hstepA, voffA);
;             PG8_WAIT_V(8); PG8_WAIT_L(0); PG8_BAR; PG8_MMA(0, 0, At, B0); PG8_MMA(0, 1, At, B1); PG8_BAR; PG8_SCHED;
;             PG8_LDA(At, 0, 1); PG8_STAGE(PG8_SB(0, 0), b2, voffB); PG8_STAGE(PG8_SB(0, 1), b2 + hstepB, voffB); PG8_STAGE(PG8_SA(0, 0), a2, voffA);
;             PG8_WAIT_V(8); PG8_WAIT_L(0); PG8_BAR; PG8_MMA(1, 0, At, B0); PG8_MMA(1, 1, At, B1); PG8_BAR; PG8_SCHED;
.LBB0_990:
	s_add_i32 s67, s44, 2
	s_add_u32 s34, s30, 0x100
	s_addc_u32 s35, s31, 0
	s_cmp_eq_u32 s59, s44
	s_cselect_b32 s45, s13, s35
	s_cselect_b32 s44, s12, s34
	s_cselect_b32 s69, s15, s66
	s_cselect_b32 s68, s14, s65
	ds_read_b128 v[114:117], v197
	ds_read_b128 v[126:129], v197 offset:1024
	ds_read_b128 v[138:141], v197 offset:2048
	ds_read_b128 v[142:145], v197 offset:3072
	ds_read_b128 v[146:149], v201
	ds_read_b128 v[150:153], v201 offset:1024
	ds_read_b128 v[154:157], v201 offset:2048
	ds_read_b128 v[158:161], v201 offset:3072
	s_add_i32 m0, s52, 0xc000
	ds_read_b128 v[162:165], v235
	ds_read_b128 v[166:169], v235 offset:1024
	ds_read_b128 v[170:173], v235 offset:2048
	ds_read_b128 v[174:177], v235 offset:3072
	ds_read_b128 v[178:181], v235 offset:4096
	ds_read_b128 v[182:185], v235 offset:5120
	ds_read_b128 v[204:207], v235 offset:6144
	ds_read_b128 v[208:211], v235 offset:7168
	global_load_lds_dwordx4 v200, s[30:31]
	s_add_i32 m0, s52, 0xe000
	s_nop 0
	global_load_lds_dwordx4 v202, s[30:31]
	s_waitcnt vmcnt(8) lgkmcnt(0)
	s_barrier
	v_mfma_f32_16x16x32_bf16 v[134:137], v[114:117], v[162:165], v[134:137]
	v_mfma_f32_16x16x32_bf16 v[130:133], v[138:141], v[162:165], v[130:133]
	v_mfma_f32_16x16x32_bf16 v[110:113], v[114:117], v[170:173], v[110:113]
	v_mfma_f32_16x16x32_bf16 v[106:109], v[138:141], v[170:173], v[106:109]
	v_mfma_f32_16x16x32_bf16 v[94:97], v[114:117], v[178:181], v[94:97]
	v_mfma_f32_16x16x32_bf16 v[90:93], v[138:141], v[178:181], v[90:93]
	v_mfma_f32_16x16x32_bf16 v[78:81], v[114:117], v[204:207], v[78:81]
	v_mfma_f32_16x16x32_bf16 v[74:77], v[138:141], v[204:207], v[74:77]
	v_mfma_f32_16x16x32_bf16 v[134:137], v[126:129], v[166:169], v[134:137]
	v_mfma_f32_16x16x32_bf16 v[130:133], v[142:145], v[166:169], v[130:133]
	v_mfma_f32_16x16x32_bf16 v[110:113], v[126:129], v[174:177], v[110:113]
	v_mfma_f32_16x16x32_bf16 v[106:109], v[142:145], v[174:177], v[106:109]
	v_mfma_f32_16x16x32_bf16 v[94:97], v[126:129], v[182:185], v[94:97]
	v_mfma_f32_16x16x32_bf16 v[90:93], v[142:145], v[182:185], v[90:93]
	v_mfma_f32_16x16x32_bf16 v[78:81], v[126:129], v[208:211], v[78:81]
	v_mfma_f32_16x16x32_bf16 v[74:77], v[142:145], v[208:211], v[74:77]
	v_mfma_f32_16x16x32_bf16 v[122:125], v[146:149], v[162:165], v[122:125]
	v_mfma_f32_16x16x32_bf16 v[118:121], v[154:157], v[162:165], v[118:121]
	v_mfma_f32_16x16x32_bf16 v[102:105], v[146:149], v[170:173], v[102:105]
	v_mfma_f32_16x16x32_bf16 v[98:101], v[154:157], v[170:173], v[98:101]
	v_mfma_f32_16x16x32_bf16 v[86:89], v[146:149], v[178:181], v[86:89]
	v_mfma_f32_16x16x32_bf16 v[82:85], v[154:157], v[178:181], v[82:85]
	v_mfma_f32_16x16x32_bf16 v[70:73], v[146:149], v[204:207], v[70:73]
	v_mfma_f32_16x16x32_bf16 v[66:69], v[154:157], v[204:207], v[66:69]
	v_mfma_f32_16x16x32_bf16 v[122:125], v[150:153], v[166:169], v[122:125]
	v_mfma_f32_16x16x32_bf16 v[118:121], v[158:161], v[166:169], v[118:121]
	v_mfma_f32_16x16x32_bf16 v[102:105], v[150:153], v[174:177], v[102:105]
	v_mfma_f32_16x16x32_bf16 v[98:101], v[158:161], v[174:177], v[98:101]
	v_mfma_f32_16x16x32_bf16 v[86:89], v[150:153], v[182:185], v[86:89]
	v_mfma_f32_16x16x32_bf16 v[82:85], v[158:161], v[182:185], v[82:85]
	v_mfma_f32_16x16x32_bf16 v[70:73], v[150:153], v[208:211], v[70:73]
	v_mfma_f32_16x16x32_bf16 v[66:69], v[158:161], v[208:211], v[66:69]
	s_barrier
	s_add_i32 s30, s47, 0x10000
	v_lshl_add_u64 v[190:191], s[68:69], 0, v[0:1]
	s_mov_b32 m0, s30
	ds_read_b128 v[162:165], v235 offset:16384
	ds_read_b128 v[166:169], v235 offset:17408
	ds_read_b128 v[170:173], v235 offset:18432
	ds_read_b128 v[174:177], v235 offset:19456
	ds_read_b128 v[178:181], v235 offset:20480
	ds_read_b128 v[182:185], v235 offset:21504
	ds_read_b128 v[204:207], v235 offset:22528
	ds_read_b128 v[208:211], v235 offset:23552
	global_load_lds_dwordx4 v[190:191], off
	s_add_i32 m0, s30, 0x2000
	s_add_u32 s30, s68, s2
	v_lshl_add_u64 v[192:193], s[68:69], 0, v[198:199]
	s_addc_u32 s31, s69, s3
	s_add_i32 s68, s47, 0x14000
	global_load_lds_dwordx4 v[192:193], off
	v_lshl_add_u64 v[212:213], s[30:31], 0, v[0:1]
	s_mov_b32 m0, s68
	v_lshl_add_u64 v[214:215], s[30:31], 0, v[198:199]
	global_load_lds_dwordx4 v[212:213], off
	s_add_i32 m0, s68, 0x2000
	global_load_lds_dwordx4 v[214:215], off
	s_mov_b32 m0, s52
	global_load_lds_dwordx4 v194, s[44:45]
	s_mov_b32 m0, s53
	s_nop 0
	global_load_lds_dwordx4 v196, s[44:45]
	s_waitcnt vmcnt(8) lgkmcnt(0)
	s_barrier
	v_mfma_f32_16x16x32_bf16 v[62:65], v[114:117], v[162:165], v[62:65]
	v_mfma_f32_16x16x32_bf16 v[58:61], v[138:141], v[162:165], v[58:61]
	v_mfma_f32_16x16x32_bf16 v[46:49], v[114:117], v[170:173], v[46:49]
	v_mfma_f32_16x16x32_bf16 v[42:45], v[138:141], v[170:173], v[42:45]
	v_mfma_f32_16x16x32_bf16 v[30:33], v[114:117], v[178:181], v[30:33]
	v_mfma_f32_16x16x32_bf16 v[26:29], v[138:141], v[178:181], v[26:29]
	v_mfma_f32_16x16x32_bf16 v[14:17], v[114:117], v[204:207], v[14:17]
	v_mfma_f32_16x16x32_bf16 v[10:13], v[138:141], v[204:207], v[10:13]
	v_mfma_f32_16x16x32_bf16 v[62:65], v[126:129], v[166:169], v[62:65]
	v_mfma_f32_16x16x32_bf16 v[58:61], v[142:145], v[166:169], v[58:61]
	v_mfma_f32_16x16x32_bf16 v[46:49], v[126:129], v[174:177], v[46:49]
	v_mfma_f32_16x16x32_bf16 v[42:45], v[142:145], v[174:177], v[42:45]
	v_mfma_f32_16x16x32_bf16 v[30:33], v[126:129], v[182:185], v[30:33]
	v_mfma_f32_16x16x32_bf16 v[26:29], v[142:145], v[182:185], v[26:29]
	v_mfma_f32_16x16x32_bf16 v[14:17], v[126:129], v[208:211], v[14:17]
	v_mfma_f32_16x16x32_bf16 v[10:13], v[142:145], v[208:211], v[10:13]
	v_mfma_f32_16x16x32_bf16 v[54:57], v[146:149], v[162:165], v[54:57]
	v_mfma_f32_16x16x32_bf16 v[50:53], v[154:157], v[162:165], v[50:53]
	v_mfma_f32_16x16x32_bf16 v[38:41], v[146:149], v[170:173], v[38:41]
	v_mfma_f32_16x16x32_bf16 v[34:37], v[154:157], v[170:173], v[34:37]
	v_mfma_f32_16x16x32_bf16 v[22:25], v[146:149], v[178:181], v[22:25]
	v_mfma_f32_16x16x32_bf16 v[18:21], v[154:157], v[178:181], v[18:21]
	v_mfma_f32_16x16x32_bf16 v[6:9], v[146:149], v[204:207], v[6:9]
	v_mfma_f32_16x16x32_bf16 v[2:5], v[154:157], v[204:207], v[2:5]
	v_mfma_f32_16x16x32_bf16 v[54:57], v[150:153], v[166:169], v[54:57]
	v_mfma_f32_16x16x32_bf16 v[50:53], v[158:161], v[166:169], v[50:53]
	v_mfma_f32_16x16x32_bf16 v[38:41], v[150:153], v[174:177], v[38:41]
	v_mfma_f32_16x16x32_bf16 v[34:37], v[158:161], v[174:177], v[34:37]
	v_mfma_f32_16x16x32_bf16 v[22:25], v[150:153], v[182:185], v[22:25]
	v_mfma_f32_16x16x32_bf16 v[18:21], v[158:161], v[182:185], v[18:21]
	v_mfma_f32_16x16x32_bf16 v[6:9], v[150:153], v[208:211], v[6:9]
	v_mfma_f32_16x16x32_bf16 v[2:5], v[158:161], v[208:211], v[2:5]
	s_barrier
; #define PG8_STAGE(bufoff, gbase, voff) do { _Pragma("unroll") for (int _i = 0; _i < 2; ++_i) \
;         __builtin_amdgcn_global_load_lds((const unsigned*)((const char*)(gbase) + (voff)[_i]), (PG8_LAS unsigned*)(lds + (bufoff) + ldsw + _i * 8192), 16, 0, 0); } while (0)
; #define PG8_LDA(dst, b, h) do { _Pragma("unroll") for (int m = 0; m < 4; ++m) _Pragma("unroll") for (int k = 0; k < 2; ++k) dst[m][k] = *(const PG8_LAS bf16x8*)(lds + PG8_SA(b, h) + aoff + m * 2048 + k * 1024); } while (0)
; #define PG8_LDB(dst, b, h) do { _Pragma("unroll") for (int n = 0; n < 2; ++n) _Pragma("unroll") for (int k = 0; k < 2; ++k) dst[n][k] = *(const PG8_LAS bf16x8*)(lds + PG8_SB(b, h) + boff + n * 2048 + k * 1024); } while (0)
; #define PG8_MMA(ai, bj, At, Bt) do { __builtin_amdgcn_s_setprio(1); _Pragma("unroll") for (int m = 0; m < 4; ++m) _Pragma("unroll") for (int n = 0; n < 2; ++n) _Pragma("unroll") for (int k = 0; k < 2; ++k) \
;         acc[ai][bj][m][n] = __builtin_amdgcn_mfma_f32_16x16x32_bf16(Bt[n][k], At[m][k], acc[ai][bj][m][n], 0, 0, 0); __builtin_amdgcn_s_setprio(0); } while (0)
; #define PG8_WAIT_V(n) asm volatile("s_waitcnt vmcnt(" #n ")" ::: "memory")
; #define PG8_WAIT_L(n) asm volatile("s_waitcnt lgkmcnt(" #n ")" ::: "memory")
; #define PG8_BAR __builtin_amdgcn_s_barrier()
; template <class Epi, class Sched, bool ALIGN_EPI = false, bool SP2 = false>
; __device__ __forceinline__ void gemm_phase(PG8_LAS unsigned char* lds, const Gemm g, const Sched& S, const Epi& E, const int wv) {
;     ...
;         for (int t = 0; t < nt; t += 2) {
;             const bool last = (t == nt - 2);
;             const char* a1 = cA + (size_t)(t + 1) * kstep;
;             const char* a2 = last ? nA : cA + (size_t)(t + 2) * kstep; const char* b2 = last ? nB : cB + (size_t)(t + 2) * kstep;
;             const char* a3 = a2 + kstep; const char* b3 = b2 + kstep;
;     ...
;             PG8_LDB(B0, 1, 0); PG8_LDB(B1, 1, 1); PG8_SCHED; PG8_LDA(At, 1, 0); PG8_STAGE(PG8_SA(0, 1), a2 + hstepA, voffA);
;             PG8_WAIT_V(8); PG8_WAIT_L(0); PG8_BAR; PG8_MMA(0, 0, At, B0); PG8_MMA(0, 1, At, B1); PG8_BAR; PG8_SCHED;
;             PG8_LDA(At, 1, 1); PG8_STAGE(PG8_SB(1, 0), b3, voffB); PG8_STAGE(PG8_SB(1, 1), b3 + hstepB, voffB); PG8_STAGE(PG8_SA(1, 0), a3, voffA);
;             PG8_WAIT_V(8); PG8_WAIT_L(0); PG8_BAR; PG8_MMA(1, 0, At, B0); PG8_MMA(1, 1, At, B1); PG8_BAR; PG8_SCHED;
	ds_read_b128 v[114:117], v203
	ds_read_b128 v[126:129], v203 offset:1024
	ds_read_b128 v[138:141], v203 offset:2048
	ds_read_b128 v[142:145], v203 offset:3072
	ds_read_b128 v[146:149], v216
	ds_read_b128 v[150:153], v216 offset:1024
	ds_read_b128 v[154:157], v216 offset:2048
	ds_read_b128 v[158:161], v216 offset:3072
	s_add_u32 s30, s44, 0x180000
	s_addc_u32 s31, s45, 0
	s_mov_b32 m0, s54
	ds_read_b128 v[162:165], v235 offset:32768
	ds_read_b128 v[166:169], v235 offset:33792
	ds_read_b128 v[170:173], v235 offset:34816
	ds_read_b128 v[174:177], v235 offset:35840
	ds_read_b128 v[178:181], v235 offset:36864
	ds_read_b128 v[182:185], v235 offset:37888
	ds_read_b128 v[204:207], v235 offset:38912
	ds_read_b128 v[208:211], v235 offset:39936
	global_load_lds_dwordx4 v194, s[30:31]
	s_mov_b32 m0, s55
	s_nop 0
	global_load_lds_dwordx4 v196, s[30:31]
	s_waitcnt vmcnt(8) lgkmcnt(0)
	s_barrier
	v_mfma_f32_16x16x32_bf16 v[134:137], v[114:117], v[162:165], v[134:137]
	v_mfma_f32_16x16x32_bf16 v[130:133], v[138:141], v[162:165], v[130:133]
	v_mfma_f32_16x16x32_bf16 v[110:113], v[114:117], v[170:173], v[110:113]
	v_mfma_f32_16x16x32_bf16 v[106:109], v[138:141], v[170:173], v[106:109]
	v_mfma_f32_16x16x32_bf16 v[94:97], v[114:117], v[178:181], v[94:97]
	v_mfma_f32_16x16x32_bf16 v[90:93], v[138:141], v[178:181], v[90:93]
	v_mfma_f32_16x16x32_bf16 v[78:81], v[114:117], v[204:207], v[78:81]
	v_mfma_f32_16x16x32_bf16 v[74:77], v[138:141], v[204:207], v[74:77]
	v_mfma_f32_16x16x32_bf16 v[134:137], v[126:129], v[166:169], v[134:137]
	v_mfma_f32_16x16x32_bf16 v[130:133], v[142:145], v[166:169], v[130:133]
	v_mfma_f32_16x16x32_bf16 v[110:113], v[126:129], v[174:177], v[110:113]
	v_mfma_f32_16x16x32_bf16 v[106:109], v[142:145], v[174:177], v[106:109]
	v_mfma_f32_16x16x32_bf16 v[94:97], v[126:129], v[182:185], v[94:97]
	v_mfma_f32_16x16x32_bf16 v[90:93], v[142:145], v[182:185], v[90:93]
	v_mfma_f32_16x16x32_bf16 v[78:81], v[126:129], v[208:211], v[78:81]
	v_mfma_f32_16x16x32_bf16 v[74:77], v[142:145], v[208:211], v[74:77]
	v_mfma_f32_16x16x32_bf16 v[122:125], v[146:149], v[162:165], v[122:125]
	v_mfma_f32_16x16x32_bf16 v[118:121], v[154:157], v[162:165], v[118:121]
	v_mfma_f32_16x16x32_bf16 v[102:105], v[146:149], v[170:173], v[102:105]
	v_mfma_f32_16x16x32_bf16 v[98:101], v[154:157], v[170:173], v[98:101]
	v_mfma_f32_16x16x32_bf16 v[86:89], v[146:149], v[178:181], v[86:89]
	v_mfma_f32_16x16x32_bf16 v[82:85], v[154:157], v[178:181], v[82:85]
	v_mfma_f32_16x16x32_bf16 v[70:73], v[146:149], v[204:207], v[70:73]
	v_mfma_f32_16x16x32_bf16 v[66:69], v[154:157], v[204:207], v[66:69]
	v_mfma_f32_16x16x32_bf16 v[122:125], v[150:153], v[166:169], v[122:125]
	v_mfma_f32_16x16x32_bf16 v[118:121], v[158:161], v[166:169], v[118:121]
	v_mfma_f32_16x16x32_bf16 v[102:105], v[150:153], v[174:177], v[102:105]
	v_mfma_f32_16x16x32_bf16 v[98:101], v[158:161], v[174:177], v[98:101]
	v_mfma_f32_16x16x32_bf16 v[86:89], v[150:153], v[182:185], v[86:89]
	v_mfma_f32_16x16x32_bf16 v[82:85], v[158:161], v[182:185], v[82:85]
	v_mfma_f32_16x16x32_bf16 v[70:73], v[150:153], v[208:211], v[70:73]
	v_mfma_f32_16x16x32_bf16 v[66:69], v[158:161], v[208:211], v[66:69]
	s_barrier
	s_add_i32 s30, s47, 0x18000
	s_add_i32 m0, s30, 0xffffff80
	ds_read_b128 v[162:165], v235 offset:49152
	ds_read_b128 v[166:169], v235 offset:50176
	ds_read_b128 v[170:173], v235 offset:51200
	ds_read_b128 v[174:177], v235 offset:52224
	ds_read_b128 v[178:181], v235 offset:53248
	ds_read_b128 v[182:185], v235 offset:54272
	ds_read_b128 v[204:207], v235 offset:55296
	ds_read_b128 v[208:211], v235 offset:56320
	global_load_lds_dwordx4 v[190:191], off offset:128
	s_add_i32 m0, s30, 0x1f80
	s_add_i32 s30, s47, 0x1c000
	global_load_lds_dwordx4 v[192:193], off offset:128
	s_add_i32 m0, s30, 0xffffff80
	s_nop 0
	global_load_lds_dwordx4 v[212:213], off offset:128
	s_add_i32 m0, s30, 0x1f80
	s_nop 0
	global_load_lds_dwordx4 v[214:215], off offset:128
	s_add_i32 m0, s57, 0xffffff80
	s_nop 0
	global_load_lds_dwordx4 v194, s[44:45] offset:128
	s_add_i32 m0, s58, 0xffffff80
	s_nop 0
	global_load_lds_dwordx4 v196, s[44:45] offset:128
	s_waitcnt vmcnt(8) lgkmcnt(0)
	s_barrier
	v_mfma_f32_16x16x32_bf16 v[62:65], v[114:117], v[162:165], v[62:65]
	v_mfma_f32_16x16x32_bf16 v[58:61], v[138:141], v[162:165], v[58:61]
	v_mfma_f32_16x16x32_bf16 v[46:49], v[114:117], v[170:173], v[46:49]
	v_mfma_f32_16x16x32_bf16 v[42:45], v[138:141], v[170:173], v[42:45]
	v_mfma_f32_16x16x32_bf16 v[30:33], v[114:117], v[178:181], v[30:33]
	v_mfma_f32_16x16x32_bf16 v[26:29], v[138:141], v[178:181], v[26:29]
	v_mfma_f32_16x16x32_bf16 v[14:17], v[114:117], v[204:207], v[14:17]
	v_mfma_f32_16x16x32_bf16 v[10:13], v[138:141], v[204:207], v[10:13]
	v_mfma_f32_16x16x32_bf16 v[62:65], v[126:129], v[166:169], v[62:65]
	v_mfma_f32_16x16x32_bf16 v[58:61], v[142:145], v[166:169], v[58:61]
	v_mfma_f32_16x16x32_bf16 v[46:49], v[126:129], v[174:177], v[46:49]
	v_mfma_f32_16x16x32_bf16 v[42:45], v[142:145], v[174:177], v[42:45]
	v_mfma_f32_16x16x32_bf16 v[30:33], v[126:129], v[182:185], v[30:33]
	v_mfma_f32_16x16x32_bf16 v[26:29], v[142:145], v[182:185], v[26:29]
	v_mfma_f32_16x16x32_bf16 v[14:17], v[126:129], v[208:211], v[14:17]
	v_mfma_f32_16x16x32_bf16 v[10:13], v[142:145], v[208:211], v[10:13]
	v_mfma_f32_16x16x32_bf16 v[54:57], v[146:149], v[162:165], v[54:57]
	v_mfma_f32_16x16x32_bf16 v[50:53], v[154:157], v[162:165], v[50:53]
	v_mfma_f32_16x16x32_bf16 v[38:41], v[146:149], v[170:173], v[38:41]
	v_mfma_f32_16x16x32_bf16 v[34:37], v[154:157], v[170:173], v[34:37]
	v_mfma_f32_16x16x32_bf16 v[22:25], v[146:149], v[178:181], v[22:25]
	v_mfma_f32_16x16x32_bf16 v[18:21], v[154:157], v[178:181], v[18:21]
	v_mfma_f32_16x16x32_bf16 v[6:9], v[146:149], v[204:207], v[6:9]
	v_mfma_f32_16x16x32_bf16 v[2:5], v[154:157], v[204:207], v[2:5]
	v_mfma_f32_16x16x32_bf16 v[54:57], v[150:153], v[166:169], v[54:57]
	v_mfma_f32_16x16x32_bf16 v[50:53], v[158:161], v[166:169], v[50:53]
	v_mfma_f32_16x16x32_bf16 v[38:41], v[150:153], v[174:177], v[38:41]
	v_mfma_f32_16x16x32_bf16 v[34:37], v[158:161], v[174:177], v[34:37]
	v_mfma_f32_16x16x32_bf16 v[22:25], v[150:153], v[182:185], v[22:25]
	v_mfma_f32_16x16x32_bf16 v[18:21], v[158:161], v[182:185], v[18:21]
	v_mfma_f32_16x16x32_bf16 v[6:9], v[150:153], v[208:211], v[6:9]
	v_mfma_f32_16x16x32_bf16 v[2:5], v[158:161], v[208:211], v[2:5]
	s_add_u32 s65, s65, 0x100
	s_addc_u32 s66, s66, 0
	s_cmp_ge_i32 s67, s56
	s_mov_b64 s[30:31], s[34:35]
	s_mov_b32 s44, s67
	s_barrier
	s_cbranch_scc0 .LBB0_990
	s_movk_i32 s68, 0x4000
	s_movk_i32 s69, 0x6000
	s_mov_b32 s70, 0x18000
	s_mov_b32 s71, 0x3f317217
	v_readlane_b32 s67, v255, 30
	s_and_b64 vcc, exec, s[28:29]
	s_cbranch_vccz .LBB0_966

; #define PG8_STAGE(bufoff, gbase, voff) do { _Pragma("unroll") for (int _i = 0; _i < 2; ++_i) \
;         __builtin_amdgcn_global_load_lds((const unsigned*)((const char*)(gbase) + (voff)[_i]), (PG8_LAS unsigned*)(lds + (bufoff) + ldsw + _i * 8192), 16, 0, 0); } while (0)
; #define PG8_LDA(dst, b, h) do { _Pragma("unroll") for (int m = 0; m < 4; ++m) _Pragma("unroll") for (int k = 0; k < 2; ++k) dst[m][k] = *(const PG8_LAS bf16x8*)(lds + PG8_SA(b, h) + aoff + m * 2048 + k * 1024); } while (0)
; #define PG8_LDB(dst, b, h) do { _Pragma("unroll") for (int n = 0; n < 2; ++n) _Pragma("unroll") for (int k = 0; k < 2; ++k) dst[n][k] = *(const PG8_LAS bf16x8*)(lds + PG8_SB(b, h) + boff + n * 2048 + k * 1024); } while (0)
; #define PG8_MMA(ai, bj, At, Bt) do { __builtin_amdgcn_s_setprio(1); _Pragma("unroll") for (int m = 0; m < 4; ++m) _Pragma("unroll") for (int n = 0; n < 2; ++n) _Pragma("unroll") for (int k = 0; k < 2; ++k) \
;         acc[ai][bj][m][n] = __builtin_amdgcn_mfma_f32_16x16x32_bf16(Bt[n][k], At[m][k], acc[ai][bj][m][n], 0, 0, 0); __builtin_amdgcn_s_setprio(0); } while (0)
; #define PG8_WAIT_V(n) asm volatile("s_waitcnt vmcnt(" #n ")" ::: "memory")
; #define PG8_WAIT_L(n) asm volatile("s_waitcnt lgkmcnt(" #n ")" ::: "memory")
; template <class Epi, class Sched, bool ALIGN_EPI = false, bool SP2 = false>
; __device__ __forceinline__ void gemm_phase(PG8_LAS unsigned char* lds, const Gemm g, const Sched& S, const Epi& E, const int wv) {
;     ...
;             const bool last = (t == nt - 2);
;             const char* a1 = cA + (size_t)(t + 1) * kstep;
;             const char* a2 = last ? nA : cA + (size_t)(t + 2) * kstep; const char* b2 = last ? nB : cB + (size_t)(t + 2) * kstep;
;             const char* a3 = a2 + kstep; const char* b3 = b2 + kstep;
;             if (last && has_next) S.a_ready(nxt);
;             if constexpr (SP2) {
;             PG8_LDB(B0, 0, 0); PG8_LDB(B1, 0, 1); PG8_SCHED; PG8_LDA(At, 0, 0); PG8_STAGE(PG8_SA(1, 1), a1 + hstepA, voffA);
;             PG8_WAIT_V(8); PG8_WAIT_L(0); PG8_BAR; PG8_MMA(0, 0, At, B0); PG8_MMA(0, 1, At, B1); PG8_BAR; PG8_SCHED;
;             PG8_LDA(At, 0, 1); PG8_STAGE(PG8_SB(0, 0), b2, voffB); PG8_STAGE(PG8_SB(0, 1), b2 + hstepB, voffB); PG8_STAGE(PG8_SA(0, 0), a2, voffA);
;             PG8_WAIT_V(8); PG8_WAIT_L(0); PG8_BAR; PG8_MMA(1, 0, At, B0); PG8_MMA(1, 1, At, B1); PG8_BAR; PG8_SCHED;
.LBB0_1074:
	s_add_i32 s63, s30, 2
	s_add_u32 s64, s28, 0xfff80080
	s_addc_u32 s31, s29, -1
	s_cmp_eq_u32 s57, s30
	s_cselect_b32 s31, s17, s31
	s_cselect_b32 s30, s40, s64
	s_cselect_b32 s65, s19, s62
	s_cselect_b32 s64, s18, s41
	ds_read_b128 v[164:167], v147
	ds_read_b128 v[168:171], v147 offset:1024
	ds_read_b128 v[172:175], v147 offset:2048
	ds_read_b128 v[176:179], v147 offset:3072
	ds_read_b128 v[180:183], v149
	ds_read_b128 v[194:197], v149 offset:1024
	ds_read_b128 v[198:201], v149 offset:2048
	ds_read_b128 v[202:205], v149 offset:3072
	s_add_i32 m0, s47, 0xc000
	ds_read_b128 v[206:209], v163
	ds_read_b128 v[210:213], v163 offset:1024
	ds_read_b128 v[214:217], v163 offset:2048
	ds_read_b128 v[228:231], v163 offset:3072
	ds_read_b128 v[232:235], v163 offset:4096
	ds_read_b128 v[236:239], v163 offset:5120
	ds_read_b128 v[240:243], v163 offset:6144
	ds_read_b128 v[244:247], v163 offset:7168
	global_load_lds_dwordx4 v146, s[28:29]
	s_add_i32 m0, s47, 0xe000
	s_nop 0
	global_load_lds_dwordx4 v148, s[28:29]
	s_waitcnt vmcnt(8) lgkmcnt(0)
	s_barrier
	v_mfma_f32_16x16x32_bf16 v[130:133], v[164:167], v[206:209], v[130:133]
	v_mfma_f32_16x16x32_bf16 v[126:129], v[172:175], v[206:209], v[126:129]
	v_mfma_f32_16x16x32_bf16 v[114:117], v[164:167], v[214:217], v[114:117]
	v_mfma_f32_16x16x32_bf16 v[110:113], v[172:175], v[214:217], v[110:113]
	v_mfma_f32_16x16x32_bf16 v[98:101], v[164:167], v[232:235], v[98:101]
	v_mfma_f32_16x16x32_bf16 v[94:97], v[172:175], v[232:235], v[94:97]
	v_mfma_f32_16x16x32_bf16 v[82:85], v[164:167], v[240:243], v[82:85]
	v_mfma_f32_16x16x32_bf16 v[78:81], v[172:175], v[240:243], v[78:81]
	v_mfma_f32_16x16x32_bf16 v[130:133], v[168:171], v[210:213], v[130:133]
	v_mfma_f32_16x16x32_bf16 v[126:129], v[176:179], v[210:213], v[126:129]
	v_mfma_f32_16x16x32_bf16 v[114:117], v[168:171], v[228:231], v[114:117]
	v_mfma_f32_16x16x32_bf16 v[110:113], v[176:179], v[228:231], v[110:113]
	v_mfma_f32_16x16x32_bf16 v[98:101], v[168:171], v[236:239], v[98:101]
	v_mfma_f32_16x16x32_bf16 v[94:97], v[176:179], v[236:239], v[94:97]
	v_mfma_f32_16x16x32_bf16 v[82:85], v[168:171], v[244:247], v[82:85]
	v_mfma_f32_16x16x32_bf16 v[78:81], v[176:179], v[244:247], v[78:81]
	v_mfma_f32_16x16x32_bf16 v[122:125], v[180:183], v[206:209], v[122:125]
	v_mfma_f32_16x16x32_bf16 v[118:121], v[198:201], v[206:209], v[118:121]
	v_mfma_f32_16x16x32_bf16 v[106:109], v[180:183], v[214:217], v[106:109]
	v_mfma_f32_16x16x32_bf16 v[102:105], v[198:201], v[214:217], v[102:105]
	v_mfma_f32_16x16x32_bf16 v[90:93], v[180:183], v[232:235], v[90:93]
	v_mfma_f32_16x16x32_bf16 v[86:89], v[198:201], v[232:235], v[86:89]
	v_mfma_f32_16x16x32_bf16 v[74:77], v[180:183], v[240:243], v[74:77]
	v_mfma_f32_16x16x32_bf16 v[70:73], v[198:201], v[240:243], v[70:73]
	v_mfma_f32_16x16x32_bf16 v[122:125], v[194:197], v[210:213], v[122:125]
	v_mfma_f32_16x16x32_bf16 v[118:121], v[202:205], v[210:213], v[118:121]
	v_mfma_f32_16x16x32_bf16 v[106:109], v[194:197], v[228:231], v[106:109]
	v_mfma_f32_16x16x32_bf16 v[102:105], v[202:205], v[228:231], v[102:105]
	v_mfma_f32_16x16x32_bf16 v[90:93], v[194:197], v[236:239], v[90:93]
	v_mfma_f32_16x16x32_bf16 v[86:89], v[202:205], v[236:239], v[86:89]
	v_mfma_f32_16x16x32_bf16 v[74:77], v[194:197], v[244:247], v[74:77]
	v_mfma_f32_16x16x32_bf16 v[70:73], v[202:205], v[244:247], v[70:73]
	s_barrier
	s_add_i32 s66, s45, 0x10000
	v_lshl_add_u64 v[150:151], s[64:65], 0, v[138:139]
	s_mov_b32 m0, s66
	ds_read_b128 v[206:209], v163 offset:16384
	ds_read_b128 v[210:213], v163 offset:17408
	ds_read_b128 v[214:217], v163 offset:18432
	ds_read_b128 v[228:231], v163 offset:19456
	ds_read_b128 v[232:235], v163 offset:20480
	ds_read_b128 v[236:239], v163 offset:21504
	ds_read_b128 v[240:243], v163 offset:22528
	ds_read_b128 v[244:247], v163 offset:23552
	global_load_lds_dwordx4 v[150:151], off
	s_add_i32 m0, s66, 0x2000
	v_lshl_add_u64 v[184:185], s[64:65], 0, v[134:135]
	s_add_u32 s64, s64, s0
	s_addc_u32 s65, s65, s1
	s_add_i32 s66, s45, 0x14000
	global_load_lds_dwordx4 v[184:185], off
	s_mov_b32 m0, s66
	global_load_lds_dwordx4 v138, s[64:65]
	s_add_i32 m0, s66, 0x2000
	global_load_lds_dwordx4 v134, s[64:65]
	s_mov_b32 m0, s47
	global_load_lds_dwordx4 v140, s[30:31]
	s_mov_b32 m0, s48
	s_nop 0
	global_load_lds_dwordx4 v136, s[30:31]
	s_waitcnt vmcnt(8) lgkmcnt(0)
	s_barrier
	v_mfma_f32_16x16x32_bf16 v[66:69], v[164:167], v[206:209], v[66:69]
	v_mfma_f32_16x16x32_bf16 v[62:65], v[172:175], v[206:209], v[62:65]
	v_mfma_f32_16x16x32_bf16 v[50:53], v[164:167], v[214:217], v[50:53]
	v_mfma_f32_16x16x32_bf16 v[46:49], v[172:175], v[214:217], v[46:49]
	v_mfma_f32_16x16x32_bf16 v[34:37], v[164:167], v[232:235], v[34:37]
	v_mfma_f32_16x16x32_bf16 v[30:33], v[172:175], v[232:235], v[30:33]
	v_mfma_f32_16x16x32_bf16 v[18:21], v[164:167], v[240:243], v[18:21]
	v_mfma_f32_16x16x32_bf16 v[14:17], v[172:175], v[240:243], v[14:17]
	v_mfma_f32_16x16x32_bf16 v[66:69], v[168:171], v[210:213], v[66:69]
	v_mfma_f32_16x16x32_bf16 v[62:65], v[176:179], v[210:213], v[62:65]
	v_mfma_f32_16x16x32_bf16 v[50:53], v[168:171], v[228:231], v[50:53]
	v_mfma_f32_16x16x32_bf16 v[46:49], v[176:179], v[228:231], v[46:49]
	v_mfma_f32_16x16x32_bf16 v[34:37], v[168:171], v[236:239], v[34:37]
	v_mfma_f32_16x16x32_bf16 v[30:33], v[176:179], v[236:239], v[30:33]
	v_mfma_f32_16x16x32_bf16 v[18:21], v[168:171], v[244:247], v[18:21]
	v_mfma_f32_16x16x32_bf16 v[14:17], v[176:179], v[244:247], v[14:17]
	v_mfma_f32_16x16x32_bf16 v[58:61], v[180:183], v[206:209], v[58:61]
	v_mfma_f32_16x16x32_bf16 v[54:57], v[198:201], v[206:209], v[54:57]
	v_mfma_f32_16x16x32_bf16 v[42:45], v[180:183], v[214:217], v[42:45]
	v_mfma_f32_16x16x32_bf16 v[38:41], v[198:201], v[214:217], v[38:41]
	v_mfma_f32_16x16x32_bf16 v[26:29], v[180:183], v[232:235], v[26:29]
	v_mfma_f32_16x16x32_bf16 v[22:25], v[198:201], v[232:235], v[22:25]
	v_mfma_f32_16x16x32_bf16 v[10:13], v[180:183], v[240:243], v[10:13]
	v_mfma_f32_16x16x32_bf16 v[6:9], v[198:201], v[240:243], v[6:9]
	v_mfma_f32_16x16x32_bf16 v[58:61], v[194:197], v[210:213], v[58:61]
	v_mfma_f32_16x16x32_bf16 v[54:57], v[202:205], v[210:213], v[54:57]
	v_mfma_f32_16x16x32_bf16 v[42:45], v[194:197], v[228:231], v[42:45]
	v_mfma_f32_16x16x32_bf16 v[38:41], v[202:205], v[228:231], v[38:41]
	v_mfma_f32_16x16x32_bf16 v[26:29], v[194:197], v[236:239], v[26:29]
	v_mfma_f32_16x16x32_bf16 v[22:25], v[202:205], v[236:239], v[22:25]
	v_mfma_f32_16x16x32_bf16 v[10:13], v[194:197], v[244:247], v[10:13]
	v_mfma_f32_16x16x32_bf16 v[6:9], v[202:205], v[244:247], v[6:9]
	s_barrier
; #define PG8_STAGE(bufoff, gbase, voff) do { _Pragma("unroll") for (int _i = 0; _i < 2; ++_i) \
;         __builtin_amdgcn_global_load_lds((const unsigned*)((const char*)(gbase) + (voff)[_i]), (PG8_LAS unsigned*)(lds + (bufoff) + ldsw + _i * 8192), 16, 0, 0); } while (0)
; #define PG8_LDA(dst, b, h) do { _Pragma("unroll") for (int m = 0; m < 4; ++m) _Pragma("unroll") for (int k = 0; k < 2; ++k) dst[m][k] = *(const PG8_LAS bf16x8*)(lds + PG8_SA(b, h) + aoff + m * 2048 + k * 1024); } while (0)
; #define PG8_LDB(dst, b, h) do { _Pragma("unroll") for (int n = 0; n < 2; ++n) _Pragma("unroll") for (int k = 0; k < 2; ++k) dst[n][k] = *(const PG8_LAS bf16x8*)(lds + PG8_SB(b, h) + boff + n * 2048 + k * 1024); } while (0)
; #define PG8_MMA(ai, bj, At, Bt) do { __builtin_amdgcn_s_setprio(1); _Pragma("unroll") for (int m = 0; m < 4; ++m) _Pragma("unroll") for (int n = 0; n < 2; ++n) _Pragma("unroll") for (int k = 0; k < 2; ++k) \
;         acc[ai][bj][m][n] = __builtin_amdgcn_mfma_f32_16x16x32_bf16(Bt[n][k], At[m][k], acc[ai][bj][m][n], 0, 0, 0); __builtin_amdgcn_s_setprio(0); } while (0)
; #define PG8_WAIT_V(n) asm volatile("s_waitcnt vmcnt(" #n ")" ::: "memory")
; #define PG8_WAIT_L(n) asm volatile("s_waitcnt lgkmcnt(" #n ")" ::: "memory")
; #define PG8_BAR __builtin_amdgcn_s_barrier()
; template <class Epi, class Sched, bool ALIGN_EPI = false, bool SP2 = false>
; __device__ __forceinline__ void gemm_phase(PG8_LAS unsigned char* lds, const Gemm g, const Sched& S, const Epi& E, const int wv) {
;     ...
;         for (int t = 0; t < nt; t += 2) {
;             const bool last = (t == nt - 2);
;             const char* a1 = cA + (size_t)(t + 1) * kstep;
;             const char* a2 = last ? nA : cA + (size_t)(t + 2) * kstep; const char* b2 = last ? nB : cB + (size_t)(t + 2) * kstep;
;             const char* a3 = a2 + kstep; const char* b3 = b2 + kstep;
;     ...
;             PG8_LDB(B0, 1, 0); PG8_LDB(B1, 1, 1); PG8_SCHED; PG8_LDA(At, 1, 0); PG8_STAGE(PG8_SA(0, 1), a2 + hstepA, voffA);
;             PG8_WAIT_V(8); PG8_WAIT_L(0); PG8_BAR; PG8_MMA(0, 0, At, B0); PG8_MMA(0, 1, At, B1); PG8_BAR; PG8_SCHED;
;             PG8_LDA(At, 1, 1); PG8_STAGE(PG8_SB(1, 0), b3, voffB); PG8_STAGE(PG8_SB(1, 1), b3 + hstepB, voffB); PG8_STAGE(PG8_SA(1, 0), a3, voffA);
;             PG8_WAIT_V(8); PG8_WAIT_L(0); PG8_BAR; PG8_MMA(1, 0, At, B0); PG8_MMA(1, 1, At, B1); PG8_BAR; PG8_SCHED;
	ds_read_b128 v[164:167], v152
	ds_read_b128 v[168:171], v152 offset:1024
	ds_read_b128 v[172:175], v152 offset:2048
	ds_read_b128 v[176:179], v152 offset:3072
	ds_read_b128 v[180:183], v154
	ds_read_b128 v[194:197], v154 offset:1024
	ds_read_b128 v[198:201], v154 offset:2048
	ds_read_b128 v[202:205], v154 offset:3072
	s_mov_b32 m0, s49
	ds_read_b128 v[206:209], v163 offset:32768
	ds_read_b128 v[210:213], v163 offset:33792
	ds_read_b128 v[214:217], v163 offset:34816
	ds_read_b128 v[228:231], v163 offset:35840
	ds_read_b128 v[232:235], v163 offset:36864
	ds_read_b128 v[236:239], v163 offset:37888
	ds_read_b128 v[240:243], v163 offset:38912
	ds_read_b128 v[244:247], v163 offset:39936
	global_load_lds_dwordx4 v0, s[30:31]
	s_mov_b32 m0, s50
	s_nop 0
	global_load_lds_dwordx4 v156, s[30:31]
	s_waitcnt vmcnt(8) lgkmcnt(0)
	s_barrier
	v_mfma_f32_16x16x32_bf16 v[130:133], v[164:167], v[206:209], v[130:133]
	v_mfma_f32_16x16x32_bf16 v[126:129], v[172:175], v[206:209], v[126:129]
	v_mfma_f32_16x16x32_bf16 v[114:117], v[164:167], v[214:217], v[114:117]
	v_mfma_f32_16x16x32_bf16 v[110:113], v[172:175], v[214:217], v[110:113]
	v_mfma_f32_16x16x32_bf16 v[98:101], v[164:167], v[232:235], v[98:101]
	v_mfma_f32_16x16x32_bf16 v[94:97], v[172:175], v[232:235], v[94:97]
	v_mfma_f32_16x16x32_bf16 v[82:85], v[164:167], v[240:243], v[82:85]
	v_mfma_f32_16x16x32_bf16 v[78:81], v[172:175], v[240:243], v[78:81]
	v_mfma_f32_16x16x32_bf16 v[130:133], v[168:171], v[210:213], v[130:133]
	v_mfma_f32_16x16x32_bf16 v[126:129], v[176:179], v[210:213], v[126:129]
	v_mfma_f32_16x16x32_bf16 v[114:117], v[168:171], v[228:231], v[114:117]
	v_mfma_f32_16x16x32_bf16 v[110:113], v[176:179], v[228:231], v[110:113]
	v_mfma_f32_16x16x32_bf16 v[98:101], v[168:171], v[236:239], v[98:101]
	v_mfma_f32_16x16x32_bf16 v[94:97], v[176:179], v[236:239], v[94:97]
	v_mfma_f32_16x16x32_bf16 v[82:85], v[168:171], v[244:247], v[82:85]
	v_mfma_f32_16x16x32_bf16 v[78:81], v[176:179], v[244:247], v[78:81]
	v_mfma_f32_16x16x32_bf16 v[122:125], v[180:183], v[206:209], v[122:125]
	v_mfma_f32_16x16x32_bf16 v[118:121], v[198:201], v[206:209], v[118:121]
	v_mfma_f32_16x16x32_bf16 v[106:109], v[180:183], v[214:217], v[106:109]
	v_mfma_f32_16x16x32_bf16 v[102:105], v[198:201], v[214:217], v[102:105]
	v_mfma_f32_16x16x32_bf16 v[90:93], v[180:183], v[232:235], v[90:93]
	v_mfma_f32_16x16x32_bf16 v[86:89], v[198:201], v[232:235], v[86:89]
	v_mfma_f32_16x16x32_bf16 v[74:77], v[180:183], v[240:243], v[74:77]
	v_mfma_f32_16x16x32_bf16 v[70:73], v[198:201], v[240:243], v[70:73]
	v_mfma_f32_16x16x32_bf16 v[122:125], v[194:197], v[210:213], v[122:125]
	v_mfma_f32_16x16x32_bf16 v[118:121], v[202:205], v[210:213], v[118:121]
	v_mfma_f32_16x16x32_bf16 v[106:109], v[194:197], v[228:231], v[106:109]
	v_mfma_f32_16x16x32_bf16 v[102:105], v[202:205], v[228:231], v[102:105]
	v_mfma_f32_16x16x32_bf16 v[90:93], v[194:197], v[236:239], v[90:93]
	v_mfma_f32_16x16x32_bf16 v[86:89], v[202:205], v[236:239], v[86:89]
	v_mfma_f32_16x16x32_bf16 v[74:77], v[194:197], v[244:247], v[74:77]
	v_mfma_f32_16x16x32_bf16 v[70:73], v[202:205], v[244:247], v[70:73]
	s_barrier
	s_add_i32 m0, s45, 0x17f80
	ds_read_b128 v[206:209], v163 offset:49152
	ds_read_b128 v[210:213], v163 offset:50176
	ds_read_b128 v[214:217], v163 offset:51200
	ds_read_b128 v[228:231], v163 offset:52224
	ds_read_b128 v[232:235], v163 offset:53248
	ds_read_b128 v[236:239], v163 offset:54272
	ds_read_b128 v[240:243], v163 offset:55296
	ds_read_b128 v[244:247], v163 offset:56320
	global_load_lds_dwordx4 v[150:151], off offset:128
	s_add_i32 m0, s45, 0x19f80
	global_load_lds_dwordx4 v[184:185], off offset:128
	s_add_i32 m0, s45, 0x1bf80
	s_nop 0
	global_load_lds_dwordx4 v138, s[64:65] offset:128
	s_add_i32 m0, s45, 0x1df80
	s_nop 0
	global_load_lds_dwordx4 v134, s[64:65] offset:128
	s_add_i32 m0, s53, 0xffffff80
	s_nop 0
	global_load_lds_dwordx4 v140, s[30:31] offset:128
	s_add_i32 m0, s54, 0xffffff80
	s_nop 0
	global_load_lds_dwordx4 v136, s[30:31] offset:128
	s_waitcnt vmcnt(8) lgkmcnt(0)
	s_barrier
	v_mfma_f32_16x16x32_bf16 v[66:69], v[164:167], v[206:209], v[66:69]
	v_mfma_f32_16x16x32_bf16 v[62:65], v[172:175], v[206:209], v[62:65]
	v_mfma_f32_16x16x32_bf16 v[50:53], v[164:167], v[214:217], v[50:53]
	v_mfma_f32_16x16x32_bf16 v[46:49], v[172:175], v[214:217], v[46:49]
	v_mfma_f32_16x16x32_bf16 v[34:37], v[164:167], v[232:235], v[34:37]
	v_mfma_f32_16x16x32_bf16 v[30:33], v[172:175], v[232:235], v[30:33]
	v_mfma_f32_16x16x32_bf16 v[18:21], v[164:167], v[240:243], v[18:21]
	v_mfma_f32_16x16x32_bf16 v[14:17], v[172:175], v[240:243], v[14:17]
	v_mfma_f32_16x16x32_bf16 v[66:69], v[168:171], v[210:213], v[66:69]
	v_mfma_f32_16x16x32_bf16 v[62:65], v[176:179], v[210:213], v[62:65]
	v_mfma_f32_16x16x32_bf16 v[50:53], v[168:171], v[228:231], v[50:53]
	v_mfma_f32_16x16x32_bf16 v[46:49], v[176:179], v[228:231], v[46:49]
	v_mfma_f32_16x16x32_bf16 v[34:37], v[168:171], v[236:239], v[34:37]
	v_mfma_f32_16x16x32_bf16 v[30:33], v[176:179], v[236:239], v[30:33]
	v_mfma_f32_16x16x32_bf16 v[18:21], v[168:171], v[244:247], v[18:21]
	v_mfma_f32_16x16x32_bf16 v[14:17], v[176:179], v[244:247], v[14:17]
	v_mfma_f32_16x16x32_bf16 v[58:61], v[180:183], v[206:209], v[58:61]
	v_mfma_f32_16x16x32_bf16 v[54:57], v[198:201], v[206:209], v[54:57]
	v_mfma_f32_16x16x32_bf16 v[42:45], v[180:183], v[214:217], v[42:45]
	v_mfma_f32_16x16x32_bf16 v[38:41], v[198:201], v[214:217], v[38:41]
	v_mfma_f32_16x16x32_bf16 v[26:29], v[180:183], v[232:235], v[26:29]
	v_mfma_f32_16x16x32_bf16 v[22:25], v[198:201], v[232:235], v[22:25]
	v_mfma_f32_16x16x32_bf16 v[10:13], v[180:183], v[240:243], v[10:13]
	v_mfma_f32_16x16x32_bf16 v[6:9], v[198:201], v[240:243], v[6:9]
	v_mfma_f32_16x16x32_bf16 v[58:61], v[194:197], v[210:213], v[58:61]
	v_mfma_f32_16x16x32_bf16 v[54:57], v[202:205], v[210:213], v[54:57]
	v_mfma_f32_16x16x32_bf16 v[42:45], v[194:197], v[228:231], v[42:45]
	v_mfma_f32_16x16x32_bf16 v[38:41], v[202:205], v[228:231], v[38:41]
	v_mfma_f32_16x16x32_bf16 v[26:29], v[194:197], v[236:239], v[26:29]
	v_mfma_f32_16x16x32_bf16 v[22:25], v[202:205], v[236:239], v[22:25]
	v_mfma_f32_16x16x32_bf16 v[10:13], v[194:197], v[244:247], v[10:13]
	v_mfma_f32_16x16x32_bf16 v[6:9], v[202:205], v[244:247], v[6:9]
	s_add_u32 s28, s28, 0x100
	s_addc_u32 s29, s29, 0
	s_add_u32 s41, s41, 0x100
	s_addc_u32 s62, s62, 0
	s_cmp_ge_i32 s63, s55
	s_mov_b32 s30, s63
	s_barrier
	s_cbranch_scc0 .LBB0_1074
	v_readlane_b32 s67, v255, 30

; #define PG8_STAGE(bufoff, gbase, voff) do { _Pragma("unroll") for (int _i = 0; _i < 2; ++_i) \
;         __builtin_amdgcn_global_load_lds((const unsigned*)((const char*)(gbase) + (voff)[_i]), (PG8_LAS unsigned*)(lds + (bufoff) + ldsw + _i * 8192), 16, 0, 0); } while (0)
; #define PG8_LDA(dst, b, h) do { _Pragma("unroll") for (int m = 0; m < 4; ++m) _Pragma("unroll") for (int k = 0; k < 2; ++k) dst[m][k] = *(const PG8_LAS bf16x8*)(lds + PG8_SA(b, h) + aoff + m * 2048 + k * 1024); } while (0)
; #define PG8_LDB(dst, b, h) do { _Pragma("unroll") for (int n = 0; n < 2; ++n) _Pragma("unroll") for (int k = 0; k < 2; ++k) dst[n][k] = *(const PG8_LAS bf16x8*)(lds + PG8_SB(b, h) + boff + n * 2048 + k * 1024); } while (0)
; #define PG8_MMA(ai, bj, At, Bt) do { __builtin_amdgcn_s_setprio(1); _Pragma("unroll") for (int m = 0; m < 4; ++m) _Pragma("unroll") for (int n = 0; n < 2; ++n) _Pragma("unroll") for (int k = 0; k < 2; ++k) \
;         acc[ai][bj][m][n] = __builtin_amdgcn_mfma_f32_16x16x32_bf16(Bt[n][k], At[m][k], acc[ai][bj][m][n], 0, 0, 0); __builtin_amdgcn_s_setprio(0); } while (0)
; #define PG8_WAIT_V(n) asm volatile("s_waitcnt vmcnt(" #n ")" ::: "memory")
; #define PG8_WAIT_L(n) asm volatile("s_waitcnt lgkmcnt(" #n ")" ::: "memory")
; template <class Epi, class Sched, bool ALIGN_EPI = false, bool SP2 = false>
; __device__ __forceinline__ void gemm_phase(PG8_LAS unsigned char* lds, const Gemm g, const Sched& S, const Epi& E, const int wv) {
;     ...
;             const bool last = (t == nt - 2);
;             const char* a1 = cA + (size_t)(t + 1) * kstep;
;             const char* a2 = last ? nA : cA + (size_t)(t + 2) * kstep; const char* b2 = last ? nB : cB + (size_t)(t + 2) * kstep;
;             const char* a3 = a2 + kstep; const char* b3 = b2 + kstep;
;             if (last && has_next) S.a_ready(nxt);
;             if constexpr (SP2) {
;             PG8_LDB(B0, 0, 0); PG8_LDB(B1, 0, 1); PG8_SCHED; PG8_LDA(At, 0, 0); PG8_STAGE(PG8_SA(1, 1), a1 + hstepA, voffA);
;             PG8_WAIT_V(8); PG8_WAIT_L(0); PG8_BAR; PG8_MMA(0, 0, At, B0); PG8_MMA(0, 1, At, B1); PG8_BAR; PG8_SCHED;
;             PG8_LDA(At, 0, 1); PG8_STAGE(PG8_SB(0, 0), b2, voffB); PG8_STAGE(PG8_SB(0, 1), b2 + hstepB, voffB); PG8_STAGE(PG8_SA(0, 0), a2, voffA);
;             PG8_WAIT_V(8); PG8_WAIT_L(0); PG8_BAR; PG8_MMA(1, 0, At, B0); PG8_MMA(1, 1, At, B1); PG8_BAR; PG8_SCHED;
.LBB0_1385:
	s_add_i32 s70, s52, 2
	s_add_u32 s71, s44, 0xfffc0080
	s_addc_u32 s53, s45, -1
	s_cmp_eq_u32 s65, s52
	s_cselect_b32 s53, s13, s53
	s_cselect_b32 s52, s19, s71
	s_cselect_b32 s73, s15, s55
	s_cselect_b32 s72, s14, s54
	ds_read_b128 v[114:117], v201
	ds_read_b128 v[126:129], v201 offset:1024
	ds_read_b128 v[138:141], v201 offset:2048
	ds_read_b128 v[142:145], v201 offset:3072
	ds_read_b128 v[146:149], v203
	ds_read_b128 v[150:153], v203 offset:1024
	ds_read_b128 v[154:157], v203 offset:2048
	ds_read_b128 v[158:161], v203 offset:3072
	s_add_i32 m0, s51, 0xc000
	ds_read_b128 v[162:165], v235
	ds_read_b128 v[166:169], v235 offset:1024
	ds_read_b128 v[170:173], v235 offset:2048
	ds_read_b128 v[174:177], v235 offset:3072
	ds_read_b128 v[178:181], v235 offset:4096
	ds_read_b128 v[182:185], v235 offset:5120
	ds_read_b128 v[204:207], v235 offset:6144
	ds_read_b128 v[208:211], v235 offset:7168
	global_load_lds_dwordx4 v200, s[44:45]
	s_add_i32 m0, s51, 0xe000
	s_nop 0
	global_load_lds_dwordx4 v202, s[44:45]
	s_waitcnt vmcnt(8) lgkmcnt(0)
	s_barrier
	v_mfma_f32_16x16x32_bf16 v[134:137], v[114:117], v[162:165], v[134:137]
	v_mfma_f32_16x16x32_bf16 v[130:133], v[138:141], v[162:165], v[130:133]
	v_mfma_f32_16x16x32_bf16 v[110:113], v[114:117], v[170:173], v[110:113]
	v_mfma_f32_16x16x32_bf16 v[106:109], v[138:141], v[170:173], v[106:109]
	v_mfma_f32_16x16x32_bf16 v[94:97], v[114:117], v[178:181], v[94:97]
	v_mfma_f32_16x16x32_bf16 v[90:93], v[138:141], v[178:181], v[90:93]
	v_mfma_f32_16x16x32_bf16 v[78:81], v[114:117], v[204:207], v[78:81]
	v_mfma_f32_16x16x32_bf16 v[74:77], v[138:141], v[204:207], v[74:77]
	v_mfma_f32_16x16x32_bf16 v[134:137], v[126:129], v[166:169], v[134:137]
	v_mfma_f32_16x16x32_bf16 v[130:133], v[142:145], v[166:169], v[130:133]
	v_mfma_f32_16x16x32_bf16 v[110:113], v[126:129], v[174:177], v[110:113]
	v_mfma_f32_16x16x32_bf16 v[106:109], v[142:145], v[174:177], v[106:109]
	v_mfma_f32_16x16x32_bf16 v[94:97], v[126:129], v[182:185], v[94:97]
	v_mfma_f32_16x16x32_bf16 v[90:93], v[142:145], v[182:185], v[90:93]
	v_mfma_f32_16x16x32_bf16 v[78:81], v[126:129], v[208:211], v[78:81]
	v_mfma_f32_16x16x32_bf16 v[74:77], v[142:145], v[208:211], v[74:77]
	v_mfma_f32_16x16x32_bf16 v[122:125], v[146:149], v[162:165], v[122:125]
	v_mfma_f32_16x16x32_bf16 v[118:121], v[154:157], v[162:165], v[118:121]
	v_mfma_f32_16x16x32_bf16 v[102:105], v[146:149], v[170:173], v[102:105]
	v_mfma_f32_16x16x32_bf16 v[98:101], v[154:157], v[170:173], v[98:101]
	v_mfma_f32_16x16x32_bf16 v[86:89], v[146:149], v[178:181], v[86:89]
	v_mfma_f32_16x16x32_bf16 v[82:85], v[154:157], v[178:181], v[82:85]
	v_mfma_f32_16x16x32_bf16 v[70:73], v[146:149], v[204:207], v[70:73]
	v_mfma_f32_16x16x32_bf16 v[66:69], v[154:157], v[204:207], v[66:69]
	v_mfma_f32_16x16x32_bf16 v[122:125], v[150:153], v[166:169], v[122:125]
	v_mfma_f32_16x16x32_bf16 v[118:121], v[158:161], v[166:169], v[118:121]
	v_mfma_f32_16x16x32_bf16 v[102:105], v[150:153], v[174:177], v[102:105]
	v_mfma_f32_16x16x32_bf16 v[98:101], v[158:161], v[174:177], v[98:101]
	v_mfma_f32_16x16x32_bf16 v[86:89], v[150:153], v[182:185], v[86:89]
	v_mfma_f32_16x16x32_bf16 v[82:85], v[158:161], v[182:185], v[82:85]
	v_mfma_f32_16x16x32_bf16 v[70:73], v[150:153], v[208:211], v[70:73]
	v_mfma_f32_16x16x32_bf16 v[66:69], v[158:161], v[208:211], v[66:69]
	s_barrier
	s_add_i32 s74, s3, 0x10000
	v_lshl_add_u64 v[190:191], s[72:73], 0, v[0:1]
	s_mov_b32 m0, s74
	ds_read_b128 v[162:165], v235 offset:16384
	ds_read_b128 v[166:169], v235 offset:17408
	ds_read_b128 v[170:173], v235 offset:18432
	ds_read_b128 v[174:177], v235 offset:19456
	ds_read_b128 v[178:181], v235 offset:20480
	ds_read_b128 v[182:185], v235 offset:21504
	ds_read_b128 v[204:207], v235 offset:22528
	ds_read_b128 v[208:211], v235 offset:23552
	global_load_lds_dwordx4 v[190:191], off
	s_add_i32 m0, s74, 0x2000
	v_lshl_add_u64 v[192:193], s[72:73], 0, v[198:199]
	s_add_u32 s72, s72, s24
	s_addc_u32 s73, s73, s25
	s_add_i32 s71, s3, 0x14000
	global_load_lds_dwordx4 v[192:193], off
	s_mov_b32 m0, s71
	global_load_lds_dwordx4 v0, s[72:73]
	s_add_i32 m0, s71, 0x2000
	global_load_lds_dwordx4 v198, s[72:73]
	s_mov_b32 m0, s51
	global_load_lds_dwordx4 v194, s[52:53]
	s_mov_b32 m0, s59
	s_nop 0
	global_load_lds_dwordx4 v196, s[52:53]
	s_waitcnt vmcnt(8) lgkmcnt(0)
	s_barrier
	v_mfma_f32_16x16x32_bf16 v[62:65], v[114:117], v[162:165], v[62:65]
	v_mfma_f32_16x16x32_bf16 v[58:61], v[138:141], v[162:165], v[58:61]
	v_mfma_f32_16x16x32_bf16 v[46:49], v[114:117], v[170:173], v[46:49]
	v_mfma_f32_16x16x32_bf16 v[42:45], v[138:141], v[170:173], v[42:45]
	v_mfma_f32_16x16x32_bf16 v[30:33], v[114:117], v[178:181], v[30:33]
	v_mfma_f32_16x16x32_bf16 v[26:29], v[138:141], v[178:181], v[26:29]
	v_mfma_f32_16x16x32_bf16 v[14:17], v[114:117], v[204:207], v[14:17]
	v_mfma_f32_16x16x32_bf16 v[10:13], v[138:141], v[204:207], v[10:13]
	v_mfma_f32_16x16x32_bf16 v[62:65], v[126:129], v[166:169], v[62:65]
	v_mfma_f32_16x16x32_bf16 v[58:61], v[142:145], v[166:169], v[58:61]
	v_mfma_f32_16x16x32_bf16 v[46:49], v[126:129], v[174:177], v[46:49]
	v_mfma_f32_16x16x32_bf16 v[42:45], v[142:145], v[174:177], v[42:45]
	v_mfma_f32_16x16x32_bf16 v[30:33], v[126:129], v[182:185], v[30:33]
	v_mfma_f32_16x16x32_bf16 v[26:29], v[142:145], v[182:185], v[26:29]
	v_mfma_f32_16x16x32_bf16 v[14:17], v[126:129], v[208:211], v[14:17]
	v_mfma_f32_16x16x32_bf16 v[10:13], v[142:145], v[208:211], v[10:13]
	v_mfma_f32_16x16x32_bf16 v[54:57], v[146:149], v[162:165], v[54:57]
	v_mfma_f32_16x16x32_bf16 v[50:53], v[154:157], v[162:165], v[50:53]
	v_mfma_f32_16x16x32_bf16 v[38:41], v[146:149], v[170:173], v[38:41]
	v_mfma_f32_16x16x32_bf16 v[34:37], v[154:157], v[170:173], v[34:37]
	v_mfma_f32_16x16x32_bf16 v[22:25], v[146:149], v[178:181], v[22:25]
	v_mfma_f32_16x16x32_bf16 v[18:21], v[154:157], v[178:181], v[18:21]
	v_mfma_f32_16x16x32_bf16 v[6:9], v[146:149], v[204:207], v[6:9]
	v_mfma_f32_16x16x32_bf16 v[2:5], v[154:157], v[204:207], v[2:5]
	v_mfma_f32_16x16x32_bf16 v[54:57], v[150:153], v[166:169], v[54:57]
	v_mfma_f32_16x16x32_bf16 v[50:53], v[158:161], v[166:169], v[50:53]
	v_mfma_f32_16x16x32_bf16 v[38:41], v[150:153], v[174:177], v[38:41]
	v_mfma_f32_16x16x32_bf16 v[34:37], v[158:161], v[174:177], v[34:37]
	v_mfma_f32_16x16x32_bf16 v[22:25], v[150:153], v[182:185], v[22:25]
	v_mfma_f32_16x16x32_bf16 v[18:21], v[158:161], v[182:185], v[18:21]
	v_mfma_f32_16x16x32_bf16 v[6:9], v[150:153], v[208:211], v[6:9]
	v_mfma_f32_16x16x32_bf16 v[2:5], v[158:161], v[208:211], v[2:5]
	s_barrier
; #define PG8_STAGE(bufoff, gbase, voff) do { _Pragma("unroll") for (int _i = 0; _i < 2; ++_i) \
;         __builtin_amdgcn_global_load_lds((const unsigned*)((const char*)(gbase) + (voff)[_i]), (PG8_LAS unsigned*)(lds + (bufoff) + ldsw + _i * 8192), 16, 0, 0); } while (0)
; #define PG8_LDA(dst, b, h) do { _Pragma("unroll") for (int m = 0; m < 4; ++m) _Pragma("unroll") for (int k = 0; k < 2; ++k) dst[m][k] = *(const PG8_LAS bf16x8*)(lds + PG8_SA(b, h) + aoff + m * 2048 + k * 1024); } while (0)
; #define PG8_LDB(dst, b, h) do { _Pragma("unroll") for (int n = 0; n < 2; ++n) _Pragma("unroll") for (int k = 0; k < 2; ++k) dst[n][k] = *(const PG8_LAS bf16x8*)(lds + PG8_SB(b, h) + boff + n * 2048 + k * 1024); } while (0)
; #define PG8_MMA(ai, bj, At, Bt) do { __builtin_amdgcn_s_setprio(1); _Pragma("unroll") for (int m = 0; m < 4; ++m) _Pragma("unroll") for (int n = 0; n < 2; ++n) _Pragma("unroll") for (int k = 0; k < 2; ++k) \
;         acc[ai][bj][m][n] = __builtin_amdgcn_mfma_f32_16x16x32_bf16(Bt[n][k], At[m][k], acc[ai][bj][m][n], 0, 0, 0); __builtin_amdgcn_s_setprio(0); } while (0)
; #define PG8_WAIT_V(n) asm volatile("s_waitcnt vmcnt(" #n ")" ::: "memory")
; #define PG8_WAIT_L(n) asm volatile("s_waitcnt lgkmcnt(" #n ")" ::: "memory")
; #define PG8_BAR __builtin_amdgcn_s_barrier()
; template <class Epi, class Sched, bool ALIGN_EPI = false, bool SP2 = false>
; __device__ __forceinline__ void gemm_phase(PG8_LAS unsigned char* lds, const Gemm g, const Sched& S, const Epi& E, const int wv) {
;     ...
;         for (int t = 0; t < nt; t += 2) {
;             const bool last = (t == nt - 2);
;             const char* a1 = cA + (size_t)(t + 1) * kstep;
;             const char* a2 = last ? nA : cA + (size_t)(t + 2) * kstep; const char* b2 = last ? nB : cB + (size_t)(t + 2) * kstep;
;             const char* a3 = a2 + kstep; const char* b3 = b2 + kstep;
;     ...
;             PG8_LDB(B0, 1, 0); PG8_LDB(B1, 1, 1); PG8_SCHED; PG8_LDA(At, 1, 0); PG8_STAGE(PG8_SA(0, 1), a2 + hstepA, voffA);
;             PG8_WAIT_V(8); PG8_WAIT_L(0); PG8_BAR; PG8_MMA(0, 0, At, B0); PG8_MMA(0, 1, At, B1); PG8_BAR; PG8_SCHED;
;             PG8_LDA(At, 1, 1); PG8_STAGE(PG8_SB(1, 0), b3, voffB); PG8_STAGE(PG8_SB(1, 1), b3 + hstepB, voffB); PG8_STAGE(PG8_SA(1, 0), a3, voffA);
;             PG8_WAIT_V(8); PG8_WAIT_L(0); PG8_BAR; PG8_MMA(1, 0, At, B0); PG8_MMA(1, 1, At, B1); PG8_BAR; PG8_SCHED;
	ds_read_b128 v[114:117], v236
	ds_read_b128 v[126:129], v236 offset:1024
	ds_read_b128 v[138:141], v236 offset:2048
	ds_read_b128 v[142:145], v236 offset:3072
	ds_read_b128 v[146:149], v237
	ds_read_b128 v[150:153], v237 offset:1024
	ds_read_b128 v[154:157], v237 offset:2048
	ds_read_b128 v[158:161], v237 offset:3072
	s_mov_b32 m0, s60
	ds_read_b128 v[162:165], v235 offset:32768
	ds_read_b128 v[166:169], v235 offset:33792
	ds_read_b128 v[170:173], v235 offset:34816
	ds_read_b128 v[174:177], v235 offset:35840
	ds_read_b128 v[178:181], v235 offset:36864
	ds_read_b128 v[182:185], v235 offset:37888
	ds_read_b128 v[204:207], v235 offset:38912
	ds_read_b128 v[208:211], v235 offset:39936
	global_load_lds_dwordx4 v212, s[52:53]
	s_mov_b32 m0, s61
	s_nop 0
	global_load_lds_dwordx4 v213, s[52:53]
	s_waitcnt vmcnt(8) lgkmcnt(0)
	s_barrier
	v_mfma_f32_16x16x32_bf16 v[134:137], v[114:117], v[162:165], v[134:137]
	v_mfma_f32_16x16x32_bf16 v[130:133], v[138:141], v[162:165], v[130:133]
	v_mfma_f32_16x16x32_bf16 v[110:113], v[114:117], v[170:173], v[110:113]
	v_mfma_f32_16x16x32_bf16 v[106:109], v[138:141], v[170:173], v[106:109]
	v_mfma_f32_16x16x32_bf16 v[94:97], v[114:117], v[178:181], v[94:97]
	v_mfma_f32_16x16x32_bf16 v[90:93], v[138:141], v[178:181], v[90:93]
	v_mfma_f32_16x16x32_bf16 v[78:81], v[114:117], v[204:207], v[78:81]
	v_mfma_f32_16x16x32_bf16 v[74:77], v[138:141], v[204:207], v[74:77]
	v_mfma_f32_16x16x32_bf16 v[134:137], v[126:129], v[166:169], v[134:137]
	v_mfma_f32_16x16x32_bf16 v[130:133], v[142:145], v[166:169], v[130:133]
	v_mfma_f32_16x16x32_bf16 v[110:113], v[126:129], v[174:177], v[110:113]
	v_mfma_f32_16x16x32_bf16 v[106:109], v[142:145], v[174:177], v[106:109]
	v_mfma_f32_16x16x32_bf16 v[94:97], v[126:129], v[182:185], v[94:97]
	v_mfma_f32_16x16x32_bf16 v[90:93], v[142:145], v[182:185], v[90:93]
	v_mfma_f32_16x16x32_bf16 v[78:81], v[126:129], v[208:211], v[78:81]
	v_mfma_f32_16x16x32_bf16 v[74:77], v[142:145], v[208:211], v[74:77]
	v_mfma_f32_16x16x32_bf16 v[122:125], v[146:149], v[162:165], v[122:125]
	v_mfma_f32_16x16x32_bf16 v[118:121], v[154:157], v[162:165], v[118:121]
	v_mfma_f32_16x16x32_bf16 v[102:105], v[146:149], v[170:173], v[102:105]
	v_mfma_f32_16x16x32_bf16 v[98:101], v[154:157], v[170:173], v[98:101]
	v_mfma_f32_16x16x32_bf16 v[86:89], v[146:149], v[178:181], v[86:89]
	v_mfma_f32_16x16x32_bf16 v[82:85], v[154:157], v[178:181], v[82:85]
	v_mfma_f32_16x16x32_bf16 v[70:73], v[146:149], v[204:207], v[70:73]
	v_mfma_f32_16x16x32_bf16 v[66:69], v[154:157], v[204:207], v[66:69]
	v_mfma_f32_16x16x32_bf16 v[122:125], v[150:153], v[166:169], v[122:125]
	v_mfma_f32_16x16x32_bf16 v[118:121], v[158:161], v[166:169], v[118:121]
	v_mfma_f32_16x16x32_bf16 v[102:105], v[150:153], v[174:177], v[102:105]
	v_mfma_f32_16x16x32_bf16 v[98:101], v[158:161], v[174:177], v[98:101]
	v_mfma_f32_16x16x32_bf16 v[86:89], v[150:153], v[182:185], v[86:89]
	v_mfma_f32_16x16x32_bf16 v[82:85], v[158:161], v[182:185], v[82:85]
	v_mfma_f32_16x16x32_bf16 v[70:73], v[150:153], v[208:211], v[70:73]
	v_mfma_f32_16x16x32_bf16 v[66:69], v[158:161], v[208:211], v[66:69]
	s_barrier
	s_add_i32 m0, s3, 0x17f80
	ds_read_b128 v[162:165], v235 offset:49152
	ds_read_b128 v[166:169], v235 offset:50176
	ds_read_b128 v[170:173], v235 offset:51200
	ds_read_b128 v[174:177], v235 offset:52224
	ds_read_b128 v[178:181], v235 offset:53248
	ds_read_b128 v[182:185], v235 offset:54272
	ds_read_b128 v[204:207], v235 offset:55296
	ds_read_b128 v[208:211], v235 offset:56320
	global_load_lds_dwordx4 v[190:191], off offset:128
	s_add_i32 m0, s3, 0x19f80
	global_load_lds_dwordx4 v[192:193], off offset:128
	s_add_i32 m0, s3, 0x1bf80
	s_nop 0
	global_load_lds_dwordx4 v0, s[72:73] offset:128
	s_add_i32 m0, s3, 0x1df80
	s_nop 0
	global_load_lds_dwordx4 v198, s[72:73] offset:128
	s_add_i32 m0, s63, 0xffffff80
	s_nop 0
	global_load_lds_dwordx4 v194, s[52:53] offset:128
	s_add_i32 m0, s64, 0xffffff80
	s_nop 0
	global_load_lds_dwordx4 v196, s[52:53] offset:128
	s_waitcnt vmcnt(8) lgkmcnt(0)
	s_barrier
	v_mfma_f32_16x16x32_bf16 v[62:65], v[114:117], v[162:165], v[62:65]
	v_mfma_f32_16x16x32_bf16 v[58:61], v[138:141], v[162:165], v[58:61]
	v_mfma_f32_16x16x32_bf16 v[46:49], v[114:117], v[170:173], v[46:49]
	v_mfma_f32_16x16x32_bf16 v[42:45], v[138:141], v[170:173], v[42:45]
	v_mfma_f32_16x16x32_bf16 v[30:33], v[114:117], v[178:181], v[30:33]
	v_mfma_f32_16x16x32_bf16 v[26:29], v[138:141], v[178:181], v[26:29]
	v_mfma_f32_16x16x32_bf16 v[14:17], v[114:117], v[204:207], v[14:17]
	v_mfma_f32_16x16x32_bf16 v[10:13], v[138:141], v[204:207], v[10:13]
	v_mfma_f32_16x16x32_bf16 v[62:65], v[126:129], v[166:169], v[62:65]
	v_mfma_f32_16x16x32_bf16 v[58:61], v[142:145], v[166:169], v[58:61]
	v_mfma_f32_16x16x32_bf16 v[46:49], v[126:129], v[174:177], v[46:49]
	v_mfma_f32_16x16x32_bf16 v[42:45], v[142:145], v[174:177], v[42:45]
	v_mfma_f32_16x16x32_bf16 v[30:33], v[126:129], v[182:185], v[30:33]
	v_mfma_f32_16x16x32_bf16 v[26:29], v[142:145], v[182:185], v[26:29]
	v_mfma_f32_16x16x32_bf16 v[14:17], v[126:129], v[208:211], v[14:17]
	v_mfma_f32_16x16x32_bf16 v[10:13], v[142:145], v[208:211], v[10:13]
	v_mfma_f32_16x16x32_bf16 v[54:57], v[146:149], v[162:165], v[54:57]
	v_mfma_f32_16x16x32_bf16 v[50:53], v[154:157], v[162:165], v[50:53]
	v_mfma_f32_16x16x32_bf16 v[38:41], v[146:149], v[170:173], v[38:41]
	v_mfma_f32_16x16x32_bf16 v[34:37], v[154:157], v[170:173], v[34:37]
	v_mfma_f32_16x16x32_bf16 v[22:25], v[146:149], v[178:181], v[22:25]
	v_mfma_f32_16x16x32_bf16 v[18:21], v[154:157], v[178:181], v[18:21]
	v_mfma_f32_16x16x32_bf16 v[6:9], v[146:149], v[204:207], v[6:9]
	v_mfma_f32_16x16x32_bf16 v[2:5], v[154:157], v[204:207], v[2:5]
	v_mfma_f32_16x16x32_bf16 v[54:57], v[150:153], v[166:169], v[54:57]
	v_mfma_f32_16x16x32_bf16 v[50:53], v[158:161], v[166:169], v[50:53]
	v_mfma_f32_16x16x32_bf16 v[38:41], v[150:153], v[174:177], v[38:41]
	v_mfma_f32_16x16x32_bf16 v[34:37], v[158:161], v[174:177], v[34:37]
	v_mfma_f32_16x16x32_bf16 v[22:25], v[150:153], v[182:185], v[22:25]
	v_mfma_f32_16x16x32_bf16 v[18:21], v[158:161], v[182:185], v[18:21]
	v_mfma_f32_16x16x32_bf16 v[6:9], v[150:153], v[208:211], v[6:9]
	v_mfma_f32_16x16x32_bf16 v[2:5], v[158:161], v[208:211], v[2:5]
	s_add_u32 s44, s44, 0x100
	s_addc_u32 s45, s45, 0
	s_add_u32 s54, s54, 0x100
	s_addc_u32 s55, s55, 0
	s_cmp_ge_i32 s70, s62
	s_mov_b32 s52, s70
	s_barrier
	s_cbranch_scc0 .LBB0_1385
	s_mov_b32 s72, 0x10000
	s_mov_b32 s73, 0x12000
	s_mov_b32 s74, 0x14000
	s_mov_b32 s70, 0x18000
	s_mov_b32 s71, 0x3f317217
	s_and_b64 vcc, exec, s[46:47]
	s_cbranch_vccz .LBB0_1361

; #define PG8_STAGE(bufoff, gbase, voff) do { _Pragma("unroll") for (int _i = 0; _i < 2; ++_i) \
;         __builtin_amdgcn_global_load_lds((const unsigned*)((const char*)(gbase) + (voff)[_i]), (PG8_LAS unsigned*)(lds + (bufoff) + ldsw + _i * 8192), 16, 0, 0); } while (0)
; #define PG8_LDA(dst, b, h) do { _Pragma("unroll") for (int m = 0; m < 4; ++m) _Pragma("unroll") for (int k = 0; k < 2; ++k) dst[m][k] = *(const PG8_LAS bf16x8*)(lds + PG8_SA(b, h) + aoff + m * 2048 + k * 1024); } while (0)
; #define PG8_LDB(dst, b, h) do { _Pragma("unroll") for (int n = 0; n < 2; ++n) _Pragma("unroll") for (int k = 0; k < 2; ++k) dst[n][k] = *(const PG8_LAS bf16x8*)(lds + PG8_SB(b, h) + boff + n * 2048 + k * 1024); } while (0)
; #define PG8_MMA(ai, bj, At, Bt) do { __builtin_amdgcn_s_setprio(1); _Pragma("unroll") for (int m = 0; m < 4; ++m) _Pragma("unroll") for (int n = 0; n < 2; ++n) _Pragma("unroll") for (int k = 0; k < 2; ++k) \
;         acc[ai][bj][m][n] = __builtin_amdgcn_mfma_f32_16x16x32_bf16(Bt[n][k], At[m][k], acc[ai][bj][m][n], 0, 0, 0); __builtin_amdgcn_s_setprio(0); } while (0)
; #define PG8_WAIT_V(n) asm volatile("s_waitcnt vmcnt(" #n ")" ::: "memory")
; #define PG8_WAIT_L(n) asm volatile("s_waitcnt lgkmcnt(" #n ")" ::: "memory")
; template <class Epi, class Sched, bool ALIGN_EPI = false, bool SP2 = false>
; __device__ __forceinline__ void gemm_phase(PG8_LAS unsigned char* lds, const Gemm g, const Sched& S, const Epi& E, const int wv) {
;     ...
;             const bool last = (t == nt - 2);
;             const char* a1 = cA + (size_t)(t + 1) * kstep;
;             const char* a2 = last ? nA : cA + (size_t)(t + 2) * kstep; const char* b2 = last ? nB : cB + (size_t)(t + 2) * kstep;
;             const char* a3 = a2 + kstep; const char* b3 = b2 + kstep;
;             if (last && has_next) S.a_ready(nxt);
;             if constexpr (SP2) {
;             PG8_LDB(B0, 0, 0); PG8_LDB(B1, 0, 1); PG8_SCHED; PG8_LDA(At, 0, 0); PG8_STAGE(PG8_SA(1, 1), a1 + hstepA, voffA);
;             PG8_WAIT_V(8); PG8_WAIT_L(0); PG8_BAR; PG8_MMA(0, 0, At, B0); PG8_MMA(0, 1, At, B1); PG8_BAR; PG8_SCHED;
;             PG8_LDA(At, 0, 1); PG8_STAGE(PG8_SB(0, 0), b2, voffB); PG8_STAGE(PG8_SB(0, 1), b2 + hstepB, voffB); PG8_STAGE(PG8_SA(0, 0), a2, voffA);
;             PG8_WAIT_V(8); PG8_WAIT_L(0); PG8_BAR; PG8_MMA(1, 0, At, B0); PG8_MMA(1, 1, At, B1); PG8_BAR; PG8_SCHED;
.LBB0_1495:
	s_add_i32 s52, s46, 2
	s_add_u32 s14, s48, 0x100
	s_addc_u32 s15, s49, 0
	s_cmp_eq_u32 s72, s46
	s_cselect_b32 s47, s11, s15
	s_cselect_b32 s46, s13, s14
	s_cselect_b32 s77, s87, s51
	s_cselect_b32 s76, s86, s35
	ds_read_b128 v[138:141], v192
	ds_read_b128 v[142:145], v192 offset:1024
	ds_read_b128 v[146:149], v192 offset:2048
	ds_read_b128 v[150:153], v192 offset:3072
	ds_read_b128 v[154:157], v193
	ds_read_b128 v[158:161], v193 offset:1024
	ds_read_b128 v[162:165], v193 offset:2048
	ds_read_b128 v[166:169], v193 offset:3072
	s_add_i32 m0, s64, 0xc000
	ds_read_b128 v[194:197], v211
	ds_read_b128 v[198:201], v211 offset:1024
	ds_read_b128 v[202:205], v211 offset:2048
	ds_read_b128 v[214:217], v211 offset:3072
	ds_read_b128 v[228:231], v211 offset:4096
	ds_read_b128 v[232:235], v211 offset:5120
	ds_read_b128 v[236:239], v211 offset:6144
	ds_read_b128 v[240:243], v211 offset:7168
	global_load_lds_dwordx4 v182, s[48:49]
	v_lshl_add_u64 v[190:191], s[48:49], 0, v[184:185]
	s_add_i32 m0, s64, 0xe000
	s_nop 0
	global_load_lds_dwordx4 v[190:191], off
	s_waitcnt vmcnt(8) lgkmcnt(0)
	s_barrier
	v_mfma_f32_16x16x32_bf16 v[118:121], v[138:141], v[194:197], v[118:121]
	v_mfma_f32_16x16x32_bf16 v[46:49], v[146:149], v[194:197], v[46:49]
	v_mfma_f32_16x16x32_bf16 v[110:113], v[138:141], v[202:205], v[110:113]
	v_mfma_f32_16x16x32_bf16 v[38:41], v[146:149], v[202:205], v[38:41]
	v_mfma_f32_16x16x32_bf16 v[134:137], v[138:141], v[228:231], v[134:137]
	v_mfma_f32_16x16x32_bf16 v[62:65], v[146:149], v[228:231], v[62:65]
	v_mfma_f32_16x16x32_bf16 v[130:133], v[138:141], v[236:239], v[130:133]
	v_mfma_f32_16x16x32_bf16 v[58:61], v[146:149], v[236:239], v[58:61]
	v_mfma_f32_16x16x32_bf16 v[118:121], v[142:145], v[198:201], v[118:121]
	v_mfma_f32_16x16x32_bf16 v[46:49], v[150:153], v[198:201], v[46:49]
	v_mfma_f32_16x16x32_bf16 v[110:113], v[142:145], v[214:217], v[110:113]
	v_mfma_f32_16x16x32_bf16 v[38:41], v[150:153], v[214:217], v[38:41]
	v_mfma_f32_16x16x32_bf16 v[134:137], v[142:145], v[232:235], v[134:137]
	v_mfma_f32_16x16x32_bf16 v[62:65], v[150:153], v[232:235], v[62:65]
	v_mfma_f32_16x16x32_bf16 v[130:133], v[142:145], v[240:243], v[130:133]
	v_mfma_f32_16x16x32_bf16 v[58:61], v[150:153], v[240:243], v[58:61]
	v_mfma_f32_16x16x32_bf16 v[114:117], v[154:157], v[194:197], v[114:117]
	v_mfma_f32_16x16x32_bf16 v[42:45], v[162:165], v[194:197], v[42:45]
	v_mfma_f32_16x16x32_bf16 v[106:109], v[154:157], v[202:205], v[106:109]
	v_mfma_f32_16x16x32_bf16 v[34:37], v[162:165], v[202:205], v[34:37]
	v_mfma_f32_16x16x32_bf16 v[126:129], v[154:157], v[228:231], v[126:129]
	v_mfma_f32_16x16x32_bf16 v[54:57], v[162:165], v[228:231], v[54:57]
	v_mfma_f32_16x16x32_bf16 v[122:125], v[154:157], v[236:239], v[122:125]
	v_mfma_f32_16x16x32_bf16 v[50:53], v[162:165], v[236:239], v[50:53]
	v_mfma_f32_16x16x32_bf16 v[114:117], v[158:161], v[198:201], v[114:117]
	v_mfma_f32_16x16x32_bf16 v[42:45], v[166:169], v[198:201], v[42:45]
	v_mfma_f32_16x16x32_bf16 v[106:109], v[158:161], v[214:217], v[106:109]
	v_mfma_f32_16x16x32_bf16 v[34:37], v[166:169], v[214:217], v[34:37]
	v_mfma_f32_16x16x32_bf16 v[126:129], v[158:161], v[232:235], v[126:129]
	v_mfma_f32_16x16x32_bf16 v[54:57], v[166:169], v[232:235], v[54:57]
	v_mfma_f32_16x16x32_bf16 v[122:125], v[158:161], v[240:243], v[122:125]
	v_mfma_f32_16x16x32_bf16 v[50:53], v[166:169], v[240:243], v[50:53]
	s_barrier
	s_add_i32 s48, s63, 0x10000
	s_mov_b32 m0, s48
	ds_read_b128 v[194:197], v211 offset:16384
	ds_read_b128 v[198:201], v211 offset:17408
	ds_read_b128 v[202:205], v211 offset:18432
	ds_read_b128 v[214:217], v211 offset:19456
	ds_read_b128 v[228:231], v211 offset:20480
	ds_read_b128 v[232:235], v211 offset:21504
	ds_read_b128 v[236:239], v211 offset:22528
	ds_read_b128 v[240:243], v211 offset:23552
	global_load_lds_dwordx4 v0, s[76:77]
	s_add_i32 m0, s48, 0x2000
	s_add_u32 s48, s76, s16
	s_addc_u32 s49, s77, s17
	s_add_i32 s53, s63, 0x14000
	global_load_lds_dwordx4 v174, s[76:77]
	s_mov_b32 m0, s53
	global_load_lds_dwordx4 v0, s[48:49]
	s_add_i32 m0, s53, 0x2000
	global_load_lds_dwordx4 v174, s[48:49]
	s_mov_b32 m0, s64
	global_load_lds_dwordx4 v170, s[46:47]
	s_mov_b32 m0, s65
	s_nop 0
	global_load_lds_dwordx4 v172, s[46:47]
	s_waitcnt vmcnt(8) lgkmcnt(0)
	s_barrier
	v_mfma_f32_16x16x32_bf16 v[86:89], v[138:141], v[194:197], v[86:89]
	v_mfma_f32_16x16x32_bf16 v[14:17], v[146:149], v[194:197], v[14:17]
	v_mfma_f32_16x16x32_bf16 v[70:73], v[138:141], v[202:205], v[70:73]
	v_mfma_f32_16x16x32_bf16 v[6:9], v[146:149], v[202:205], v[6:9]
	v_mfma_f32_16x16x32_bf16 v[102:105], v[138:141], v[228:231], v[102:105]
	v_mfma_f32_16x16x32_bf16 v[30:33], v[146:149], v[228:231], v[30:33]
	v_mfma_f32_16x16x32_bf16 v[98:101], v[138:141], v[236:239], v[98:101]
	v_mfma_f32_16x16x32_bf16 v[26:29], v[146:149], v[236:239], v[26:29]
	v_mfma_f32_16x16x32_bf16 v[86:89], v[142:145], v[198:201], v[86:89]
	v_mfma_f32_16x16x32_bf16 v[14:17], v[150:153], v[198:201], v[14:17]
	v_mfma_f32_16x16x32_bf16 v[70:73], v[142:145], v[214:217], v[70:73]
	v_mfma_f32_16x16x32_bf16 v[6:9], v[150:153], v[214:217], v[6:9]
	v_mfma_f32_16x16x32_bf16 v[102:105], v[142:145], v[232:235], v[102:105]
	v_mfma_f32_16x16x32_bf16 v[30:33], v[150:153], v[232:235], v[30:33]
	v_mfma_f32_16x16x32_bf16 v[98:101], v[142:145], v[240:243], v[98:101]
	v_mfma_f32_16x16x32_bf16 v[26:29], v[150:153], v[240:243], v[26:29]
	v_mfma_f32_16x16x32_bf16 v[82:85], v[154:157], v[194:197], v[82:85]
	v_mfma_f32_16x16x32_bf16 v[10:13], v[162:165], v[194:197], v[10:13]
	v_mfma_f32_16x16x32_bf16 v[66:69], v[154:157], v[202:205], v[66:69]
	v_mfma_f32_16x16x32_bf16 v[2:5], v[162:165], v[202:205], v[2:5]
	v_mfma_f32_16x16x32_bf16 v[94:97], v[154:157], v[228:231], v[94:97]
	v_mfma_f32_16x16x32_bf16 v[22:25], v[162:165], v[228:231], v[22:25]
	v_mfma_f32_16x16x32_bf16 v[90:93], v[154:157], v[236:239], v[90:93]
	v_mfma_f32_16x16x32_bf16 v[18:21], v[162:165], v[236:239], v[18:21]
	v_mfma_f32_16x16x32_bf16 v[82:85], v[158:161], v[198:201], v[82:85]
	v_mfma_f32_16x16x32_bf16 v[10:13], v[166:169], v[198:201], v[10:13]
	v_mfma_f32_16x16x32_bf16 v[66:69], v[158:161], v[214:217], v[66:69]
	v_mfma_f32_16x16x32_bf16 v[2:5], v[166:169], v[214:217], v[2:5]
	v_mfma_f32_16x16x32_bf16 v[94:97], v[158:161], v[232:235], v[94:97]
	v_mfma_f32_16x16x32_bf16 v[22:25], v[166:169], v[232:235], v[22:25]
	v_mfma_f32_16x16x32_bf16 v[90:93], v[158:161], v[240:243], v[90:93]
	v_mfma_f32_16x16x32_bf16 v[18:21], v[166:169], v[240:243], v[18:21]
	s_barrier
; #define PG8_STAGE(bufoff, gbase, voff) do { _Pragma("unroll") for (int _i = 0; _i < 2; ++_i) \
;         __builtin_amdgcn_global_load_lds((const unsigned*)((const char*)(gbase) + (voff)[_i]), (PG8_LAS unsigned*)(lds + (bufoff) + ldsw + _i * 8192), 16, 0, 0); } while (0)
; #define PG8_LDA(dst, b, h) do { _Pragma("unroll") for (int m = 0; m < 4; ++m) _Pragma("unroll") for (int k = 0; k < 2; ++k) dst[m][k] = *(const PG8_LAS bf16x8*)(lds + PG8_SA(b, h) + aoff + m * 2048 + k * 1024); } while (0)
; #define PG8_LDB(dst, b, h) do { _Pragma("unroll") for (int n = 0; n < 2; ++n) _Pragma("unroll") for (int k = 0; k < 2; ++k) dst[n][k] = *(const PG8_LAS bf16x8*)(lds + PG8_SB(b, h) + boff + n * 2048 + k * 1024); } while (0)
; #define PG8_MMA(ai, bj, At, Bt) do { __builtin_amdgcn_s_setprio(1); _Pragma("unroll") for (int m = 0; m < 4; ++m) _Pragma("unroll") for (int n = 0; n < 2; ++n) _Pragma("unroll") for (int k = 0; k < 2; ++k) \
;         acc[ai][bj][m][n] = __builtin_amdgcn_mfma_f32_16x16x32_bf16(Bt[n][k], At[m][k], acc[ai][bj][m][n], 0, 0, 0); __builtin_amdgcn_s_setprio(0); } while (0)
; #define PG8_WAIT_V(n) asm volatile("s_waitcnt vmcnt(" #n ")" ::: "memory")
; #define PG8_WAIT_L(n) asm volatile("s_waitcnt lgkmcnt(" #n ")" ::: "memory")
; #define PG8_BAR __builtin_amdgcn_s_barrier()
; template <class Epi, class Sched, bool ALIGN_EPI = false, bool SP2 = false>
; __device__ __forceinline__ void gemm_phase(PG8_LAS unsigned char* lds, const Gemm g, const Sched& S, const Epi& E, const int wv) {
;     ...
;         for (int t = 0; t < nt; t += 2) {
;             const bool last = (t == nt - 2);
;             const char* a1 = cA + (size_t)(t + 1) * kstep;
;             const char* a2 = last ? nA : cA + (size_t)(t + 2) * kstep; const char* b2 = last ? nB : cB + (size_t)(t + 2) * kstep;
;             const char* a3 = a2 + kstep; const char* b3 = b2 + kstep;
;     ...
;             PG8_LDB(B0, 1, 0); PG8_LDB(B1, 1, 1); PG8_SCHED; PG8_LDA(At, 1, 0); PG8_STAGE(PG8_SA(0, 1), a2 + hstepA, voffA);
;             PG8_WAIT_V(8); PG8_WAIT_L(0); PG8_BAR; PG8_MMA(0, 0, At, B0); PG8_MMA(0, 1, At, B1); PG8_BAR; PG8_SCHED;
;             PG8_LDA(At, 1, 1); PG8_STAGE(PG8_SB(1, 0), b3, voffB); PG8_STAGE(PG8_SB(1, 1), b3 + hstepB, voffB); PG8_STAGE(PG8_SA(1, 0), a3, voffA);
;             PG8_WAIT_V(8); PG8_WAIT_L(0); PG8_BAR; PG8_MMA(1, 0, At, B0); PG8_MMA(1, 1, At, B1); PG8_BAR; PG8_SCHED;
	ds_read_b128 v[138:141], v213
	ds_read_b128 v[142:145], v213 offset:1024
	ds_read_b128 v[146:149], v213 offset:2048
	ds_read_b128 v[150:153], v213 offset:3072
	ds_read_b128 v[154:157], v227
	ds_read_b128 v[158:161], v227 offset:1024
	ds_read_b128 v[162:165], v227 offset:2048
	ds_read_b128 v[166:169], v227 offset:3072
	s_mov_b32 m0, s66
	ds_read_b128 v[194:197], v211 offset:32768
	ds_read_b128 v[198:201], v211 offset:33792
	ds_read_b128 v[202:205], v211 offset:34816
	ds_read_b128 v[214:217], v211 offset:35840
	ds_read_b128 v[228:231], v211 offset:36864
	ds_read_b128 v[232:235], v211 offset:37888
	ds_read_b128 v[236:239], v211 offset:38912
	ds_read_b128 v[240:243], v211 offset:39936
	global_load_lds_dwordx4 v218, s[46:47]
	s_mov_b32 m0, s67
	s_nop 0
	global_load_lds_dwordx4 v219, s[46:47]
	s_waitcnt vmcnt(8) lgkmcnt(0)
	s_barrier
	v_mfma_f32_16x16x32_bf16 v[118:121], v[138:141], v[194:197], v[118:121]
	v_mfma_f32_16x16x32_bf16 v[46:49], v[146:149], v[194:197], v[46:49]
	v_mfma_f32_16x16x32_bf16 v[110:113], v[138:141], v[202:205], v[110:113]
	v_mfma_f32_16x16x32_bf16 v[38:41], v[146:149], v[202:205], v[38:41]
	v_mfma_f32_16x16x32_bf16 v[134:137], v[138:141], v[228:231], v[134:137]
	v_mfma_f32_16x16x32_bf16 v[62:65], v[146:149], v[228:231], v[62:65]
	v_mfma_f32_16x16x32_bf16 v[130:133], v[138:141], v[236:239], v[130:133]
	v_mfma_f32_16x16x32_bf16 v[58:61], v[146:149], v[236:239], v[58:61]
	v_mfma_f32_16x16x32_bf16 v[118:121], v[142:145], v[198:201], v[118:121]
	v_mfma_f32_16x16x32_bf16 v[46:49], v[150:153], v[198:201], v[46:49]
	v_mfma_f32_16x16x32_bf16 v[110:113], v[142:145], v[214:217], v[110:113]
	v_mfma_f32_16x16x32_bf16 v[38:41], v[150:153], v[214:217], v[38:41]
	v_mfma_f32_16x16x32_bf16 v[134:137], v[142:145], v[232:235], v[134:137]
	v_mfma_f32_16x16x32_bf16 v[62:65], v[150:153], v[232:235], v[62:65]
	v_mfma_f32_16x16x32_bf16 v[130:133], v[142:145], v[240:243], v[130:133]
	v_mfma_f32_16x16x32_bf16 v[58:61], v[150:153], v[240:243], v[58:61]
	v_mfma_f32_16x16x32_bf16 v[114:117], v[154:157], v[194:197], v[114:117]
	v_mfma_f32_16x16x32_bf16 v[42:45], v[162:165], v[194:197], v[42:45]
	v_mfma_f32_16x16x32_bf16 v[106:109], v[154:157], v[202:205], v[106:109]
	v_mfma_f32_16x16x32_bf16 v[34:37], v[162:165], v[202:205], v[34:37]
	v_mfma_f32_16x16x32_bf16 v[126:129], v[154:157], v[228:231], v[126:129]
	v_mfma_f32_16x16x32_bf16 v[54:57], v[162:165], v[228:231], v[54:57]
	v_mfma_f32_16x16x32_bf16 v[122:125], v[154:157], v[236:239], v[122:125]
	v_mfma_f32_16x16x32_bf16 v[50:53], v[162:165], v[236:239], v[50:53]
	v_mfma_f32_16x16x32_bf16 v[114:117], v[158:161], v[198:201], v[114:117]
	v_mfma_f32_16x16x32_bf16 v[42:45], v[166:169], v[198:201], v[42:45]
	v_mfma_f32_16x16x32_bf16 v[106:109], v[158:161], v[214:217], v[106:109]
	v_mfma_f32_16x16x32_bf16 v[34:37], v[166:169], v[214:217], v[34:37]
	v_mfma_f32_16x16x32_bf16 v[126:129], v[158:161], v[232:235], v[126:129]
	v_mfma_f32_16x16x32_bf16 v[54:57], v[166:169], v[232:235], v[54:57]
	v_mfma_f32_16x16x32_bf16 v[122:125], v[158:161], v[240:243], v[122:125]
	v_mfma_f32_16x16x32_bf16 v[50:53], v[166:169], v[240:243], v[50:53]
	s_barrier
	s_add_i32 m0, s63, 0x17f80
	ds_read_b128 v[194:197], v211 offset:49152
	ds_read_b128 v[198:201], v211 offset:50176
	ds_read_b128 v[202:205], v211 offset:51200
	ds_read_b128 v[214:217], v211 offset:52224
	ds_read_b128 v[228:231], v211 offset:53248
	ds_read_b128 v[232:235], v211 offset:54272
	ds_read_b128 v[236:239], v211 offset:55296
	ds_read_b128 v[240:243], v211 offset:56320
	global_load_lds_dwordx4 v0, s[76:77] offset:128
	s_add_i32 m0, s63, 0x19f80
	global_load_lds_dwordx4 v174, s[76:77] offset:128
	s_add_i32 m0, s63, 0x1bf80
	s_nop 0
	global_load_lds_dwordx4 v0, s[48:49] offset:128
	s_add_i32 m0, s63, 0x1df80
	s_nop 0
	global_load_lds_dwordx4 v174, s[48:49] offset:128
	s_add_i32 m0, s70, 0xffffff80
	s_nop 0
	global_load_lds_dwordx4 v170, s[46:47] offset:128
	s_add_i32 m0, s71, 0xffffff80
	s_nop 0
	global_load_lds_dwordx4 v172, s[46:47] offset:128
	s_waitcnt vmcnt(8) lgkmcnt(0)
	s_barrier
	v_mfma_f32_16x16x32_bf16 v[86:89], v[138:141], v[194:197], v[86:89]
	v_mfma_f32_16x16x32_bf16 v[14:17], v[146:149], v[194:197], v[14:17]
	v_mfma_f32_16x16x32_bf16 v[70:73], v[138:141], v[202:205], v[70:73]
	v_mfma_f32_16x16x32_bf16 v[6:9], v[146:149], v[202:205], v[6:9]
	v_mfma_f32_16x16x32_bf16 v[102:105], v[138:141], v[228:231], v[102:105]
	v_mfma_f32_16x16x32_bf16 v[30:33], v[146:149], v[228:231], v[30:33]
	v_mfma_f32_16x16x32_bf16 v[98:101], v[138:141], v[236:239], v[98:101]
	v_mfma_f32_16x16x32_bf16 v[26:29], v[146:149], v[236:239], v[26:29]
	v_mfma_f32_16x16x32_bf16 v[86:89], v[142:145], v[198:201], v[86:89]
	v_mfma_f32_16x16x32_bf16 v[14:17], v[150:153], v[198:201], v[14:17]
	v_mfma_f32_16x16x32_bf16 v[70:73], v[142:145], v[214:217], v[70:73]
	v_mfma_f32_16x16x32_bf16 v[6:9], v[150:153], v[214:217], v[6:9]
	v_mfma_f32_16x16x32_bf16 v[102:105], v[142:145], v[232:235], v[102:105]
	v_mfma_f32_16x16x32_bf16 v[30:33], v[150:153], v[232:235], v[30:33]
	v_mfma_f32_16x16x32_bf16 v[98:101], v[142:145], v[240:243], v[98:101]
	v_mfma_f32_16x16x32_bf16 v[26:29], v[150:153], v[240:243], v[26:29]
	v_mfma_f32_16x16x32_bf16 v[82:85], v[154:157], v[194:197], v[82:85]
	v_mfma_f32_16x16x32_bf16 v[10:13], v[162:165], v[194:197], v[10:13]
	v_mfma_f32_16x16x32_bf16 v[66:69], v[154:157], v[202:205], v[66:69]
	v_mfma_f32_16x16x32_bf16 v[2:5], v[162:165], v[202:205], v[2:5]
	v_mfma_f32_16x16x32_bf16 v[94:97], v[154:157], v[228:231], v[94:97]
	v_mfma_f32_16x16x32_bf16 v[22:25], v[162:165], v[228:231], v[22:25]
	v_mfma_f32_16x16x32_bf16 v[90:93], v[154:157], v[236:239], v[90:93]
	v_mfma_f32_16x16x32_bf16 v[18:21], v[162:165], v[236:239], v[18:21]
	v_mfma_f32_16x16x32_bf16 v[82:85], v[158:161], v[198:201], v[82:85]
	v_mfma_f32_16x16x32_bf16 v[10:13], v[166:169], v[198:201], v[10:13]
	v_mfma_f32_16x16x32_bf16 v[66:69], v[158:161], v[214:217], v[66:69]
	v_mfma_f32_16x16x32_bf16 v[2:5], v[166:169], v[214:217], v[2:5]
	v_mfma_f32_16x16x32_bf16 v[94:97], v[158:161], v[232:235], v[94:97]
	v_mfma_f32_16x16x32_bf16 v[22:25], v[166:169], v[232:235], v[22:25]
	v_mfma_f32_16x16x32_bf16 v[90:93], v[158:161], v[240:243], v[90:93]
	v_mfma_f32_16x16x32_bf16 v[18:21], v[166:169], v[240:243], v[18:21]
	s_add_u32 s35, s35, 0x100
	s_addc_u32 s51, s51, 0
	s_cmp_ge_i32 s52, s68
	s_mov_b64 s[48:49], s[14:15]
	s_mov_b32 s46, s52
	s_barrier
	s_cbranch_scc0 .LBB0_1495
	s_movk_i32 s78, 0x7ff
	s_movk_i32 s76, 0x3000
	s_and_b64 vcc, exec, s[30:31]
	s_cbranch_vccz .LBB0_1470

; #define PG8_STAGE(bufoff, gbase, voff) do { _Pragma("unroll") for (int _i = 0; _i < 2; ++_i) \
;         __builtin_amdgcn_global_load_lds((const unsigned*)((const char*)(gbase) + (voff)[_i]), (PG8_LAS unsigned*)(lds + (bufoff) + ldsw + _i * 8192), 16, 0, 0); } while (0)
; #define PG8_LDA(dst, b, h) do { _Pragma("unroll") for (int m = 0; m < 4; ++m) _Pragma("unroll") for (int k = 0; k < 2; ++k) dst[m][k] = *(const PG8_LAS bf16x8*)(lds + PG8_SA(b, h) + aoff + m * 2048 + k * 1024); } while (0)
; #define PG8_LDB(dst, b, h) do { _Pragma("unroll") for (int n = 0; n < 2; ++n) _Pragma("unroll") for (int k = 0; k < 2; ++k) dst[n][k] = *(const PG8_LAS bf16x8*)(lds + PG8_SB(b, h) + boff + n * 2048 + k * 1024); } while (0)
; #define PG8_MMA(ai, bj, At, Bt) do { __builtin_amdgcn_s_setprio(1); _Pragma("unroll") for (int m = 0; m < 4; ++m) _Pragma("unroll") for (int n = 0; n < 2; ++n) _Pragma("unroll") for (int k = 0; k < 2; ++k) \
;         acc[ai][bj][m][n] = __builtin_amdgcn_mfma_f32_16x16x32_bf16(Bt[n][k], At[m][k], acc[ai][bj][m][n], 0, 0, 0); __builtin_amdgcn_s_setprio(0); } while (0)
; #define PG8_WAIT_V(n) asm volatile("s_waitcnt vmcnt(" #n ")" ::: "memory")
; #define PG8_WAIT_L(n) asm volatile("s_waitcnt lgkmcnt(" #n ")" ::: "memory")
; template <class Epi, class Sched, bool ALIGN_EPI = false, bool SP2 = false>
; __device__ __forceinline__ void gemm_phase(PG8_LAS unsigned char* lds, const Gemm g, const Sched& S, const Epi& E, const int wv) {
;     ...
;             const bool last = (t == nt - 2);
;             const char* a1 = cA + (size_t)(t + 1) * kstep;
;             const char* a2 = last ? nA : cA + (size_t)(t + 2) * kstep; const char* b2 = last ? nB : cB + (size_t)(t + 2) * kstep;
;             const char* a3 = a2 + kstep; const char* b3 = b2 + kstep;
;             if (last && has_next) S.a_ready(nxt);
;             if constexpr (SP2) {
;             PG8_LDB(B0, 0, 0); PG8_LDB(B1, 0, 1); PG8_SCHED; PG8_LDA(At, 0, 0); PG8_STAGE(PG8_SA(1, 1), a1 + hstepA, voffA);
;             PG8_WAIT_V(8); PG8_WAIT_L(0); PG8_BAR; PG8_MMA(0, 0, At, B0); PG8_MMA(0, 1, At, B1); PG8_BAR; PG8_SCHED;
;             PG8_LDA(At, 0, 1); PG8_STAGE(PG8_SB(0, 0), b2, voffB); PG8_STAGE(PG8_SB(0, 1), b2 + hstepB, voffB); PG8_STAGE(PG8_SA(0, 0), a2, voffA);
;             PG8_WAIT_V(8); PG8_WAIT_L(0); PG8_BAR; PG8_MMA(1, 0, At, B0); PG8_MMA(1, 1, At, B1); PG8_BAR; PG8_SCHED;
.LBB0_1676:
	s_add_i32 s67, s44, 2
	s_add_u32 s34, s30, 0x100
	s_addc_u32 s35, s31, 0
	s_cmp_eq_u32 s59, s44
	s_cselect_b32 s45, s13, s35
	s_cselect_b32 s44, s12, s34
	s_cselect_b32 s69, s15, s66
	s_cselect_b32 s68, s14, s65
	ds_read_b128 v[114:117], v197
	ds_read_b128 v[126:129], v197 offset:1024
	ds_read_b128 v[138:141], v197 offset:2048
	ds_read_b128 v[142:145], v197 offset:3072
	ds_read_b128 v[146:149], v201
	ds_read_b128 v[150:153], v201 offset:1024
	ds_read_b128 v[154:157], v201 offset:2048
	ds_read_b128 v[158:161], v201 offset:3072
	s_add_i32 m0, s52, 0xc000
	ds_read_b128 v[162:165], v235
	ds_read_b128 v[166:169], v235 offset:1024
	ds_read_b128 v[170:173], v235 offset:2048
	ds_read_b128 v[174:177], v235 offset:3072
	ds_read_b128 v[178:181], v235 offset:4096
	ds_read_b128 v[182:185], v235 offset:5120
	ds_read_b128 v[204:207], v235 offset:6144
	ds_read_b128 v[208:211], v235 offset:7168
	global_load_lds_dwordx4 v200, s[30:31]
	s_add_i32 m0, s52, 0xe000
	s_nop 0
	global_load_lds_dwordx4 v202, s[30:31]
	s_waitcnt vmcnt(8) lgkmcnt(0)
	s_barrier
	v_mfma_f32_16x16x32_bf16 v[134:137], v[114:117], v[162:165], v[134:137]
	v_mfma_f32_16x16x32_bf16 v[130:133], v[138:141], v[162:165], v[130:133]
	v_mfma_f32_16x16x32_bf16 v[110:113], v[114:117], v[170:173], v[110:113]
	v_mfma_f32_16x16x32_bf16 v[106:109], v[138:141], v[170:173], v[106:109]
	v_mfma_f32_16x16x32_bf16 v[94:97], v[114:117], v[178:181], v[94:97]
	v_mfma_f32_16x16x32_bf16 v[90:93], v[138:141], v[178:181], v[90:93]
	v_mfma_f32_16x16x32_bf16 v[78:81], v[114:117], v[204:207], v[78:81]
	v_mfma_f32_16x16x32_bf16 v[74:77], v[138:141], v[204:207], v[74:77]
	v_mfma_f32_16x16x32_bf16 v[134:137], v[126:129], v[166:169], v[134:137]
	v_mfma_f32_16x16x32_bf16 v[130:133], v[142:145], v[166:169], v[130:133]
	v_mfma_f32_16x16x32_bf16 v[110:113], v[126:129], v[174:177], v[110:113]
	v_mfma_f32_16x16x32_bf16 v[106:109], v[142:145], v[174:177], v[106:109]
	v_mfma_f32_16x16x32_bf16 v[94:97], v[126:129], v[182:185], v[94:97]
	v_mfma_f32_16x16x32_bf16 v[90:93], v[142:145], v[182:185], v[90:93]
	v_mfma_f32_16x16x32_bf16 v[78:81], v[126:129], v[208:211], v[78:81]
	v_mfma_f32_16x16x32_bf16 v[74:77], v[142:145], v[208:211], v[74:77]
	v_mfma_f32_16x16x32_bf16 v[122:125], v[146:149], v[162:165], v[122:125]
	v_mfma_f32_16x16x32_bf16 v[118:121], v[154:157], v[162:165], v[118:121]
	v_mfma_f32_16x16x32_bf16 v[102:105], v[146:149], v[170:173], v[102:105]
	v_mfma_f32_16x16x32_bf16 v[98:101], v[154:157], v[170:173], v[98:101]
	v_mfma_f32_16x16x32_bf16 v[86:89], v[146:149], v[178:181], v[86:89]
	v_mfma_f32_16x16x32_bf16 v[82:85], v[154:157], v[178:181], v[82:85]
	v_mfma_f32_16x16x32_bf16 v[70:73], v[146:149], v[204:207], v[70:73]
	v_mfma_f32_16x16x32_bf16 v[66:69], v[154:157], v[204:207], v[66:69]
	v_mfma_f32_16x16x32_bf16 v[122:125], v[150:153], v[166:169], v[122:125]
	v_mfma_f32_16x16x32_bf16 v[118:121], v[158:161], v[166:169], v[118:121]
	v_mfma_f32_16x16x32_bf16 v[102:105], v[150:153], v[174:177], v[102:105]
	v_mfma_f32_16x16x32_bf16 v[98:101], v[158:161], v[174:177], v[98:101]
	v_mfma_f32_16x16x32_bf16 v[86:89], v[150:153], v[182:185], v[86:89]
	v_mfma_f32_16x16x32_bf16 v[82:85], v[158:161], v[182:185], v[82:85]
	v_mfma_f32_16x16x32_bf16 v[70:73], v[150:153], v[208:211], v[70:73]
	v_mfma_f32_16x16x32_bf16 v[66:69], v[158:161], v[208:211], v[66:69]
	s_barrier
	s_add_i32 s30, s47, 0x10000
	v_lshl_add_u64 v[190:191], s[68:69], 0, v[0:1]
	s_mov_b32 m0, s30
	ds_read_b128 v[162:165], v235 offset:16384
	ds_read_b128 v[166:169], v235 offset:17408
	ds_read_b128 v[170:173], v235 offset:18432
	ds_read_b128 v[174:177], v235 offset:19456
	ds_read_b128 v[178:181], v235 offset:20480
	ds_read_b128 v[182:185], v235 offset:21504
	ds_read_b128 v[204:207], v235 offset:22528
	ds_read_b128 v[208:211], v235 offset:23552
	global_load_lds_dwordx4 v[190:191], off
	s_add_i32 m0, s30, 0x2000
	s_add_u32 s30, s68, s2
	v_lshl_add_u64 v[192:193], s[68:69], 0, v[198:199]
	s_addc_u32 s31, s69, s3
	s_add_i32 s68, s47, 0x14000
	global_load_lds_dwordx4 v[192:193], off
	v_lshl_add_u64 v[212:213], s[30:31], 0, v[0:1]
	s_mov_b32 m0, s68
	v_lshl_add_u64 v[214:215], s[30:31], 0, v[198:199]
	global_load_lds_dwordx4 v[212:213], off
	s_add_i32 m0, s68, 0x2000
	global_load_lds_dwordx4 v[214:215], off
	s_mov_b32 m0, s52
	global_load_lds_dwordx4 v194, s[44:45]
	s_mov_b32 m0, s53
	s_nop 0
	global_load_lds_dwordx4 v196, s[44:45]
	s_waitcnt vmcnt(8) lgkmcnt(0)
	s_barrier
	v_mfma_f32_16x16x32_bf16 v[62:65], v[114:117], v[162:165], v[62:65]
	v_mfma_f32_16x16x32_bf16 v[58:61], v[138:141], v[162:165], v[58:61]
	v_mfma_f32_16x16x32_bf16 v[46:49], v[114:117], v[170:173], v[46:49]
	v_mfma_f32_16x16x32_bf16 v[42:45], v[138:141], v[170:173], v[42:45]
	v_mfma_f32_16x16x32_bf16 v[30:33], v[114:117], v[178:181], v[30:33]
	v_mfma_f32_16x16x32_bf16 v[26:29], v[138:141], v[178:181], v[26:29]
	v_mfma_f32_16x16x32_bf16 v[14:17], v[114:117], v[204:207], v[14:17]
	v_mfma_f32_16x16x32_bf16 v[10:13], v[138:141], v[204:207], v[10:13]
	v_mfma_f32_16x16x32_bf16 v[62:65], v[126:129], v[166:169], v[62:65]
	v_mfma_f32_16x16x32_bf16 v[58:61], v[142:145], v[166:169], v[58:61]
	v_mfma_f32_16x16x32_bf16 v[46:49], v[126:129], v[174:177], v[46:49]
	v_mfma_f32_16x16x32_bf16 v[42:45], v[142:145], v[174:177], v[42:45]
	v_mfma_f32_16x16x32_bf16 v[30:33], v[126:129], v[182:185], v[30:33]
	v_mfma_f32_16x16x32_bf16 v[26:29], v[142:145], v[182:185], v[26:29]
	v_mfma_f32_16x16x32_bf16 v[14:17], v[126:129], v[208:211], v[14:17]
	v_mfma_f32_16x16x32_bf16 v[10:13], v[142:145], v[208:211], v[10:13]
	v_mfma_f32_16x16x32_bf16 v[54:57], v[146:149], v[162:165], v[54:57]
	v_mfma_f32_16x16x32_bf16 v[50:53], v[154:157], v[162:165], v[50:53]
	v_mfma_f32_16x16x32_bf16 v[38:41], v[146:149], v[170:173], v[38:41]
	v_mfma_f32_16x16x32_bf16 v[34:37], v[154:157], v[170:173], v[34:37]
	v_mfma_f32_16x16x32_bf16 v[22:25], v[146:149], v[178:181], v[22:25]
	v_mfma_f32_16x16x32_bf16 v[18:21], v[154:157], v[178:181], v[18:21]
	v_mfma_f32_16x16x32_bf16 v[6:9], v[146:149], v[204:207], v[6:9]
	v_mfma_f32_16x16x32_bf16 v[2:5], v[154:157], v[204:207], v[2:5]
	v_mfma_f32_16x16x32_bf16 v[54:57], v[150:153], v[166:169], v[54:57]
	v_mfma_f32_16x16x32_bf16 v[50:53], v[158:161], v[166:169], v[50:53]
	v_mfma_f32_16x16x32_bf16 v[38:41], v[150:153], v[174:177], v[38:41]
	v_mfma_f32_16x16x32_bf16 v[34:37], v[158:161], v[174:177], v[34:37]
	v_mfma_f32_16x16x32_bf16 v[22:25], v[150:153], v[182:185], v[22:25]
	v_mfma_f32_16x16x32_bf16 v[18:21], v[158:161], v[182:185], v[18:21]
	v_mfma_f32_16x16x32_bf16 v[6:9], v[150:153], v[208:211], v[6:9]
	v_mfma_f32_16x16x32_bf16 v[2:5], v[158:161], v[208:211], v[2:5]
	s_barrier
; #define PG8_STAGE(bufoff, gbase, voff) do { _Pragma("unroll") for (int _i = 0; _i < 2; ++_i) \
;         __builtin_amdgcn_global_load_lds((const unsigned*)((const char*)(gbase) + (voff)[_i]), (PG8_LAS unsigned*)(lds + (bufoff) + ldsw + _i * 8192), 16, 0, 0); } while (0)
; #define PG8_LDA(dst, b, h) do { _Pragma("unroll") for (int m = 0; m < 4; ++m) _Pragma("unroll") for (int k = 0; k < 2; ++k) dst[m][k] = *(const PG8_LAS bf16x8*)(lds + PG8_SA(b, h) + aoff + m * 2048 + k * 1024); } while (0)
; #define PG8_LDB(dst, b, h) do { _Pragma("unroll") for (int n = 0; n < 2; ++n) _Pragma("unroll") for (int k = 0; k < 2; ++k) dst[n][k] = *(const PG8_LAS bf16x8*)(lds + PG8_SB(b, h) + boff + n * 2048 + k * 1024); } while (0)
; #define PG8_MMA(ai, bj, At, Bt) do { __builtin_amdgcn_s_setprio(1); _Pragma("unroll") for (int m = 0; m < 4; ++m) _Pragma("unroll") for (int n = 0; n < 2; ++n) _Pragma("unroll") for (int k = 0; k < 2; ++k) \
;         acc[ai][bj][m][n] = __builtin_amdgcn_mfma_f32_16x16x32_bf16(Bt[n][k], At[m][k], acc[ai][bj][m][n], 0, 0, 0); __builtin_amdgcn_s_setprio(0); } while (0)
; #define PG8_WAIT_V(n) asm volatile("s_waitcnt vmcnt(" #n ")" ::: "memory")
; #define PG8_WAIT_L(n) asm volatile("s_waitcnt lgkmcnt(" #n ")" ::: "memory")
; #define PG8_BAR __builtin_amdgcn_s_barrier()
; template <class Epi, class Sched, bool ALIGN_EPI = false, bool SP2 = false>
; __device__ __forceinline__ void gemm_phase(PG8_LAS unsigned char* lds, const Gemm g, const Sched& S, const Epi& E, const int wv) {
;     ...
;         for (int t = 0; t < nt; t += 2) {
;             const bool last = (t == nt - 2);
;             const char* a1 = cA + (size_t)(t + 1) * kstep;
;             const char* a2 = last ? nA : cA + (size_t)(t + 2) * kstep; const char* b2 = last ? nB : cB + (size_t)(t + 2) * kstep;
;             const char* a3 = a2 + kstep; const char* b3 = b2 + kstep;
;     ...
;             PG8_LDB(B0, 1, 0); PG8_LDB(B1, 1, 1); PG8_SCHED; PG8_LDA(At, 1, 0); PG8_STAGE(PG8_SA(0, 1), a2 + hstepA, voffA);
;             PG8_WAIT_V(8); PG8_WAIT_L(0); PG8_BAR; PG8_MMA(0, 0, At, B0); PG8_MMA(0, 1, At, B1); PG8_BAR; PG8_SCHED;
;             PG8_LDA(At, 1, 1); PG8_STAGE(PG8_SB(1, 0), b3, voffB); PG8_STAGE(PG8_SB(1, 1), b3 + hstepB, voffB); PG8_STAGE(PG8_SA(1, 0), a3, voffA);
;             PG8_WAIT_V(8); PG8_WAIT_L(0); PG8_BAR; PG8_MMA(1, 0, At, B0); PG8_MMA(1, 1, At, B1); PG8_BAR; PG8_SCHED;
	ds_read_b128 v[114:117], v203
	ds_read_b128 v[126:129], v203 offset:1024
	ds_read_b128 v[138:141], v203 offset:2048
	ds_read_b128 v[142:145], v203 offset:3072
	ds_read_b128 v[146:149], v216
	ds_read_b128 v[150:153], v216 offset:1024
	ds_read_b128 v[154:157], v216 offset:2048
	ds_read_b128 v[158:161], v216 offset:3072
	s_add_u32 s30, s44, 0x180000
	s_addc_u32 s31, s45, 0
	s_mov_b32 m0, s54
	ds_read_b128 v[162:165], v235 offset:32768
	ds_read_b128 v[166:169], v235 offset:33792
	ds_read_b128 v[170:173], v235 offset:34816
	ds_read_b128 v[174:177], v235 offset:35840
	ds_read_b128 v[178:181], v235 offset:36864
	ds_read_b128 v[182:185], v235 offset:37888
	ds_read_b128 v[204:207], v235 offset:38912
	ds_read_b128 v[208:211], v235 offset:39936
	global_load_lds_dwordx4 v194, s[30:31]
	s_mov_b32 m0, s55
	s_nop 0
	global_load_lds_dwordx4 v196, s[30:31]
	s_waitcnt vmcnt(8) lgkmcnt(0)
	s_barrier
	v_mfma_f32_16x16x32_bf16 v[134:137], v[114:117], v[162:165], v[134:137]
	v_mfma_f32_16x16x32_bf16 v[130:133], v[138:141], v[162:165], v[130:133]
	v_mfma_f32_16x16x32_bf16 v[110:113], v[114:117], v[170:173], v[110:113]
	v_mfma_f32_16x16x32_bf16 v[106:109], v[138:141], v[170:173], v[106:109]
	v_mfma_f32_16x16x32_bf16 v[94:97], v[114:117], v[178:181], v[94:97]
	v_mfma_f32_16x16x32_bf16 v[90:93], v[138:141], v[178:181], v[90:93]
	v_mfma_f32_16x16x32_bf16 v[78:81], v[114:117], v[204:207], v[78:81]
	v_mfma_f32_16x16x32_bf16 v[74:77], v[138:141], v[204:207], v[74:77]
	v_mfma_f32_16x16x32_bf16 v[134:137], v[126:129], v[166:169], v[134:137]
	v_mfma_f32_16x16x32_bf16 v[130:133], v[142:145], v[166:169], v[130:133]
	v_mfma_f32_16x16x32_bf16 v[110:113], v[126:129], v[174:177], v[110:113]
	v_mfma_f32_16x16x32_bf16 v[106:109], v[142:145], v[174:177], v[106:109]
	v_mfma_f32_16x16x32_bf16 v[94:97], v[126:129], v[182:185], v[94:97]
	v_mfma_f32_16x16x32_bf16 v[90:93], v[142:145], v[182:185], v[90:93]
	v_mfma_f32_16x16x32_bf16 v[78:81], v[126:129], v[208:211], v[78:81]
	v_mfma_f32_16x16x32_bf16 v[74:77], v[142:145], v[208:211], v[74:77]
	v_mfma_f32_16x16x32_bf16 v[122:125], v[146:149], v[162:165], v[122:125]
	v_mfma_f32_16x16x32_bf16 v[118:121], v[154:157], v[162:165], v[118:121]
	v_mfma_f32_16x16x32_bf16 v[102:105], v[146:149], v[170:173], v[102:105]
	v_mfma_f32_16x16x32_bf16 v[98:101], v[154:157], v[170:173], v[98:101]
	v_mfma_f32_16x16x32_bf16 v[86:89], v[146:149], v[178:181], v[86:89]
	v_mfma_f32_16x16x32_bf16 v[82:85], v[154:157], v[178:181], v[82:85]
	v_mfma_f32_16x16x32_bf16 v[70:73], v[146:149], v[204:207], v[70:73]
	v_mfma_f32_16x16x32_bf16 v[66:69], v[154:157], v[204:207], v[66:69]
	v_mfma_f32_16x16x32_bf16 v[122:125], v[150:153], v[166:169], v[122:125]
	v_mfma_f32_16x16x32_bf16 v[118:121], v[158:161], v[166:169], v[118:121]
	v_mfma_f32_16x16x32_bf16 v[102:105], v[150:153], v[174:177], v[102:105]
	v_mfma_f32_16x16x32_bf16 v[98:101], v[158:161], v[174:177], v[98:101]
	v_mfma_f32_16x16x32_bf16 v[86:89], v[150:153], v[182:185], v[86:89]
	v_mfma_f32_16x16x32_bf16 v[82:85], v[158:161], v[182:185], v[82:85]
	v_mfma_f32_16x16x32_bf16 v[70:73], v[150:153], v[208:211], v[70:73]
	v_mfma_f32_16x16x32_bf16 v[66:69], v[158:161], v[208:211], v[66:69]
	s_barrier
	s_add_i32 s30, s47, 0x18000
	s_add_i32 m0, s30, 0xffffff80
	ds_read_b128 v[162:165], v235 offset:49152
	ds_read_b128 v[166:169], v235 offset:50176
	ds_read_b128 v[170:173], v235 offset:51200
	ds_read_b128 v[174:177], v235 offset:52224
	ds_read_b128 v[178:181], v235 offset:53248
	ds_read_b128 v[182:185], v235 offset:54272
	ds_read_b128 v[204:207], v235 offset:55296
	ds_read_b128 v[208:211], v235 offset:56320
	global_load_lds_dwordx4 v[190:191], off offset:128
	s_add_i32 m0, s30, 0x1f80
	s_add_i32 s30, s47, 0x1c000
	global_load_lds_dwordx4 v[192:193], off offset:128
	s_add_i32 m0, s30, 0xffffff80
	s_nop 0
	global_load_lds_dwordx4 v[212:213], off offset:128
	s_add_i32 m0, s30, 0x1f80
	s_nop 0
	global_load_lds_dwordx4 v[214:215], off offset:128
	s_add_i32 m0, s57, 0xffffff80
	s_nop 0
	global_load_lds_dwordx4 v194, s[44:45] offset:128
	s_add_i32 m0, s58, 0xffffff80
	s_nop 0
	global_load_lds_dwordx4 v196, s[44:45] offset:128
	s_waitcnt vmcnt(8) lgkmcnt(0)
	s_barrier
	v_mfma_f32_16x16x32_bf16 v[62:65], v[114:117], v[162:165], v[62:65]
	v_mfma_f32_16x16x32_bf16 v[58:61], v[138:141], v[162:165], v[58:61]
	v_mfma_f32_16x16x32_bf16 v[46:49], v[114:117], v[170:173], v[46:49]
	v_mfma_f32_16x16x32_bf16 v[42:45], v[138:141], v[170:173], v[42:45]
	v_mfma_f32_16x16x32_bf16 v[30:33], v[114:117], v[178:181], v[30:33]
	v_mfma_f32_16x16x32_bf16 v[26:29], v[138:141], v[178:181], v[26:29]
	v_mfma_f32_16x16x32_bf16 v[14:17], v[114:117], v[204:207], v[14:17]
	v_mfma_f32_16x16x32_bf16 v[10:13], v[138:141], v[204:207], v[10:13]
	v_mfma_f32_16x16x32_bf16 v[62:65], v[126:129], v[166:169], v[62:65]
	v_mfma_f32_16x16x32_bf16 v[58:61], v[142:145], v[166:169], v[58:61]
	v_mfma_f32_16x16x32_bf16 v[46:49], v[126:129], v[174:177], v[46:49]
	v_mfma_f32_16x16x32_bf16 v[42:45], v[142:145], v[174:177], v[42:45]
	v_mfma_f32_16x16x32_bf16 v[30:33], v[126:129], v[182:185], v[30:33]
	v_mfma_f32_16x16x32_bf16 v[26:29], v[142:145], v[182:185], v[26:29]
	v_mfma_f32_16x16x32_bf16 v[14:17], v[126:129], v[208:211], v[14:17]
	v_mfma_f32_16x16x32_bf16 v[10:13], v[142:145], v[208:211], v[10:13]
	v_mfma_f32_16x16x32_bf16 v[54:57], v[146:149], v[162:165], v[54:57]
	v_mfma_f32_16x16x32_bf16 v[50:53], v[154:157], v[162:165], v[50:53]
	v_mfma_f32_16x16x32_bf16 v[38:41], v[146:149], v[170:173], v[38:41]
	v_mfma_f32_16x16x32_bf16 v[34:37], v[154:157], v[170:173], v[34:37]
	v_mfma_f32_16x16x32_bf16 v[22:25], v[146:149], v[178:181], v[22:25]
	v_mfma_f32_16x16x32_bf16 v[18:21], v[154:157], v[178:181], v[18:21]
	v_mfma_f32_16x16x32_bf16 v[6:9], v[146:149], v[204:207], v[6:9]
	v_mfma_f32_16x16x32_bf16 v[2:5], v[154:157], v[204:207], v[2:5]
	v_mfma_f32_16x16x32_bf16 v[54:57], v[150:153], v[166:169], v[54:57]
	v_mfma_f32_16x16x32_bf16 v[50:53], v[158:161], v[166:169], v[50:53]
	v_mfma_f32_16x16x32_bf16 v[38:41], v[150:153], v[174:177], v[38:41]
	v_mfma_f32_16x16x32_bf16 v[34:37], v[158:161], v[174:177], v[34:37]
	v_mfma_f32_16x16x32_bf16 v[22:25], v[150:153], v[182:185], v[22:25]
	v_mfma_f32_16x16x32_bf16 v[18:21], v[158:161], v[182:185], v[18:21]
	v_mfma_f32_16x16x32_bf16 v[6:9], v[150:153], v[208:211], v[6:9]
	v_mfma_f32_16x16x32_bf16 v[2:5], v[158:161], v[208:211], v[2:5]
	s_add_u32 s65, s65, 0x100
	s_addc_u32 s66, s66, 0
	s_cmp_ge_i32 s67, s56
	s_mov_b64 s[30:31], s[34:35]
	s_mov_b32 s44, s67
	s_barrier
	s_cbranch_scc0 .LBB0_1676
	s_movk_i32 s68, 0x4000
	s_movk_i32 s69, 0x6000
	s_mov_b32 s70, 0x18000
	s_mov_b32 s71, 0x3f317217
	s_and_b64 vcc, exec, s[28:29]
	s_cbranch_vccz .LBB0_1652
